# GEMM K-loops: redundant compiler lgkmcnt(0) wait after the barrier removed (MFMA segment starts with its MFMAs)
# baseline (speedup 1.0000x reference)
; #define PG8_STAGE(bufoff, gbase, voff) do { _Pragma("unroll") for (int _i = 0; _i < 2; ++_i) \
;         __builtin_amdgcn_global_load_lds((const unsigned*)((const char*)(gbase) + (voff)[_i]), (PG8_LAS unsigned*)(lds + (bufoff) + ldsw + _i * 8192), 16, 0, 0); } while (0)
; #define PG8_LDA(dst, b, h) do { _Pragma("unroll") for (int m = 0; m < 4; ++m) _Pragma("unroll") for (int k = 0; k < 2; ++k) dst[m][k] = *(const PG8_LAS bf16x8*)(lds + PG8_SA(b, h) + aoff + m * 2048 + k * 1024); } while (0)
; #define PG8_LDB(dst, b, h) do { _Pragma("unroll") for (int n = 0; n < 2; ++n) _Pragma("unroll") for (int k = 0; k < 2; ++k) dst[n][k] = *(const PG8_LAS bf16x8*)(lds + PG8_SB(b, h) + boff + n * 2048 + k * 1024); } while (0)
; #define PG8_MMA(ai, bj, At, Bt) do { __builtin_amdgcn_s_setprio(1); _Pragma("unroll") for (int m = 0; m < 4; ++m) _Pragma("unroll") for (int n = 0; n < 2; ++n) _Pragma("unroll") for (int k = 0; k < 2; ++k) \
;         acc[ai][bj][m][n] = __builtin_amdgcn_mfma_f32_16x16x32_bf16(Bt[n][k], At[m][k], acc[ai][bj][m][n], 0, 0, 0); __builtin_amdgcn_s_setprio(0); } while (0)
; #define PG8_WAIT_V(n) asm volatile("s_waitcnt vmcnt(" #n ")" ::: "memory")
; #define PG8_BAR __builtin_amdgcn_s_barrier()
; template <class Epi, class Sched, bool ALIGN_EPI = false, bool SP2 = false, bool HALFM = false>
; __device__ __forceinline__ void gemm_phase(PG8_LAS unsigned char* lds, const Gemm g, const Sched& S, const Epi& E) {
;     ...
;             const bool last = (t == nt - 2);
;             const char* a1 = cA + (size_t)(t + 1) * kstep;
;             const char* a2 = last ? nA : cA + (size_t)(t + 2) * kstep; const char* b2 = last ? nB : cB + (size_t)(t + 2) * kstep;
;             const char* a3 = a2 + kstep; const char* b3 = b2 + kstep;
;             if (last && has_next) S.a_ready(nxt);
;             if constexpr (SP2) {
;             PG8_LDB(B0, 0, 0); PG8_LDB(B1, 0, 1); PG8_SCHED; PG8_LDA(At, 0, 0); PG8_STAGE(PG8_SA(1, 1), a1 + hstep, voffA);
;             PG8_WAIT_V(8); PG8_WAIT_L(0); PG8_BAR; PG8_MMA(0, 0, At, B0); PG8_MMA(0, 1, At, B1); PG8_BAR; PG8_SCHED;
;             PG8_LDA(At, 0, 1); PG8_STAGE(PG8_SB(0, 0), b2, voffB); PG8_STAGE(PG8_SB(0, 1), b2 + hstep, voffB); PG8_STAGE(PG8_SA(0, 0), a2, voffA);
;             PG8_WAIT_V(8); PG8_WAIT_L(0); PG8_BAR; if constexpr (!HALFM) { PG8_MMA(1, 0, At, B0); PG8_MMA(1, 1, At, B1); } PG8_BAR; PG8_SCHED;
.LBB0_496:
	ds_read_b128 v[154:157], v150
	ds_read_b128 v[158:161], v150 offset:1024
	ds_read_b128 v[162:165], v150 offset:2048
	ds_read_b128 v[166:169], v150 offset:3072
	ds_read_b128 v[170:173], v151
	ds_read_b128 v[174:177], v151 offset:1024
	ds_read_b128 v[178:181], v151 offset:2048
	ds_read_b128 v[182:185], v151 offset:3072
	s_add_u32 s24, s22, 0xfffc0080
	s_addc_u32 s25, s23, -1
	s_cmp_eq_u32 s45, 12
	s_cselect_b32 s27, s15, s25
	s_cselect_b32 s26, s41, s24
	s_cselect_b32 s25, s13, s44
	s_cselect_b32 s24, s42, s43
	v_lshl_add_u64 v[146:147], s[22:23], 0, v[138:139]
	s_add_i32 m0, s2, 0xc000
	ds_read_b128 v[186:189], v152
	ds_read_b128 v[190:193], v152 offset:1024
	ds_read_b128 v[194:197], v152 offset:2048
	ds_read_b128 v[198:201], v152 offset:3072
	ds_read_b128 v[202:205], v152 offset:4096
	ds_read_b128 v[206:209], v152 offset:5120
	ds_read_b128 v[210:213], v152 offset:6144
	ds_read_b128 v[214:217], v152 offset:7168
	global_load_lds_dwordx4 v[146:147], off
	v_lshl_add_u64 v[146:147], s[22:23], 0, v[140:141]
	s_add_i32 m0, s2, 0xe000
	s_nop 0
	global_load_lds_dwordx4 v[146:147], off
	s_mov_b32 m0, s30
	v_lshl_add_u64 v[146:147], v[220:221], 0, s[8:9]
	global_load_lds_dwordx4 v[146:147], off
	s_mov_b32 m0, s31
	v_lshl_add_u64 v[146:147], v[222:223], 0, s[8:9]
	global_load_lds_dwordx4 v[146:147], off
	s_waitcnt vmcnt(10)
	s_waitcnt lgkmcnt(0)
	s_barrier
	s_setprio 1
	v_mfma_f32_16x16x32_bf16 v[126:129], v[154:157], v[186:189], v[126:129]
	v_mfma_f32_16x16x32_bf16 v[122:125], v[162:165], v[186:189], v[122:125]
	v_mfma_f32_16x16x32_bf16 v[110:113], v[154:157], v[194:197], v[110:113]
	v_mfma_f32_16x16x32_bf16 v[106:109], v[162:165], v[194:197], v[106:109]
	v_mfma_f32_16x16x32_bf16 v[94:97], v[154:157], v[202:205], v[94:97]
	v_mfma_f32_16x16x32_bf16 v[90:93], v[162:165], v[202:205], v[90:93]
	v_mfma_f32_16x16x32_bf16 v[78:81], v[154:157], v[210:213], v[78:81]
	v_mfma_f32_16x16x32_bf16 v[74:77], v[162:165], v[210:213], v[74:77]
	v_mfma_f32_16x16x32_bf16 v[126:129], v[158:161], v[190:193], v[126:129]
	v_mfma_f32_16x16x32_bf16 v[122:125], v[166:169], v[190:193], v[122:125]
	v_mfma_f32_16x16x32_bf16 v[110:113], v[158:161], v[198:201], v[110:113]
	v_mfma_f32_16x16x32_bf16 v[106:109], v[166:169], v[198:201], v[106:109]
	v_mfma_f32_16x16x32_bf16 v[94:97], v[158:161], v[206:209], v[94:97]
	v_mfma_f32_16x16x32_bf16 v[90:93], v[166:169], v[206:209], v[90:93]
	v_mfma_f32_16x16x32_bf16 v[78:81], v[158:161], v[214:217], v[78:81]
	v_mfma_f32_16x16x32_bf16 v[74:77], v[166:169], v[214:217], v[74:77]
	s_setprio 0
	s_setprio 1
	v_mfma_f32_16x16x32_bf16 v[118:121], v[170:173], v[186:189], v[118:121]
	v_mfma_f32_16x16x32_bf16 v[114:117], v[178:181], v[186:189], v[114:117]
	v_mfma_f32_16x16x32_bf16 v[102:105], v[170:173], v[194:197], v[102:105]
	v_mfma_f32_16x16x32_bf16 v[98:101], v[178:181], v[194:197], v[98:101]
	v_mfma_f32_16x16x32_bf16 v[86:89], v[170:173], v[202:205], v[86:89]
	v_mfma_f32_16x16x32_bf16 v[82:85], v[178:181], v[202:205], v[82:85]
	v_mfma_f32_16x16x32_bf16 v[70:73], v[170:173], v[210:213], v[70:73]
	v_mfma_f32_16x16x32_bf16 v[66:69], v[178:181], v[210:213], v[66:69]
	v_mfma_f32_16x16x32_bf16 v[118:121], v[174:177], v[190:193], v[118:121]
	v_mfma_f32_16x16x32_bf16 v[114:117], v[182:185], v[190:193], v[114:117]
	v_mfma_f32_16x16x32_bf16 v[102:105], v[174:177], v[198:201], v[102:105]
	v_mfma_f32_16x16x32_bf16 v[98:101], v[182:185], v[198:201], v[98:101]
	v_mfma_f32_16x16x32_bf16 v[86:89], v[174:177], v[206:209], v[86:89]
	v_mfma_f32_16x16x32_bf16 v[82:85], v[182:185], v[206:209], v[82:85]
	v_mfma_f32_16x16x32_bf16 v[70:73], v[174:177], v[214:217], v[70:73]
	v_mfma_f32_16x16x32_bf16 v[66:69], v[182:185], v[214:217], v[66:69]
	s_setprio 0
	s_barrier
	s_add_i32 s46, s37, s0
	v_lshl_add_u64 v[146:147], s[24:25], 0, v[134:135]
	s_mov_b32 m0, s46
	ds_read_b128 v[186:189], v152 offset:16384
	ds_read_b128 v[190:193], v152 offset:17408
	ds_read_b128 v[194:197], v152 offset:18432
	ds_read_b128 v[198:201], v152 offset:19456
	ds_read_b128 v[202:205], v152 offset:20480
	ds_read_b128 v[206:209], v152 offset:21504
	ds_read_b128 v[210:213], v152 offset:22528
	ds_read_b128 v[214:217], v152 offset:23552
	global_load_lds_dwordx4 v[146:147], off
	s_add_i32 m0, s46, 0x2000
	s_add_u32 s46, s24, 0x40000
	v_lshl_add_u64 v[218:219], s[24:25], 0, v[130:131]
	s_addc_u32 s47, s25, 0
	s_add_i32 s48, s38, s0
	global_load_lds_dwordx4 v[218:219], off
	v_lshl_add_u64 v[220:221], s[46:47], 0, v[134:135]
	s_mov_b32 m0, s48
	v_lshl_add_u64 v[222:223], s[26:27], 0, v[132:133]
	global_load_lds_dwordx4 v[220:221], off
	v_lshl_add_u64 v[220:221], s[46:47], 0, v[130:131]
	s_add_i32 m0, s48, 0x2000
	s_nop 0
	global_load_lds_dwordx4 v[220:221], off
	v_lshl_add_u64 v[220:221], s[26:27], 0, v[136:137]
	s_waitcnt vmcnt(4)
	s_waitcnt lgkmcnt(0)
	s_barrier
; #define PG8_STAGE(bufoff, gbase, voff) do { _Pragma("unroll") for (int _i = 0; _i < 2; ++_i) \
;         __builtin_amdgcn_global_load_lds((const unsigned*)((const char*)(gbase) + (voff)[_i]), (PG8_LAS unsigned*)(lds + (bufoff) + ldsw + _i * 8192), 16, 0, 0); } while (0)
; #define PG8_LDA(dst, b, h) do { _Pragma("unroll") for (int m = 0; m < 4; ++m) _Pragma("unroll") for (int k = 0; k < 2; ++k) dst[m][k] = *(const PG8_LAS bf16x8*)(lds + PG8_SA(b, h) + aoff + m * 2048 + k * 1024); } while (0)
; #define PG8_LDB(dst, b, h) do { _Pragma("unroll") for (int n = 0; n < 2; ++n) _Pragma("unroll") for (int k = 0; k < 2; ++k) dst[n][k] = *(const PG8_LAS bf16x8*)(lds + PG8_SB(b, h) + boff + n * 2048 + k * 1024); } while (0)
; #define PG8_MMA(ai, bj, At, Bt) do { __builtin_amdgcn_s_setprio(1); _Pragma("unroll") for (int m = 0; m < 4; ++m) _Pragma("unroll") for (int n = 0; n < 2; ++n) _Pragma("unroll") for (int k = 0; k < 2; ++k) \
;         acc[ai][bj][m][n] = __builtin_amdgcn_mfma_f32_16x16x32_bf16(Bt[n][k], At[m][k], acc[ai][bj][m][n], 0, 0, 0); __builtin_amdgcn_s_setprio(0); } while (0)
; #define PG8_WAIT_V(n) asm volatile("s_waitcnt vmcnt(" #n ")" ::: "memory")
; #define PG8_WAIT_L(n) asm volatile("s_waitcnt lgkmcnt(" #n ")" ::: "memory")
; #define PG8_BAR __builtin_amdgcn_s_barrier()
; #define PG8_SCHED __builtin_amdgcn_sched_barrier(0)
; template <class Epi, class Sched, bool ALIGN_EPI = false, bool SP2 = false, bool HALFM = false>
; __device__ __forceinline__ void gemm_phase(PG8_LAS unsigned char* lds, const Gemm g, const Sched& S, const Epi& E) {
;     ...
;             PG8_WAIT_V(8); PG8_WAIT_L(0); PG8_BAR; if constexpr (!HALFM) { PG8_MMA(1, 0, At, B0); PG8_MMA(1, 1, At, B1); } PG8_BAR; PG8_SCHED;
;             PG8_LDB(B0, 1, 0); PG8_LDB(B1, 1, 1); PG8_SCHED; PG8_LDA(At, 1, 0); PG8_STAGE(PG8_SA(0, 1), a2 + hstep, voffA);
;             PG8_WAIT_V(8); PG8_WAIT_L(0); PG8_BAR; PG8_MMA(0, 0, At, B0); PG8_MMA(0, 1, At, B1); PG8_BAR; PG8_SCHED;
	s_setprio 1
	v_mfma_f32_16x16x32_bf16 v[62:65], v[154:157], v[186:189], v[62:65]
	v_mfma_f32_16x16x32_bf16 v[58:61], v[162:165], v[186:189], v[58:61]
	v_mfma_f32_16x16x32_bf16 v[46:49], v[154:157], v[194:197], v[46:49]
	v_mfma_f32_16x16x32_bf16 v[42:45], v[162:165], v[194:197], v[42:45]
	v_mfma_f32_16x16x32_bf16 v[30:33], v[154:157], v[202:205], v[30:33]
	v_mfma_f32_16x16x32_bf16 v[26:29], v[162:165], v[202:205], v[26:29]
	v_mfma_f32_16x16x32_bf16 v[14:17], v[154:157], v[210:213], v[14:17]
	v_mfma_f32_16x16x32_bf16 v[10:13], v[162:165], v[210:213], v[10:13]
	v_mfma_f32_16x16x32_bf16 v[62:65], v[158:161], v[190:193], v[62:65]
	v_mfma_f32_16x16x32_bf16 v[58:61], v[166:169], v[190:193], v[58:61]
	v_mfma_f32_16x16x32_bf16 v[46:49], v[158:161], v[198:201], v[46:49]
	v_mfma_f32_16x16x32_bf16 v[42:45], v[166:169], v[198:201], v[42:45]
	v_mfma_f32_16x16x32_bf16 v[30:33], v[158:161], v[206:209], v[30:33]
	v_mfma_f32_16x16x32_bf16 v[26:29], v[166:169], v[206:209], v[26:29]
	v_mfma_f32_16x16x32_bf16 v[14:17], v[158:161], v[214:217], v[14:17]
	v_mfma_f32_16x16x32_bf16 v[10:13], v[166:169], v[214:217], v[10:13]
	s_setprio 0
	s_setprio 1
	v_mfma_f32_16x16x32_bf16 v[54:57], v[170:173], v[186:189], v[54:57]
	v_mfma_f32_16x16x32_bf16 v[50:53], v[178:181], v[186:189], v[50:53]
	v_mfma_f32_16x16x32_bf16 v[38:41], v[170:173], v[194:197], v[38:41]
	v_mfma_f32_16x16x32_bf16 v[34:37], v[178:181], v[194:197], v[34:37]
	v_mfma_f32_16x16x32_bf16 v[22:25], v[170:173], v[202:205], v[22:25]
	v_mfma_f32_16x16x32_bf16 v[18:21], v[178:181], v[202:205], v[18:21]
	v_mfma_f32_16x16x32_bf16 v[6:9], v[170:173], v[210:213], v[6:9]
	v_mfma_f32_16x16x32_bf16 v[2:5], v[178:181], v[210:213], v[2:5]
	v_mfma_f32_16x16x32_bf16 v[54:57], v[174:177], v[190:193], v[54:57]
	v_mfma_f32_16x16x32_bf16 v[50:53], v[182:185], v[190:193], v[50:53]
	v_mfma_f32_16x16x32_bf16 v[38:41], v[174:177], v[198:201], v[38:41]
	v_mfma_f32_16x16x32_bf16 v[34:37], v[182:185], v[198:201], v[34:37]
	v_mfma_f32_16x16x32_bf16 v[22:25], v[174:177], v[206:209], v[22:25]
	v_mfma_f32_16x16x32_bf16 v[18:21], v[182:185], v[206:209], v[18:21]
	v_mfma_f32_16x16x32_bf16 v[6:9], v[174:177], v[214:217], v[6:9]
	v_mfma_f32_16x16x32_bf16 v[2:5], v[182:185], v[214:217], v[2:5]
	s_setprio 0
	s_barrier
	s_add_i32 s46, 0, 0x18000
	v_add_u32_e32 v153, s46, v148
	s_add_i32 s47, 0, 0x1c000
	ds_read_b128 v[154:157], v153
	ds_read_b128 v[158:161], v153 offset:1024
	ds_read_b128 v[162:165], v153 offset:2048
	ds_read_b128 v[166:169], v153 offset:3072
	v_add_u32_e32 v153, s47, v148
	ds_read_b128 v[170:173], v153
	ds_read_b128 v[174:177], v153 offset:1024
	ds_read_b128 v[178:181], v153 offset:2048
	ds_read_b128 v[182:185], v153 offset:3072
	s_add_u32 s26, s26, 0x40000
	s_addc_u32 s27, s27, 0
	s_mov_b32 m0, s21
	v_lshl_add_u64 v[224:225], s[26:27], 0, v[136:137]
	ds_read_b128 v[186:189], v152 offset:32768
	ds_read_b128 v[190:193], v152 offset:33792
	ds_read_b128 v[194:197], v152 offset:34816
	ds_read_b128 v[198:201], v152 offset:35840
	ds_read_b128 v[202:205], v152 offset:36864
	ds_read_b128 v[206:209], v152 offset:37888
	ds_read_b128 v[210:213], v152 offset:38912
	ds_read_b128 v[214:217], v152 offset:39936
	global_load_lds_dwordx4 v[224:225], off
	v_lshl_add_u64 v[224:225], s[26:27], 0, v[132:133]
	s_mov_b32 m0, s28
	s_nop 0
	global_load_lds_dwordx4 v[224:225], off
	s_mov_b32 m0, s2
	s_nop 0
	global_load_lds_dwordx4 v[220:221], off
	s_mov_b32 m0, s3
	s_nop 0
	global_load_lds_dwordx4 v[222:223], off
	s_waitcnt vmcnt(10)
	s_waitcnt lgkmcnt(0)
	s_barrier
; #define PG8_STAGE(bufoff, gbase, voff) do { _Pragma("unroll") for (int _i = 0; _i < 2; ++_i) \
;         __builtin_amdgcn_global_load_lds((const unsigned*)((const char*)(gbase) + (voff)[_i]), (PG8_LAS unsigned*)(lds + (bufoff) + ldsw + _i * 8192), 16, 0, 0); } while (0)
; #define PG8_LDA(dst, b, h) do { _Pragma("unroll") for (int m = 0; m < 4; ++m) _Pragma("unroll") for (int k = 0; k < 2; ++k) dst[m][k] = *(const PG8_LAS bf16x8*)(lds + PG8_SA(b, h) + aoff + m * 2048 + k * 1024); } while (0)
; #define PG8_MMA(ai, bj, At, Bt) do { __builtin_amdgcn_s_setprio(1); _Pragma("unroll") for (int m = 0; m < 4; ++m) _Pragma("unroll") for (int n = 0; n < 2; ++n) _Pragma("unroll") for (int k = 0; k < 2; ++k) \
;         acc[ai][bj][m][n] = __builtin_amdgcn_mfma_f32_16x16x32_bf16(Bt[n][k], At[m][k], acc[ai][bj][m][n], 0, 0, 0); __builtin_amdgcn_s_setprio(0); } while (0)
; #define PG8_WAIT_V(n) asm volatile("s_waitcnt vmcnt(" #n ")" ::: "memory")
; #define PG8_WAIT_L(n) asm volatile("s_waitcnt lgkmcnt(" #n ")" ::: "memory")
; #define PG8_BAR __builtin_amdgcn_s_barrier()
; #define PG8_SCHED __builtin_amdgcn_sched_barrier(0)
; template <class Epi, class Sched, bool ALIGN_EPI = false, bool SP2 = false, bool HALFM = false>
; __device__ __forceinline__ void gemm_phase(PG8_LAS unsigned char* lds, const Gemm g, const Sched& S, const Epi& E) {
;     ...
;             PG8_WAIT_V(8); PG8_WAIT_L(0); PG8_BAR; PG8_MMA(0, 0, At, B0); PG8_MMA(0, 1, At, B1); PG8_BAR; PG8_SCHED;
;             PG8_LDA(At, 1, 1); PG8_STAGE(PG8_SB(1, 0), b3, voffB); PG8_STAGE(PG8_SB(1, 1), b3 + hstep, voffB); PG8_STAGE(PG8_SA(1, 0), a3, voffA);
;             PG8_WAIT_V(8); PG8_WAIT_L(0); PG8_BAR; if constexpr (!HALFM) { PG8_MMA(1, 0, At, B0); PG8_MMA(1, 1, At, B1); } PG8_BAR; PG8_SCHED;
	s_setprio 1
	v_mfma_f32_16x16x32_bf16 v[126:129], v[154:157], v[186:189], v[126:129]
	v_mfma_f32_16x16x32_bf16 v[122:125], v[162:165], v[186:189], v[122:125]
	v_mfma_f32_16x16x32_bf16 v[110:113], v[154:157], v[194:197], v[110:113]
	v_mfma_f32_16x16x32_bf16 v[106:109], v[162:165], v[194:197], v[106:109]
	v_mfma_f32_16x16x32_bf16 v[94:97], v[154:157], v[202:205], v[94:97]
	v_mfma_f32_16x16x32_bf16 v[90:93], v[162:165], v[202:205], v[90:93]
	v_mfma_f32_16x16x32_bf16 v[78:81], v[154:157], v[210:213], v[78:81]
	v_mfma_f32_16x16x32_bf16 v[74:77], v[162:165], v[210:213], v[74:77]
	v_mfma_f32_16x16x32_bf16 v[126:129], v[158:161], v[190:193], v[126:129]
	v_mfma_f32_16x16x32_bf16 v[122:125], v[166:169], v[190:193], v[122:125]
	v_mfma_f32_16x16x32_bf16 v[110:113], v[158:161], v[198:201], v[110:113]
	v_mfma_f32_16x16x32_bf16 v[106:109], v[166:169], v[198:201], v[106:109]
	v_mfma_f32_16x16x32_bf16 v[94:97], v[158:161], v[206:209], v[94:97]
	v_mfma_f32_16x16x32_bf16 v[90:93], v[166:169], v[206:209], v[90:93]
	v_mfma_f32_16x16x32_bf16 v[78:81], v[158:161], v[214:217], v[78:81]
	v_mfma_f32_16x16x32_bf16 v[74:77], v[166:169], v[214:217], v[74:77]
	s_setprio 0
	s_setprio 1
	v_mfma_f32_16x16x32_bf16 v[118:121], v[170:173], v[186:189], v[118:121]
	v_mfma_f32_16x16x32_bf16 v[114:117], v[178:181], v[186:189], v[114:117]
	v_mfma_f32_16x16x32_bf16 v[102:105], v[170:173], v[194:197], v[102:105]
	v_mfma_f32_16x16x32_bf16 v[98:101], v[178:181], v[194:197], v[98:101]
	v_mfma_f32_16x16x32_bf16 v[86:89], v[170:173], v[202:205], v[86:89]
	v_mfma_f32_16x16x32_bf16 v[82:85], v[178:181], v[202:205], v[82:85]
	v_mfma_f32_16x16x32_bf16 v[70:73], v[170:173], v[210:213], v[70:73]
	v_mfma_f32_16x16x32_bf16 v[66:69], v[178:181], v[210:213], v[66:69]
	v_mfma_f32_16x16x32_bf16 v[118:121], v[174:177], v[190:193], v[118:121]
	v_mfma_f32_16x16x32_bf16 v[114:117], v[182:185], v[190:193], v[114:117]
	v_mfma_f32_16x16x32_bf16 v[102:105], v[174:177], v[198:201], v[102:105]
	v_mfma_f32_16x16x32_bf16 v[98:101], v[182:185], v[198:201], v[98:101]
	v_mfma_f32_16x16x32_bf16 v[86:89], v[174:177], v[206:209], v[86:89]
	v_mfma_f32_16x16x32_bf16 v[82:85], v[182:185], v[206:209], v[82:85]
	v_mfma_f32_16x16x32_bf16 v[70:73], v[174:177], v[214:217], v[70:73]
	v_mfma_f32_16x16x32_bf16 v[66:69], v[182:185], v[214:217], v[66:69]
	s_setprio 0
	s_barrier
	s_add_i32 s26, s46, s0
	v_lshl_add_u64 v[146:147], v[146:147], 0, s[8:9]
	s_mov_b32 m0, s26
	ds_read_b128 v[186:189], v152 offset:49152
	ds_read_b128 v[190:193], v152 offset:50176
	ds_read_b128 v[194:197], v152 offset:51200
	ds_read_b128 v[198:201], v152 offset:52224
	ds_read_b128 v[202:205], v152 offset:53248
	ds_read_b128 v[206:209], v152 offset:54272
	ds_read_b128 v[210:213], v152 offset:55296
	ds_read_b128 v[214:217], v152 offset:56320
	global_load_lds_dwordx4 v[146:147], off
	s_add_i32 m0, s26, 0x2000
	s_add_u32 s24, s24, 0x40080
	v_lshl_add_u64 v[146:147], v[218:219], 0, s[8:9]
	s_addc_u32 s25, s25, 0
	s_add_i32 s26, s47, s0
	global_load_lds_dwordx4 v[146:147], off
	v_lshl_add_u64 v[146:147], s[24:25], 0, v[134:135]
	s_mov_b32 m0, s26
	s_nop 0
	global_load_lds_dwordx4 v[146:147], off
	v_lshl_add_u64 v[146:147], s[24:25], 0, v[130:131]
	s_add_i32 m0, s26, 0x2000
	s_nop 0
	global_load_lds_dwordx4 v[146:147], off
	s_waitcnt vmcnt(4)
	s_waitcnt lgkmcnt(0)
	s_barrier
	s_setprio 1
	v_mfma_f32_16x16x32_bf16 v[62:65], v[154:157], v[186:189], v[62:65]
	v_mfma_f32_16x16x32_bf16 v[58:61], v[162:165], v[186:189], v[58:61]
	v_mfma_f32_16x16x32_bf16 v[46:49], v[154:157], v[194:197], v[46:49]
	v_mfma_f32_16x16x32_bf16 v[42:45], v[162:165], v[194:197], v[42:45]
	v_mfma_f32_16x16x32_bf16 v[30:33], v[154:157], v[202:205], v[30:33]
	v_mfma_f32_16x16x32_bf16 v[26:29], v[162:165], v[202:205], v[26:29]
	v_mfma_f32_16x16x32_bf16 v[14:17], v[154:157], v[210:213], v[14:17]
	v_mfma_f32_16x16x32_bf16 v[10:13], v[162:165], v[210:213], v[10:13]
	v_mfma_f32_16x16x32_bf16 v[62:65], v[158:161], v[190:193], v[62:65]
	v_mfma_f32_16x16x32_bf16 v[58:61], v[166:169], v[190:193], v[58:61]
	v_mfma_f32_16x16x32_bf16 v[46:49], v[158:161], v[198:201], v[46:49]
	v_mfma_f32_16x16x32_bf16 v[42:45], v[166:169], v[198:201], v[42:45]
	v_mfma_f32_16x16x32_bf16 v[30:33], v[158:161], v[206:209], v[30:33]
	v_mfma_f32_16x16x32_bf16 v[26:29], v[166:169], v[206:209], v[26:29]
	v_mfma_f32_16x16x32_bf16 v[14:17], v[158:161], v[214:217], v[14:17]
	v_mfma_f32_16x16x32_bf16 v[10:13], v[166:169], v[214:217], v[10:13]
	s_setprio 0
	s_setprio 1
	v_mfma_f32_16x16x32_bf16 v[54:57], v[170:173], v[186:189], v[54:57]
	v_mfma_f32_16x16x32_bf16 v[50:53], v[178:181], v[186:189], v[50:53]
	v_mfma_f32_16x16x32_bf16 v[38:41], v[170:173], v[194:197], v[38:41]
	v_mfma_f32_16x16x32_bf16 v[34:37], v[178:181], v[194:197], v[34:37]
	v_mfma_f32_16x16x32_bf16 v[22:25], v[170:173], v[202:205], v[22:25]
	v_mfma_f32_16x16x32_bf16 v[18:21], v[178:181], v[202:205], v[18:21]
	v_mfma_f32_16x16x32_bf16 v[6:9], v[170:173], v[210:213], v[6:9]
	v_mfma_f32_16x16x32_bf16 v[2:5], v[178:181], v[210:213], v[2:5]
	v_mfma_f32_16x16x32_bf16 v[54:57], v[174:177], v[190:193], v[54:57]
	v_mfma_f32_16x16x32_bf16 v[50:53], v[182:185], v[190:193], v[50:53]
	v_mfma_f32_16x16x32_bf16 v[38:41], v[174:177], v[198:201], v[38:41]
	v_mfma_f32_16x16x32_bf16 v[34:37], v[182:185], v[198:201], v[34:37]
	v_mfma_f32_16x16x32_bf16 v[22:25], v[174:177], v[206:209], v[22:25]
	v_mfma_f32_16x16x32_bf16 v[18:21], v[182:185], v[206:209], v[18:21]
	v_mfma_f32_16x16x32_bf16 v[6:9], v[174:177], v[214:217], v[6:9]
	v_mfma_f32_16x16x32_bf16 v[2:5], v[182:185], v[214:217], v[2:5]
	s_setprio 0
	s_barrier
	s_add_i32 s45, s45, 2
	s_add_u32 s22, s22, 0x100
	s_addc_u32 s23, s23, 0
	s_add_u32 s43, s43, 0x100
	s_addc_u32 s44, s44, 0
	s_cmp_gt_u32 s45, 13
	s_cbranch_scc0 .LBB0_496
	s_and_b64 vcc, exec, s[10:11]
	s_cbranch_vccz .LBB0_499
	s_barrier

; #define PG8_STAGE(bufoff, gbase, voff) do { _Pragma("unroll") for (int _i = 0; _i < 2; ++_i) \
;         __builtin_amdgcn_global_load_lds((const unsigned*)((const char*)(gbase) + (voff)[_i]), (PG8_LAS unsigned*)(lds + (bufoff) + ldsw + _i * 8192), 16, 0, 0); } while (0)
; #define PG8_LDA(dst, b, h) do { _Pragma("unroll") for (int m = 0; m < 4; ++m) _Pragma("unroll") for (int k = 0; k < 2; ++k) dst[m][k] = *(const PG8_LAS bf16x8*)(lds + PG8_SA(b, h) + aoff + m * 2048 + k * 1024); } while (0)
; #define PG8_LDB(dst, b, h) do { _Pragma("unroll") for (int n = 0; n < 2; ++n) _Pragma("unroll") for (int k = 0; k < 2; ++k) dst[n][k] = *(const PG8_LAS bf16x8*)(lds + PG8_SB(b, h) + boff + n * 2048 + k * 1024); } while (0)
; #define PG8_MMA(ai, bj, At, Bt) do { __builtin_amdgcn_s_setprio(1); _Pragma("unroll") for (int m = 0; m < 4; ++m) _Pragma("unroll") for (int n = 0; n < 2; ++n) _Pragma("unroll") for (int k = 0; k < 2; ++k) \
;         acc[ai][bj][m][n] = __builtin_amdgcn_mfma_f32_16x16x32_bf16(Bt[n][k], At[m][k], acc[ai][bj][m][n], 0, 0, 0); __builtin_amdgcn_s_setprio(0); } while (0)
; #define PG8_WAIT_V(n) asm volatile("s_waitcnt vmcnt(" #n ")" ::: "memory")
; #define PG8_BAR __builtin_amdgcn_s_barrier()
; template <class Epi, class Sched, bool ALIGN_EPI = false, bool SP2 = false, bool HALFM = false>
; __device__ __forceinline__ void gemm_phase(PG8_LAS unsigned char* lds, const Gemm g, const Sched& S, const Epi& E) {
;     ...
;             const bool last = (t == nt - 2);
;             const char* a1 = cA + (size_t)(t + 1) * kstep;
;             const char* a2 = last ? nA : cA + (size_t)(t + 2) * kstep; const char* b2 = last ? nB : cB + (size_t)(t + 2) * kstep;
;             const char* a3 = a2 + kstep; const char* b3 = b2 + kstep;
;             if (last && has_next) S.a_ready(nxt);
;             if constexpr (SP2) {
;             PG8_LDB(B0, 0, 0); PG8_LDB(B1, 0, 1); PG8_SCHED; PG8_LDA(At, 0, 0); PG8_STAGE(PG8_SA(1, 1), a1 + hstep, voffA);
;             PG8_WAIT_V(8); PG8_WAIT_L(0); PG8_BAR; PG8_MMA(0, 0, At, B0); PG8_MMA(0, 1, At, B1); PG8_BAR; PG8_SCHED;
;             PG8_LDA(At, 0, 1); PG8_STAGE(PG8_SB(0, 0), b2, voffB); PG8_STAGE(PG8_SB(0, 1), b2 + hstep, voffB); PG8_STAGE(PG8_SA(0, 0), a2, voffA);
;             PG8_WAIT_V(8); PG8_WAIT_L(0); PG8_BAR; if constexpr (!HALFM) { PG8_MMA(1, 0, At, B0); PG8_MMA(1, 1, At, B1); } PG8_BAR; PG8_SCHED;
.LBB0_637:
	ds_read_b128 v[130:133], v208
	ds_read_b128 v[134:137], v208 offset:1024
	ds_read_b128 v[138:141], v208 offset:2048
	ds_read_b128 v[142:145], v208 offset:3072
	ds_read_b128 v[146:149], v209
	ds_read_b128 v[150:153], v209 offset:1024
	ds_read_b128 v[154:157], v209 offset:2048
	ds_read_b128 v[158:161], v209 offset:3072
	s_add_u32 s26, s24, 0x100
	s_addc_u32 s27, s25, 0
	s_cmp_eq_u32 s49, 40
	s_cselect_b32 s31, s11, s27
	s_cselect_b32 s30, s10, s26
	s_cselect_b32 s29, s23, s48
	s_cselect_b32 s28, s22, s47
	v_lshl_add_u64 v[216:217], s[24:25], 0, v[186:187]
	s_add_i32 m0, s1, 0xc000
	ds_read_b128 v[162:165], v210
	ds_read_b128 v[166:169], v210 offset:1024
	ds_read_b128 v[170:173], v210 offset:2048
	ds_read_b128 v[174:177], v210 offset:3072
	ds_read_b128 v[194:197], v210 offset:4096
	ds_read_b128 v[198:201], v210 offset:5120
	ds_read_b128 v[202:205], v210 offset:6144
	ds_read_b128 v[212:215], v210 offset:7168
	global_load_lds_dwordx4 v[216:217], off
	v_lshl_add_u64 v[216:217], s[24:25], 0, v[188:189]
	s_add_i32 m0, s1, 0xe000
	s_nop 0
	global_load_lds_dwordx4 v[216:217], off
	s_mov_b32 m0, s38
	v_lshl_add_u64 v[216:217], v[220:221], 0, s[18:19]
	global_load_lds_dwordx4 v[216:217], off
	s_mov_b32 m0, s39
	v_lshl_add_u64 v[216:217], v[222:223], 0, s[18:19]
	global_load_lds_dwordx4 v[216:217], off
	s_waitcnt vmcnt(10)
	s_waitcnt lgkmcnt(0)
	s_barrier
	s_setprio 1
	v_mfma_f32_16x16x32_bf16 v[126:129], v[130:133], v[162:165], v[126:129]
	v_mfma_f32_16x16x32_bf16 v[122:125], v[138:141], v[162:165], v[122:125]
	v_mfma_f32_16x16x32_bf16 v[110:113], v[130:133], v[170:173], v[110:113]
	v_mfma_f32_16x16x32_bf16 v[106:109], v[138:141], v[170:173], v[106:109]
	v_mfma_f32_16x16x32_bf16 v[94:97], v[130:133], v[194:197], v[94:97]
	v_mfma_f32_16x16x32_bf16 v[90:93], v[138:141], v[194:197], v[90:93]
	v_mfma_f32_16x16x32_bf16 v[78:81], v[130:133], v[202:205], v[78:81]
	v_mfma_f32_16x16x32_bf16 v[74:77], v[138:141], v[202:205], v[74:77]
	v_mfma_f32_16x16x32_bf16 v[126:129], v[134:137], v[166:169], v[126:129]
	v_mfma_f32_16x16x32_bf16 v[122:125], v[142:145], v[166:169], v[122:125]
	v_mfma_f32_16x16x32_bf16 v[110:113], v[134:137], v[174:177], v[110:113]
	v_mfma_f32_16x16x32_bf16 v[106:109], v[142:145], v[174:177], v[106:109]
	v_mfma_f32_16x16x32_bf16 v[94:97], v[134:137], v[198:201], v[94:97]
	v_mfma_f32_16x16x32_bf16 v[90:93], v[142:145], v[198:201], v[90:93]
	v_mfma_f32_16x16x32_bf16 v[78:81], v[134:137], v[212:215], v[78:81]
	v_mfma_f32_16x16x32_bf16 v[74:77], v[142:145], v[212:215], v[74:77]
	s_setprio 0
	s_setprio 1
	v_mfma_f32_16x16x32_bf16 v[118:121], v[146:149], v[162:165], v[118:121]
	v_mfma_f32_16x16x32_bf16 v[114:117], v[154:157], v[162:165], v[114:117]
	v_mfma_f32_16x16x32_bf16 v[102:105], v[146:149], v[170:173], v[102:105]
	v_mfma_f32_16x16x32_bf16 v[98:101], v[154:157], v[170:173], v[98:101]
	v_mfma_f32_16x16x32_bf16 v[86:89], v[146:149], v[194:197], v[86:89]
	v_mfma_f32_16x16x32_bf16 v[82:85], v[154:157], v[194:197], v[82:85]
	v_mfma_f32_16x16x32_bf16 v[70:73], v[146:149], v[202:205], v[70:73]
	v_mfma_f32_16x16x32_bf16 v[66:69], v[154:157], v[202:205], v[66:69]
	v_mfma_f32_16x16x32_bf16 v[118:121], v[150:153], v[166:169], v[118:121]
	v_mfma_f32_16x16x32_bf16 v[114:117], v[158:161], v[166:169], v[114:117]
	v_mfma_f32_16x16x32_bf16 v[102:105], v[150:153], v[174:177], v[102:105]
	v_mfma_f32_16x16x32_bf16 v[98:101], v[158:161], v[174:177], v[98:101]
	v_mfma_f32_16x16x32_bf16 v[86:89], v[150:153], v[198:201], v[86:89]
	v_mfma_f32_16x16x32_bf16 v[82:85], v[158:161], v[198:201], v[82:85]
	v_mfma_f32_16x16x32_bf16 v[70:73], v[150:153], v[212:215], v[70:73]
	v_mfma_f32_16x16x32_bf16 v[66:69], v[158:161], v[212:215], v[66:69]
	s_setprio 0
	s_barrier
	s_add_i32 s24, s41, s0
	v_lshl_add_u64 v[216:217], s[28:29], 0, v[180:181]
	s_mov_b32 m0, s24
	ds_read_b128 v[162:165], v210 offset:16384
	ds_read_b128 v[166:169], v210 offset:17408
	ds_read_b128 v[170:173], v210 offset:18432
	ds_read_b128 v[174:177], v210 offset:19456
	ds_read_b128 v[194:197], v210 offset:20480
	ds_read_b128 v[198:201], v210 offset:21504
	ds_read_b128 v[202:205], v210 offset:22528
	ds_read_b128 v[212:215], v210 offset:23552
	global_load_lds_dwordx4 v[216:217], off
	s_add_i32 m0, s24, 0x2000
	s_add_u32 s24, s28, 0xb0000
	v_lshl_add_u64 v[218:219], s[28:29], 0, v[184:185]
	s_addc_u32 s25, s29, 0
	s_add_i32 s50, s42, s0
	global_load_lds_dwordx4 v[218:219], off
	v_lshl_add_u64 v[220:221], s[24:25], 0, v[180:181]
	s_mov_b32 m0, s50
	v_lshl_add_u64 v[222:223], s[30:31], 0, v[182:183]
	global_load_lds_dwordx4 v[220:221], off
	v_lshl_add_u64 v[220:221], s[24:25], 0, v[184:185]
	s_add_i32 m0, s50, 0x2000
	s_nop 0
	global_load_lds_dwordx4 v[220:221], off
	v_lshl_add_u64 v[220:221], s[30:31], 0, v[178:179]
	s_waitcnt vmcnt(4)
	s_waitcnt lgkmcnt(0)
	s_barrier
; #define PG8_STAGE(bufoff, gbase, voff) do { _Pragma("unroll") for (int _i = 0; _i < 2; ++_i) \
;         __builtin_amdgcn_global_load_lds((const unsigned*)((const char*)(gbase) + (voff)[_i]), (PG8_LAS unsigned*)(lds + (bufoff) + ldsw + _i * 8192), 16, 0, 0); } while (0)
; #define PG8_LDA(dst, b, h) do { _Pragma("unroll") for (int m = 0; m < 4; ++m) _Pragma("unroll") for (int k = 0; k < 2; ++k) dst[m][k] = *(const PG8_LAS bf16x8*)(lds + PG8_SA(b, h) + aoff + m * 2048 + k * 1024); } while (0)
; #define PG8_LDB(dst, b, h) do { _Pragma("unroll") for (int n = 0; n < 2; ++n) _Pragma("unroll") for (int k = 0; k < 2; ++k) dst[n][k] = *(const PG8_LAS bf16x8*)(lds + PG8_SB(b, h) + boff + n * 2048 + k * 1024); } while (0)
; #define PG8_MMA(ai, bj, At, Bt) do { __builtin_amdgcn_s_setprio(1); _Pragma("unroll") for (int m = 0; m < 4; ++m) _Pragma("unroll") for (int n = 0; n < 2; ++n) _Pragma("unroll") for (int k = 0; k < 2; ++k) \
;         acc[ai][bj][m][n] = __builtin_amdgcn_mfma_f32_16x16x32_bf16(Bt[n][k], At[m][k], acc[ai][bj][m][n], 0, 0, 0); __builtin_amdgcn_s_setprio(0); } while (0)
; #define PG8_WAIT_V(n) asm volatile("s_waitcnt vmcnt(" #n ")" ::: "memory")
; #define PG8_WAIT_L(n) asm volatile("s_waitcnt lgkmcnt(" #n ")" ::: "memory")
; #define PG8_BAR __builtin_amdgcn_s_barrier()
; #define PG8_SCHED __builtin_amdgcn_sched_barrier(0)
; template <class Epi, class Sched, bool ALIGN_EPI = false, bool SP2 = false, bool HALFM = false>
; __device__ __forceinline__ void gemm_phase(PG8_LAS unsigned char* lds, const Gemm g, const Sched& S, const Epi& E) {
;     ...
;             PG8_WAIT_V(8); PG8_WAIT_L(0); PG8_BAR; if constexpr (!HALFM) { PG8_MMA(1, 0, At, B0); PG8_MMA(1, 1, At, B1); } PG8_BAR; PG8_SCHED;
;             PG8_LDB(B0, 1, 0); PG8_LDB(B1, 1, 1); PG8_SCHED; PG8_LDA(At, 1, 0); PG8_STAGE(PG8_SA(0, 1), a2 + hstep, voffA);
;             PG8_WAIT_V(8); PG8_WAIT_L(0); PG8_BAR; PG8_MMA(0, 0, At, B0); PG8_MMA(0, 1, At, B1); PG8_BAR; PG8_SCHED;
	s_setprio 1
	v_mfma_f32_16x16x32_bf16 v[62:65], v[130:133], v[162:165], v[62:65]
	v_mfma_f32_16x16x32_bf16 v[58:61], v[138:141], v[162:165], v[58:61]
	v_mfma_f32_16x16x32_bf16 v[46:49], v[130:133], v[170:173], v[46:49]
	v_mfma_f32_16x16x32_bf16 v[42:45], v[138:141], v[170:173], v[42:45]
	v_mfma_f32_16x16x32_bf16 v[30:33], v[130:133], v[194:197], v[30:33]
	v_mfma_f32_16x16x32_bf16 v[26:29], v[138:141], v[194:197], v[26:29]
	v_mfma_f32_16x16x32_bf16 v[14:17], v[130:133], v[202:205], v[14:17]
	v_mfma_f32_16x16x32_bf16 v[10:13], v[138:141], v[202:205], v[10:13]
	v_mfma_f32_16x16x32_bf16 v[62:65], v[134:137], v[166:169], v[62:65]
	v_mfma_f32_16x16x32_bf16 v[58:61], v[142:145], v[166:169], v[58:61]
	v_mfma_f32_16x16x32_bf16 v[46:49], v[134:137], v[174:177], v[46:49]
	v_mfma_f32_16x16x32_bf16 v[42:45], v[142:145], v[174:177], v[42:45]
	v_mfma_f32_16x16x32_bf16 v[30:33], v[134:137], v[198:201], v[30:33]
	v_mfma_f32_16x16x32_bf16 v[26:29], v[142:145], v[198:201], v[26:29]
	v_mfma_f32_16x16x32_bf16 v[14:17], v[134:137], v[212:215], v[14:17]
	v_mfma_f32_16x16x32_bf16 v[10:13], v[142:145], v[212:215], v[10:13]
	s_setprio 0
	s_setprio 1
	v_mfma_f32_16x16x32_bf16 v[54:57], v[146:149], v[162:165], v[54:57]
	v_mfma_f32_16x16x32_bf16 v[50:53], v[154:157], v[162:165], v[50:53]
	v_mfma_f32_16x16x32_bf16 v[38:41], v[146:149], v[170:173], v[38:41]
	v_mfma_f32_16x16x32_bf16 v[34:37], v[154:157], v[170:173], v[34:37]
	v_mfma_f32_16x16x32_bf16 v[22:25], v[146:149], v[194:197], v[22:25]
	v_mfma_f32_16x16x32_bf16 v[18:21], v[154:157], v[194:197], v[18:21]
	v_mfma_f32_16x16x32_bf16 v[6:9], v[146:149], v[202:205], v[6:9]
	v_mfma_f32_16x16x32_bf16 v[2:5], v[154:157], v[202:205], v[2:5]
	v_mfma_f32_16x16x32_bf16 v[54:57], v[150:153], v[166:169], v[54:57]
	v_mfma_f32_16x16x32_bf16 v[50:53], v[158:161], v[166:169], v[50:53]
	v_mfma_f32_16x16x32_bf16 v[38:41], v[150:153], v[174:177], v[38:41]
	v_mfma_f32_16x16x32_bf16 v[34:37], v[158:161], v[174:177], v[34:37]
	v_mfma_f32_16x16x32_bf16 v[22:25], v[150:153], v[198:201], v[22:25]
	v_mfma_f32_16x16x32_bf16 v[18:21], v[158:161], v[198:201], v[18:21]
	v_mfma_f32_16x16x32_bf16 v[6:9], v[150:153], v[212:215], v[6:9]
	v_mfma_f32_16x16x32_bf16 v[2:5], v[158:161], v[212:215], v[2:5]
	s_setprio 0
	s_barrier
	s_add_i32 s50, 0, 0x18000
	s_add_i32 s51, 0, 0x1c000
	v_add_u32_e32 v142, s50, v206
	v_add_u32_e32 v158, s51, v206
	ds_read_b128 v[130:133], v142
	ds_read_b128 v[134:137], v142 offset:1024
	ds_read_b128 v[138:141], v142 offset:2048
	ds_read_b128 v[142:145], v142 offset:3072
	ds_read_b128 v[146:149], v158
	ds_read_b128 v[150:153], v158 offset:1024
	ds_read_b128 v[154:157], v158 offset:2048
	ds_read_b128 v[158:161], v158 offset:3072
	s_add_u32 s24, s30, 0xb0000
	s_addc_u32 s25, s31, 0
	s_mov_b32 m0, s3
	v_lshl_add_u64 v[224:225], s[24:25], 0, v[178:179]
	ds_read_b128 v[162:165], v210 offset:32768
	ds_read_b128 v[166:169], v210 offset:33792
	ds_read_b128 v[170:173], v210 offset:34816
	ds_read_b128 v[174:177], v210 offset:35840
	ds_read_b128 v[194:197], v210 offset:36864
	ds_read_b128 v[198:201], v210 offset:37888
	ds_read_b128 v[202:205], v210 offset:38912
	ds_read_b128 v[212:215], v210 offset:39936
	global_load_lds_dwordx4 v[224:225], off
	v_lshl_add_u64 v[224:225], s[24:25], 0, v[182:183]
	s_mov_b32 m0, s36
	s_nop 0
	global_load_lds_dwordx4 v[224:225], off
	s_mov_b32 m0, s1
	s_nop 0
	global_load_lds_dwordx4 v[220:221], off
	s_mov_b32 m0, s2
	s_nop 0
	global_load_lds_dwordx4 v[222:223], off
	s_waitcnt vmcnt(10)
	s_waitcnt lgkmcnt(0)
	s_barrier
; #define PG8_STAGE(bufoff, gbase, voff) do { _Pragma("unroll") for (int _i = 0; _i < 2; ++_i) \
;         __builtin_amdgcn_global_load_lds((const unsigned*)((const char*)(gbase) + (voff)[_i]), (PG8_LAS unsigned*)(lds + (bufoff) + ldsw + _i * 8192), 16, 0, 0); } while (0)
; #define PG8_LDA(dst, b, h) do { _Pragma("unroll") for (int m = 0; m < 4; ++m) _Pragma("unroll") for (int k = 0; k < 2; ++k) dst[m][k] = *(const PG8_LAS bf16x8*)(lds + PG8_SA(b, h) + aoff + m * 2048 + k * 1024); } while (0)
; #define PG8_MMA(ai, bj, At, Bt) do { __builtin_amdgcn_s_setprio(1); _Pragma("unroll") for (int m = 0; m < 4; ++m) _Pragma("unroll") for (int n = 0; n < 2; ++n) _Pragma("unroll") for (int k = 0; k < 2; ++k) \
;         acc[ai][bj][m][n] = __builtin_amdgcn_mfma_f32_16x16x32_bf16(Bt[n][k], At[m][k], acc[ai][bj][m][n], 0, 0, 0); __builtin_amdgcn_s_setprio(0); } while (0)
; #define PG8_WAIT_V(n) asm volatile("s_waitcnt vmcnt(" #n ")" ::: "memory")
; #define PG8_WAIT_L(n) asm volatile("s_waitcnt lgkmcnt(" #n ")" ::: "memory")
; #define PG8_BAR __builtin_amdgcn_s_barrier()
; #define PG8_SCHED __builtin_amdgcn_sched_barrier(0)
; template <class Epi, class Sched, bool ALIGN_EPI = false, bool SP2 = false, bool HALFM = false>
; __device__ __forceinline__ void gemm_phase(PG8_LAS unsigned char* lds, const Gemm g, const Sched& S, const Epi& E) {
;     ...
;             PG8_WAIT_V(8); PG8_WAIT_L(0); PG8_BAR; PG8_MMA(0, 0, At, B0); PG8_MMA(0, 1, At, B1); PG8_BAR; PG8_SCHED;
;             PG8_LDA(At, 1, 1); PG8_STAGE(PG8_SB(1, 0), b3, voffB); PG8_STAGE(PG8_SB(1, 1), b3 + hstep, voffB); PG8_STAGE(PG8_SA(1, 0), a3, voffA);
;             PG8_WAIT_V(8); PG8_WAIT_L(0); PG8_BAR; if constexpr (!HALFM) { PG8_MMA(1, 0, At, B0); PG8_MMA(1, 1, At, B1); } PG8_BAR; PG8_SCHED;
	s_setprio 1
	v_mfma_f32_16x16x32_bf16 v[126:129], v[130:133], v[162:165], v[126:129]
	v_mfma_f32_16x16x32_bf16 v[122:125], v[138:141], v[162:165], v[122:125]
	v_mfma_f32_16x16x32_bf16 v[110:113], v[130:133], v[170:173], v[110:113]
	v_mfma_f32_16x16x32_bf16 v[106:109], v[138:141], v[170:173], v[106:109]
	v_mfma_f32_16x16x32_bf16 v[94:97], v[130:133], v[194:197], v[94:97]
	v_mfma_f32_16x16x32_bf16 v[90:93], v[138:141], v[194:197], v[90:93]
	v_mfma_f32_16x16x32_bf16 v[78:81], v[130:133], v[202:205], v[78:81]
	v_mfma_f32_16x16x32_bf16 v[74:77], v[138:141], v[202:205], v[74:77]
	v_mfma_f32_16x16x32_bf16 v[126:129], v[134:137], v[166:169], v[126:129]
	v_mfma_f32_16x16x32_bf16 v[122:125], v[142:145], v[166:169], v[122:125]
	v_mfma_f32_16x16x32_bf16 v[110:113], v[134:137], v[174:177], v[110:113]
	v_mfma_f32_16x16x32_bf16 v[106:109], v[142:145], v[174:177], v[106:109]
	v_mfma_f32_16x16x32_bf16 v[94:97], v[134:137], v[198:201], v[94:97]
	v_mfma_f32_16x16x32_bf16 v[90:93], v[142:145], v[198:201], v[90:93]
	v_mfma_f32_16x16x32_bf16 v[78:81], v[134:137], v[212:215], v[78:81]
	v_mfma_f32_16x16x32_bf16 v[74:77], v[142:145], v[212:215], v[74:77]
	s_setprio 0
	s_setprio 1
	v_mfma_f32_16x16x32_bf16 v[118:121], v[146:149], v[162:165], v[118:121]
	v_mfma_f32_16x16x32_bf16 v[114:117], v[154:157], v[162:165], v[114:117]
	v_mfma_f32_16x16x32_bf16 v[102:105], v[146:149], v[170:173], v[102:105]
	v_mfma_f32_16x16x32_bf16 v[98:101], v[154:157], v[170:173], v[98:101]
	v_mfma_f32_16x16x32_bf16 v[86:89], v[146:149], v[194:197], v[86:89]
	v_mfma_f32_16x16x32_bf16 v[82:85], v[154:157], v[194:197], v[82:85]
	v_mfma_f32_16x16x32_bf16 v[70:73], v[146:149], v[202:205], v[70:73]
	v_mfma_f32_16x16x32_bf16 v[66:69], v[154:157], v[202:205], v[66:69]
	v_mfma_f32_16x16x32_bf16 v[118:121], v[150:153], v[166:169], v[118:121]
	v_mfma_f32_16x16x32_bf16 v[114:117], v[158:161], v[166:169], v[114:117]
	v_mfma_f32_16x16x32_bf16 v[102:105], v[150:153], v[174:177], v[102:105]
	v_mfma_f32_16x16x32_bf16 v[98:101], v[158:161], v[174:177], v[98:101]
	v_mfma_f32_16x16x32_bf16 v[86:89], v[150:153], v[198:201], v[86:89]
	v_mfma_f32_16x16x32_bf16 v[82:85], v[158:161], v[198:201], v[82:85]
	v_mfma_f32_16x16x32_bf16 v[70:73], v[150:153], v[212:215], v[70:73]
	v_mfma_f32_16x16x32_bf16 v[66:69], v[158:161], v[212:215], v[66:69]
	s_setprio 0
	s_barrier
	s_add_i32 s24, s50, s0
	v_lshl_add_u64 v[216:217], v[216:217], 0, s[18:19]
	s_mov_b32 m0, s24
	ds_read_b128 v[162:165], v210 offset:49152
	ds_read_b128 v[166:169], v210 offset:50176
	ds_read_b128 v[170:173], v210 offset:51200
	ds_read_b128 v[174:177], v210 offset:52224
	ds_read_b128 v[194:197], v210 offset:53248
	ds_read_b128 v[198:201], v210 offset:54272
	ds_read_b128 v[202:205], v210 offset:55296
	ds_read_b128 v[212:215], v210 offset:56320
	global_load_lds_dwordx4 v[216:217], off
	s_add_i32 m0, s24, 0x2000
	s_add_u32 s24, s28, 0xb0080
	v_lshl_add_u64 v[216:217], v[218:219], 0, s[18:19]
	s_addc_u32 s25, s29, 0
	s_add_i32 s28, s51, s0
	global_load_lds_dwordx4 v[216:217], off
	v_lshl_add_u64 v[216:217], s[24:25], 0, v[180:181]
	s_mov_b32 m0, s28
	s_nop 0
	global_load_lds_dwordx4 v[216:217], off
	v_lshl_add_u64 v[216:217], s[24:25], 0, v[184:185]
	s_add_i32 m0, s28, 0x2000
	s_nop 0
	global_load_lds_dwordx4 v[216:217], off
	s_waitcnt vmcnt(4)
	s_waitcnt lgkmcnt(0)
	s_barrier
	s_setprio 1
	v_mfma_f32_16x16x32_bf16 v[62:65], v[130:133], v[162:165], v[62:65]
	v_mfma_f32_16x16x32_bf16 v[58:61], v[138:141], v[162:165], v[58:61]
	v_mfma_f32_16x16x32_bf16 v[46:49], v[130:133], v[170:173], v[46:49]
	v_mfma_f32_16x16x32_bf16 v[42:45], v[138:141], v[170:173], v[42:45]
	v_mfma_f32_16x16x32_bf16 v[30:33], v[130:133], v[194:197], v[30:33]
	v_mfma_f32_16x16x32_bf16 v[26:29], v[138:141], v[194:197], v[26:29]
	v_mfma_f32_16x16x32_bf16 v[14:17], v[130:133], v[202:205], v[14:17]
	v_mfma_f32_16x16x32_bf16 v[10:13], v[138:141], v[202:205], v[10:13]
	v_mfma_f32_16x16x32_bf16 v[62:65], v[134:137], v[166:169], v[62:65]
	v_mfma_f32_16x16x32_bf16 v[58:61], v[142:145], v[166:169], v[58:61]
	v_mfma_f32_16x16x32_bf16 v[46:49], v[134:137], v[174:177], v[46:49]
	v_mfma_f32_16x16x32_bf16 v[42:45], v[142:145], v[174:177], v[42:45]
	v_mfma_f32_16x16x32_bf16 v[30:33], v[134:137], v[198:201], v[30:33]
	v_mfma_f32_16x16x32_bf16 v[26:29], v[142:145], v[198:201], v[26:29]
	v_mfma_f32_16x16x32_bf16 v[14:17], v[134:137], v[212:215], v[14:17]
	v_mfma_f32_16x16x32_bf16 v[10:13], v[142:145], v[212:215], v[10:13]
	s_setprio 0
	s_setprio 1
	v_mfma_f32_16x16x32_bf16 v[54:57], v[146:149], v[162:165], v[54:57]
	v_mfma_f32_16x16x32_bf16 v[50:53], v[154:157], v[162:165], v[50:53]
	v_mfma_f32_16x16x32_bf16 v[38:41], v[146:149], v[170:173], v[38:41]
	v_mfma_f32_16x16x32_bf16 v[34:37], v[154:157], v[170:173], v[34:37]
	v_mfma_f32_16x16x32_bf16 v[22:25], v[146:149], v[194:197], v[22:25]
	v_mfma_f32_16x16x32_bf16 v[18:21], v[154:157], v[194:197], v[18:21]
	v_mfma_f32_16x16x32_bf16 v[6:9], v[146:149], v[202:205], v[6:9]
	v_mfma_f32_16x16x32_bf16 v[2:5], v[154:157], v[202:205], v[2:5]
	v_mfma_f32_16x16x32_bf16 v[54:57], v[150:153], v[166:169], v[54:57]
	v_mfma_f32_16x16x32_bf16 v[50:53], v[158:161], v[166:169], v[50:53]
	v_mfma_f32_16x16x32_bf16 v[38:41], v[150:153], v[174:177], v[38:41]
	v_mfma_f32_16x16x32_bf16 v[34:37], v[158:161], v[174:177], v[34:37]
	v_mfma_f32_16x16x32_bf16 v[22:25], v[150:153], v[198:201], v[22:25]
	v_mfma_f32_16x16x32_bf16 v[18:21], v[158:161], v[198:201], v[18:21]
	v_mfma_f32_16x16x32_bf16 v[6:9], v[150:153], v[212:215], v[6:9]
	v_mfma_f32_16x16x32_bf16 v[2:5], v[158:161], v[212:215], v[2:5]
	s_setprio 0
	s_barrier
	s_add_i32 s49, s49, 2
	s_add_u32 s47, s47, 0x100
	s_addc_u32 s48, s48, 0
	s_cmp_gt_u32 s49, 41
	s_mov_b64 s[24:25], s[26:27]
	s_cbranch_scc0 .LBB0_637
	s_and_b64 vcc, exec, s[20:21]
	s_cbranch_vccz .LBB0_640
	s_barrier

; #define PG8_STAGE(bufoff, gbase, voff) do { _Pragma("unroll") for (int _i = 0; _i < 2; ++_i) \
;         __builtin_amdgcn_global_load_lds((const unsigned*)((const char*)(gbase) + (voff)[_i]), (PG8_LAS unsigned*)(lds + (bufoff) + ldsw + _i * 8192), 16, 0, 0); } while (0)
; #define PG8_LDA(dst, b, h) do { _Pragma("unroll") for (int m = 0; m < 4; ++m) _Pragma("unroll") for (int k = 0; k < 2; ++k) dst[m][k] = *(const PG8_LAS bf16x8*)(lds + PG8_SA(b, h) + aoff + m * 2048 + k * 1024); } while (0)
; #define PG8_LDB(dst, b, h) do { _Pragma("unroll") for (int n = 0; n < 2; ++n) _Pragma("unroll") for (int k = 0; k < 2; ++k) dst[n][k] = *(const PG8_LAS bf16x8*)(lds + PG8_SB(b, h) + boff + n * 2048 + k * 1024); } while (0)
; #define PG8_MMA(ai, bj, At, Bt) do { __builtin_amdgcn_s_setprio(1); _Pragma("unroll") for (int m = 0; m < 4; ++m) _Pragma("unroll") for (int n = 0; n < 2; ++n) _Pragma("unroll") for (int k = 0; k < 2; ++k) \
;         acc[ai][bj][m][n] = __builtin_amdgcn_mfma_f32_16x16x32_bf16(Bt[n][k], At[m][k], acc[ai][bj][m][n], 0, 0, 0); __builtin_amdgcn_s_setprio(0); } while (0)
; template <class Epi, class Sched, bool ALIGN_EPI = false, bool SP2 = false, bool HALFM = false>
; __device__ __forceinline__ void gemm_phase(PG8_LAS unsigned char* lds, const Gemm g, const Sched& S, const Epi& E) {
;     ...
;             PG8_LDB(B0, 0, 0); PG8_LDB(B1, 0, 1); PG8_SCHED; PG8_LDA(At, 0, 0); PG8_STAGE(PG8_SA(1, 1), a1 + hstep, voffA);
;             PG8_WAIT_V(8); PG8_WAIT_L(0); PG8_BAR; PG8_MMA(0, 0, At, B0); PG8_MMA(0, 1, At, B1); PG8_BAR; PG8_SCHED;
;             PG8_LDA(At, 0, 1); PG8_STAGE(PG8_SB(0, 0), b2, voffB); PG8_STAGE(PG8_SB(0, 1), b2 + hstep, voffB); PG8_STAGE(PG8_SA(0, 0), a2, voffA);
;             PG8_WAIT_V(8); PG8_WAIT_L(0); PG8_BAR; if constexpr (!HALFM) { PG8_MMA(1, 0, At, B0); PG8_MMA(1, 1, At, B1); } PG8_BAR; PG8_SCHED;
;             PG8_LDB(B0, 1, 0); PG8_LDB(B1, 1, 1); PG8_SCHED; PG8_LDA(At, 1, 0); PG8_STAGE(PG8_SA(0, 1), a2 + hstep, voffA);
;             PG8_WAIT_V(8); PG8_WAIT_L(0); PG8_BAR; PG8_MMA(0, 0, At, B0); PG8_MMA(0, 1, At, B1); PG8_BAR; PG8_SCHED;
;             PG8_LDA(At, 1, 1); PG8_STAGE(PG8_SB(1, 0), b3, voffB); PG8_STAGE(PG8_SB(1, 1), b3 + hstep, voffB); PG8_STAGE(PG8_SA(1, 0), a3, voffA);
;             PG8_WAIT_V(8); PG8_WAIT_L(0); PG8_BAR; if constexpr (!HALFM) { PG8_MMA(1, 0, At, B0); PG8_MMA(1, 1, At, B1); } PG8_BAR; PG8_SCHED;
.LBB0_752:
	s_waitcnt lgkmcnt(0)
	ds_read_b128 v[82:85], v190
	ds_read_b128 v[134:137], v190 offset:1024
	ds_read_b128 v[160:163], v190 offset:2048
	ds_read_b128 v[164:167], v190 offset:3072
	ds_read_b128 v[168:171], v191
	ds_read_b128 v[172:175], v191 offset:1024
	ds_read_b128 v[176:179], v191 offset:2048
	ds_read_b128 v[180:183], v191 offset:3072
	s_add_u32 s31, s8, 0xfffc0080
	s_addc_u32 s38, s9, -1
	s_cmp_eq_u32 s29, 12
	s_cselect_b32 s41, s0, s38
	s_cselect_b32 s40, s1, s31
	s_cselect_b32 s39, s2, s11
	s_cselect_b32 s38, s3, s5
	v_lshl_add_u64 v[224:225], s[8:9], 0, v[152:153]
	s_add_i32 m0, s44, 0xc000
	ds_read_b128 v[184:187], v192
	ds_read_b128 v[196:199], v192 offset:1024
	ds_read_b128 v[200:203], v192 offset:2048
	ds_read_b128 v[204:207], v192 offset:3072
	ds_read_b128 v[208:211], v192 offset:4096
	ds_read_b128 v[212:215], v192 offset:5120
	ds_read_b128 v[216:219], v192 offset:6144
	ds_read_b128 v[220:223], v192 offset:7168
	global_load_lds_dwordx4 v[224:225], off
	v_lshl_add_u64 v[224:225], s[8:9], 0, v[154:155]
	s_add_i32 m0, s44, 0xe000
	s_nop 0
	global_load_lds_dwordx4 v[224:225], off
	s_mov_b32 m0, s52
	v_lshl_add_u64 v[224:225], v[228:229], 0, s[20:21]
	global_load_lds_dwordx4 v[224:225], off
	s_mov_b32 m0, s53
	v_lshl_add_u64 v[224:225], v[230:231], 0, s[20:21]
	global_load_lds_dwordx4 v[224:225], off
	s_waitcnt vmcnt(10)
	s_waitcnt lgkmcnt(0)
	s_barrier
	s_setprio 1
	v_mfma_f32_16x16x32_bf16 v[130:133], v[82:85], v[184:187], v[130:133]
	v_mfma_f32_16x16x32_bf16 v[126:129], v[160:163], v[184:187], v[126:129]
	v_mfma_f32_16x16x32_bf16 v[114:117], v[82:85], v[200:203], v[114:117]
	v_mfma_f32_16x16x32_bf16 v[110:113], v[160:163], v[200:203], v[110:113]
	v_mfma_f32_16x16x32_bf16 v[98:101], v[82:85], v[208:211], v[98:101]
	v_mfma_f32_16x16x32_bf16 v[94:97], v[160:163], v[208:211], v[94:97]
	v_mfma_f32_16x16x32_bf16 v[78:81], v[82:85], v[216:219], v[78:81]
	v_mfma_f32_16x16x32_bf16 v[74:77], v[160:163], v[216:219], v[74:77]
	v_mfma_f32_16x16x32_bf16 v[130:133], v[134:137], v[196:199], v[130:133]
	v_mfma_f32_16x16x32_bf16 v[126:129], v[164:167], v[196:199], v[126:129]
	v_mfma_f32_16x16x32_bf16 v[114:117], v[134:137], v[204:207], v[114:117]
	v_mfma_f32_16x16x32_bf16 v[110:113], v[164:167], v[204:207], v[110:113]
	v_mfma_f32_16x16x32_bf16 v[98:101], v[134:137], v[212:215], v[98:101]
	v_mfma_f32_16x16x32_bf16 v[94:97], v[164:167], v[212:215], v[94:97]
	v_mfma_f32_16x16x32_bf16 v[78:81], v[134:137], v[220:223], v[78:81]
	v_mfma_f32_16x16x32_bf16 v[74:77], v[164:167], v[220:223], v[74:77]
	s_setprio 0
	s_setprio 1
	v_mfma_f32_16x16x32_bf16 v[122:125], v[168:171], v[184:187], v[122:125]
	v_mfma_f32_16x16x32_bf16 v[118:121], v[176:179], v[184:187], v[118:121]
	v_mfma_f32_16x16x32_bf16 v[106:109], v[168:171], v[200:203], v[106:109]
	v_mfma_f32_16x16x32_bf16 v[102:105], v[176:179], v[200:203], v[102:105]
	v_mfma_f32_16x16x32_bf16 v[90:93], v[168:171], v[208:211], v[90:93]
	v_mfma_f32_16x16x32_bf16 v[86:89], v[176:179], v[208:211], v[86:89]
	v_mfma_f32_16x16x32_bf16 v[70:73], v[168:171], v[216:219], v[70:73]
	v_mfma_f32_16x16x32_bf16 v[66:69], v[176:179], v[216:219], v[66:69]
	v_mfma_f32_16x16x32_bf16 v[122:125], v[172:175], v[196:199], v[122:125]
	v_mfma_f32_16x16x32_bf16 v[118:121], v[180:183], v[196:199], v[118:121]
	v_mfma_f32_16x16x32_bf16 v[106:109], v[172:175], v[204:207], v[106:109]
	v_mfma_f32_16x16x32_bf16 v[102:105], v[180:183], v[204:207], v[102:105]
	v_mfma_f32_16x16x32_bf16 v[90:93], v[172:175], v[212:215], v[90:93]
	v_mfma_f32_16x16x32_bf16 v[86:89], v[180:183], v[212:215], v[86:89]
	v_mfma_f32_16x16x32_bf16 v[70:73], v[172:175], v[220:223], v[70:73]
	v_mfma_f32_16x16x32_bf16 v[66:69], v[180:183], v[220:223], v[66:69]
	s_setprio 0
	s_barrier
	s_add_i32 s31, s56, s27
	v_lshl_add_u64 v[224:225], s[38:39], 0, v[140:141]
	s_mov_b32 m0, s31
	ds_read_b128 v[184:187], v192 offset:16384
	ds_read_b128 v[196:199], v192 offset:17408
	ds_read_b128 v[200:203], v192 offset:18432
	ds_read_b128 v[204:207], v192 offset:19456
	ds_read_b128 v[208:211], v192 offset:20480
	ds_read_b128 v[212:215], v192 offset:21504
	ds_read_b128 v[216:219], v192 offset:22528
	ds_read_b128 v[220:223], v192 offset:23552
	global_load_lds_dwordx4 v[224:225], off
	s_add_i32 m0, s31, 0x2000
	s_add_u32 s42, s38, 0x40000
	v_lshl_add_u64 v[226:227], s[38:39], 0, v[144:145]
	s_addc_u32 s43, s39, 0
	s_add_i32 s31, s57, s27
	global_load_lds_dwordx4 v[226:227], off
	v_lshl_add_u64 v[228:229], s[42:43], 0, v[140:141]
	s_mov_b32 m0, s31
	v_lshl_add_u64 v[230:231], s[40:41], 0, v[142:143]
	global_load_lds_dwordx4 v[228:229], off
	v_lshl_add_u64 v[228:229], s[42:43], 0, v[144:145]
	s_add_i32 m0, s31, 0x2000
	s_nop 0
	global_load_lds_dwordx4 v[228:229], off
	v_lshl_add_u64 v[228:229], s[40:41], 0, v[138:139]
	s_waitcnt vmcnt(4)
	s_waitcnt lgkmcnt(0)
	s_barrier
; #define PG8_STAGE(bufoff, gbase, voff) do { _Pragma("unroll") for (int _i = 0; _i < 2; ++_i) \
;         __builtin_amdgcn_global_load_lds((const unsigned*)((const char*)(gbase) + (voff)[_i]), (PG8_LAS unsigned*)(lds + (bufoff) + ldsw + _i * 8192), 16, 0, 0); } while (0)
; #define PG8_LDA(dst, b, h) do { _Pragma("unroll") for (int m = 0; m < 4; ++m) _Pragma("unroll") for (int k = 0; k < 2; ++k) dst[m][k] = *(const PG8_LAS bf16x8*)(lds + PG8_SA(b, h) + aoff + m * 2048 + k * 1024); } while (0)
; #define PG8_LDB(dst, b, h) do { _Pragma("unroll") for (int n = 0; n < 2; ++n) _Pragma("unroll") for (int k = 0; k < 2; ++k) dst[n][k] = *(const PG8_LAS bf16x8*)(lds + PG8_SB(b, h) + boff + n * 2048 + k * 1024); } while (0)
; #define PG8_MMA(ai, bj, At, Bt) do { __builtin_amdgcn_s_setprio(1); _Pragma("unroll") for (int m = 0; m < 4; ++m) _Pragma("unroll") for (int n = 0; n < 2; ++n) _Pragma("unroll") for (int k = 0; k < 2; ++k) \
;         acc[ai][bj][m][n] = __builtin_amdgcn_mfma_f32_16x16x32_bf16(Bt[n][k], At[m][k], acc[ai][bj][m][n], 0, 0, 0); __builtin_amdgcn_s_setprio(0); } while (0)
; template <class Epi, class Sched, bool ALIGN_EPI = false, bool SP2 = false, bool HALFM = false>
; __device__ __forceinline__ void gemm_phase(PG8_LAS unsigned char* lds, const Gemm g, const Sched& S, const Epi& E) {
;     ...
;             PG8_LDB(B0, 0, 0); PG8_LDB(B1, 0, 1); PG8_SCHED; PG8_LDA(At, 0, 0); PG8_STAGE(PG8_SA(1, 1), a1 + hstep, voffA);
;             PG8_WAIT_V(8); PG8_WAIT_L(0); PG8_BAR; PG8_MMA(0, 0, At, B0); PG8_MMA(0, 1, At, B1); PG8_BAR; PG8_SCHED;
;             PG8_LDA(At, 0, 1); PG8_STAGE(PG8_SB(0, 0), b2, voffB); PG8_STAGE(PG8_SB(0, 1), b2 + hstep, voffB); PG8_STAGE(PG8_SA(0, 0), a2, voffA);
;             PG8_WAIT_V(8); PG8_WAIT_L(0); PG8_BAR; if constexpr (!HALFM) { PG8_MMA(1, 0, At, B0); PG8_MMA(1, 1, At, B1); } PG8_BAR; PG8_SCHED;
;             PG8_LDB(B0, 1, 0); PG8_LDB(B1, 1, 1); PG8_SCHED; PG8_LDA(At, 1, 0); PG8_STAGE(PG8_SA(0, 1), a2 + hstep, voffA);
;             PG8_WAIT_V(8); PG8_WAIT_L(0); PG8_BAR; PG8_MMA(0, 0, At, B0); PG8_MMA(0, 1, At, B1); PG8_BAR; PG8_SCHED;
;             PG8_LDA(At, 1, 1); PG8_STAGE(PG8_SB(1, 0), b3, voffB); PG8_STAGE(PG8_SB(1, 1), b3 + hstep, voffB); PG8_STAGE(PG8_SA(1, 0), a3, voffA);
;             PG8_WAIT_V(8); PG8_WAIT_L(0); PG8_BAR; if constexpr (!HALFM) { PG8_MMA(1, 0, At, B0); PG8_MMA(1, 1, At, B1); } PG8_BAR; PG8_SCHED;
	s_setprio 1
	v_mfma_f32_16x16x32_bf16 v[62:65], v[82:85], v[184:187], v[62:65]
	v_mfma_f32_16x16x32_bf16 v[58:61], v[160:163], v[184:187], v[58:61]
	v_mfma_f32_16x16x32_bf16 v[46:49], v[82:85], v[200:203], v[46:49]
	v_mfma_f32_16x16x32_bf16 v[42:45], v[160:163], v[200:203], v[42:45]
	v_mfma_f32_16x16x32_bf16 v[30:33], v[82:85], v[208:211], v[30:33]
	v_mfma_f32_16x16x32_bf16 v[26:29], v[160:163], v[208:211], v[26:29]
	v_mfma_f32_16x16x32_bf16 v[14:17], v[82:85], v[216:219], v[14:17]
	v_mfma_f32_16x16x32_bf16 v[10:13], v[160:163], v[216:219], v[10:13]
	v_mfma_f32_16x16x32_bf16 v[62:65], v[134:137], v[196:199], v[62:65]
	v_mfma_f32_16x16x32_bf16 v[58:61], v[164:167], v[196:199], v[58:61]
	v_mfma_f32_16x16x32_bf16 v[46:49], v[134:137], v[204:207], v[46:49]
	v_mfma_f32_16x16x32_bf16 v[42:45], v[164:167], v[204:207], v[42:45]
	v_mfma_f32_16x16x32_bf16 v[30:33], v[134:137], v[212:215], v[30:33]
	v_mfma_f32_16x16x32_bf16 v[26:29], v[164:167], v[212:215], v[26:29]
	v_mfma_f32_16x16x32_bf16 v[14:17], v[134:137], v[220:223], v[14:17]
	v_mfma_f32_16x16x32_bf16 v[10:13], v[164:167], v[220:223], v[10:13]
	s_setprio 0
	s_setprio 1
	v_mfma_f32_16x16x32_bf16 v[54:57], v[168:171], v[184:187], v[54:57]
	v_mfma_f32_16x16x32_bf16 v[50:53], v[176:179], v[184:187], v[50:53]
	v_mfma_f32_16x16x32_bf16 v[38:41], v[168:171], v[200:203], v[38:41]
	v_mfma_f32_16x16x32_bf16 v[34:37], v[176:179], v[200:203], v[34:37]
	v_mfma_f32_16x16x32_bf16 v[22:25], v[168:171], v[208:211], v[22:25]
	v_mfma_f32_16x16x32_bf16 v[18:21], v[176:179], v[208:211], v[18:21]
	v_mfma_f32_16x16x32_bf16 v[6:9], v[168:171], v[216:219], v[6:9]
	v_mfma_f32_16x16x32_bf16 v[2:5], v[176:179], v[216:219], v[2:5]
	v_mfma_f32_16x16x32_bf16 v[54:57], v[172:175], v[196:199], v[54:57]
	v_mfma_f32_16x16x32_bf16 v[50:53], v[180:183], v[196:199], v[50:53]
	v_mfma_f32_16x16x32_bf16 v[38:41], v[172:175], v[204:207], v[38:41]
	v_mfma_f32_16x16x32_bf16 v[34:37], v[180:183], v[204:207], v[34:37]
	v_mfma_f32_16x16x32_bf16 v[22:25], v[172:175], v[212:215], v[22:25]
	v_mfma_f32_16x16x32_bf16 v[18:21], v[180:183], v[212:215], v[18:21]
	v_mfma_f32_16x16x32_bf16 v[6:9], v[172:175], v[220:223], v[6:9]
	v_mfma_f32_16x16x32_bf16 v[2:5], v[180:183], v[220:223], v[2:5]
	s_setprio 0
	s_barrier
	s_add_i32 s31, 0, 0x18000
	s_add_i32 s42, 0, 0x1c000
	v_add_u32_e32 v164, s31, v188
	v_add_u32_e32 v180, s42, v188
	ds_read_b128 v[82:85], v164
	ds_read_b128 v[134:137], v164 offset:1024
	ds_read_b128 v[160:163], v164 offset:2048
	ds_read_b128 v[164:167], v164 offset:3072
	ds_read_b128 v[168:171], v180
	ds_read_b128 v[172:175], v180 offset:1024
	ds_read_b128 v[176:179], v180 offset:2048
	ds_read_b128 v[180:183], v180 offset:3072
	s_add_u32 s40, s40, 0x40000
	s_addc_u32 s41, s41, 0
	s_mov_b32 m0, s48
	v_lshl_add_u64 v[232:233], s[40:41], 0, v[138:139]
	ds_read_b128 v[184:187], v192 offset:32768
	ds_read_b128 v[196:199], v192 offset:33792
	ds_read_b128 v[200:203], v192 offset:34816
	ds_read_b128 v[204:207], v192 offset:35840
	ds_read_b128 v[208:211], v192 offset:36864
	ds_read_b128 v[212:215], v192 offset:37888
	ds_read_b128 v[216:219], v192 offset:38912
	ds_read_b128 v[220:223], v192 offset:39936
	global_load_lds_dwordx4 v[232:233], off
	v_lshl_add_u64 v[232:233], s[40:41], 0, v[142:143]
	s_mov_b32 m0, s49
	s_nop 0
	global_load_lds_dwordx4 v[232:233], off
	s_mov_b32 m0, s44
	s_nop 0
	global_load_lds_dwordx4 v[228:229], off
	s_mov_b32 m0, s45
	s_nop 0
	global_load_lds_dwordx4 v[230:231], off
	s_waitcnt vmcnt(10)
	s_waitcnt lgkmcnt(0)
	s_barrier
	s_setprio 1
	v_mfma_f32_16x16x32_bf16 v[130:133], v[82:85], v[184:187], v[130:133]
	v_mfma_f32_16x16x32_bf16 v[126:129], v[160:163], v[184:187], v[126:129]
	v_mfma_f32_16x16x32_bf16 v[114:117], v[82:85], v[200:203], v[114:117]
	v_mfma_f32_16x16x32_bf16 v[110:113], v[160:163], v[200:203], v[110:113]
	v_mfma_f32_16x16x32_bf16 v[98:101], v[82:85], v[208:211], v[98:101]
	v_mfma_f32_16x16x32_bf16 v[94:97], v[160:163], v[208:211], v[94:97]
	v_mfma_f32_16x16x32_bf16 v[78:81], v[82:85], v[216:219], v[78:81]
	v_mfma_f32_16x16x32_bf16 v[74:77], v[160:163], v[216:219], v[74:77]
	v_mfma_f32_16x16x32_bf16 v[130:133], v[134:137], v[196:199], v[130:133]
	v_mfma_f32_16x16x32_bf16 v[126:129], v[164:167], v[196:199], v[126:129]
	v_mfma_f32_16x16x32_bf16 v[114:117], v[134:137], v[204:207], v[114:117]
	v_mfma_f32_16x16x32_bf16 v[110:113], v[164:167], v[204:207], v[110:113]
	v_mfma_f32_16x16x32_bf16 v[98:101], v[134:137], v[212:215], v[98:101]
	v_mfma_f32_16x16x32_bf16 v[94:97], v[164:167], v[212:215], v[94:97]
	v_mfma_f32_16x16x32_bf16 v[78:81], v[134:137], v[220:223], v[78:81]
	v_mfma_f32_16x16x32_bf16 v[74:77], v[164:167], v[220:223], v[74:77]
	s_setprio 0
	s_setprio 1
	v_mfma_f32_16x16x32_bf16 v[122:125], v[168:171], v[184:187], v[122:125]
	v_mfma_f32_16x16x32_bf16 v[118:121], v[176:179], v[184:187], v[118:121]
	v_mfma_f32_16x16x32_bf16 v[106:109], v[168:171], v[200:203], v[106:109]
	v_mfma_f32_16x16x32_bf16 v[102:105], v[176:179], v[200:203], v[102:105]
	v_mfma_f32_16x16x32_bf16 v[90:93], v[168:171], v[208:211], v[90:93]
	v_mfma_f32_16x16x32_bf16 v[86:89], v[176:179], v[208:211], v[86:89]
	v_mfma_f32_16x16x32_bf16 v[70:73], v[168:171], v[216:219], v[70:73]
	v_mfma_f32_16x16x32_bf16 v[66:69], v[176:179], v[216:219], v[66:69]
	v_mfma_f32_16x16x32_bf16 v[122:125], v[172:175], v[196:199], v[122:125]
	v_mfma_f32_16x16x32_bf16 v[118:121], v[180:183], v[196:199], v[118:121]
	v_mfma_f32_16x16x32_bf16 v[106:109], v[172:175], v[204:207], v[106:109]
	v_mfma_f32_16x16x32_bf16 v[102:105], v[180:183], v[204:207], v[102:105]
	v_mfma_f32_16x16x32_bf16 v[90:93], v[172:175], v[212:215], v[90:93]
	v_mfma_f32_16x16x32_bf16 v[86:89], v[180:183], v[212:215], v[86:89]
	v_mfma_f32_16x16x32_bf16 v[70:73], v[172:175], v[220:223], v[70:73]
	v_mfma_f32_16x16x32_bf16 v[66:69], v[180:183], v[220:223], v[66:69]
	s_setprio 0
	s_barrier
; #define PG8_STAGE(bufoff, gbase, voff) do { _Pragma("unroll") for (int _i = 0; _i < 2; ++_i) \
;         __builtin_amdgcn_global_load_lds((const unsigned*)((const char*)(gbase) + (voff)[_i]), (PG8_LAS unsigned*)(lds + (bufoff) + ldsw + _i * 8192), 16, 0, 0); } while (0)
; #define PG8_LDA(dst, b, h) do { _Pragma("unroll") for (int m = 0; m < 4; ++m) _Pragma("unroll") for (int k = 0; k < 2; ++k) dst[m][k] = *(const PG8_LAS bf16x8*)(lds + PG8_SA(b, h) + aoff + m * 2048 + k * 1024); } while (0)
; #define PG8_LDB(dst, b, h) do { _Pragma("unroll") for (int n = 0; n < 2; ++n) _Pragma("unroll") for (int k = 0; k < 2; ++k) dst[n][k] = *(const PG8_LAS bf16x8*)(lds + PG8_SB(b, h) + boff + n * 2048 + k * 1024); } while (0)
; #define PG8_WAIT_V(n) asm volatile("s_waitcnt vmcnt(" #n ")" ::: "memory")
; #define PG8_WAIT_L(n) asm volatile("s_waitcnt lgkmcnt(" #n ")" ::: "memory")
; #define PG8_BAR __builtin_amdgcn_s_barrier()
; #define PG8_SCHED __builtin_amdgcn_sched_barrier(0)
; template <class Epi, class Sched, bool ALIGN_EPI = false, bool SP2 = false, bool HALFM = false>
; __device__ __forceinline__ void gemm_phase(PG8_LAS unsigned char* lds, const Gemm g, const Sched& S, const Epi& E) {
;     ...
;         for (int t = 0; t < nt; t += 2) {
;     ...
;             PG8_LDB(B0, 0, 0); PG8_LDB(B1, 0, 1); PG8_SCHED; PG8_LDA(At, 0, 0); PG8_STAGE(PG8_SA(1, 1), a1 + hstep, voffA);
;             PG8_WAIT_V(8); PG8_WAIT_L(0); PG8_BAR; PG8_MMA(0, 0, At, B0); PG8_MMA(0, 1, At, B1); PG8_BAR; PG8_SCHED;
;             PG8_LDA(At, 0, 1); PG8_STAGE(PG8_SB(0, 0), b2, voffB); PG8_STAGE(PG8_SB(0, 1), b2 + hstep, voffB); PG8_STAGE(PG8_SA(0, 0), a2, voffA);
;             PG8_WAIT_V(8); PG8_WAIT_L(0); PG8_BAR; if constexpr (!HALFM) { PG8_MMA(1, 0, At, B0); PG8_MMA(1, 1, At, B1); } PG8_BAR; PG8_SCHED;
;             PG8_LDB(B0, 1, 0); PG8_LDB(B1, 1, 1); PG8_SCHED; PG8_LDA(At, 1, 0); PG8_STAGE(PG8_SA(0, 1), a2 + hstep, voffA);
;             PG8_WAIT_V(8); PG8_WAIT_L(0); PG8_BAR; PG8_MMA(0, 0, At, B0); PG8_MMA(0, 1, At, B1); PG8_BAR; PG8_SCHED;
;             PG8_LDA(At, 1, 1); PG8_STAGE(PG8_SB(1, 0), b3, voffB); PG8_STAGE(PG8_SB(1, 1), b3 + hstep, voffB); PG8_STAGE(PG8_SA(1, 0), a3, voffA);
;             PG8_WAIT_V(8); PG8_WAIT_L(0); PG8_BAR; if constexpr (!HALFM) { PG8_MMA(1, 0, At, B0); PG8_MMA(1, 1, At, B1); } PG8_BAR; PG8_SCHED;
	s_add_i32 s31, s31, s27
	v_lshl_add_u64 v[224:225], v[224:225], 0, s[20:21]
	s_mov_b32 m0, s31
	ds_read_b128 v[184:187], v192 offset:49152
	ds_read_b128 v[196:199], v192 offset:50176
	ds_read_b128 v[200:203], v192 offset:51200
	ds_read_b128 v[204:207], v192 offset:52224
	ds_read_b128 v[208:211], v192 offset:53248
	ds_read_b128 v[212:215], v192 offset:54272
	ds_read_b128 v[216:219], v192 offset:55296
	ds_read_b128 v[220:223], v192 offset:56320
	global_load_lds_dwordx4 v[224:225], off
	s_add_i32 m0, s31, 0x2000
	s_add_u32 s38, s38, 0x40080
	v_lshl_add_u64 v[224:225], v[226:227], 0, s[20:21]
	s_addc_u32 s39, s39, 0
	s_add_i32 s31, s42, s27
	global_load_lds_dwordx4 v[224:225], off
	v_lshl_add_u64 v[224:225], s[38:39], 0, v[140:141]
	s_mov_b32 m0, s31
	s_nop 0
	global_load_lds_dwordx4 v[224:225], off
	v_lshl_add_u64 v[224:225], s[38:39], 0, v[144:145]
	s_add_i32 m0, s31, 0x2000
	s_nop 0
	global_load_lds_dwordx4 v[224:225], off
	s_waitcnt vmcnt(4)
	s_waitcnt lgkmcnt(0)
	s_barrier
	s_setprio 1
	v_mfma_f32_16x16x32_bf16 v[62:65], v[82:85], v[184:187], v[62:65]
	v_mfma_f32_16x16x32_bf16 v[58:61], v[160:163], v[184:187], v[58:61]
	v_mfma_f32_16x16x32_bf16 v[46:49], v[82:85], v[200:203], v[46:49]
	v_mfma_f32_16x16x32_bf16 v[42:45], v[160:163], v[200:203], v[42:45]
	v_mfma_f32_16x16x32_bf16 v[30:33], v[82:85], v[208:211], v[30:33]
	v_mfma_f32_16x16x32_bf16 v[26:29], v[160:163], v[208:211], v[26:29]
	v_mfma_f32_16x16x32_bf16 v[14:17], v[82:85], v[216:219], v[14:17]
	v_mfma_f32_16x16x32_bf16 v[10:13], v[160:163], v[216:219], v[10:13]
	v_mfma_f32_16x16x32_bf16 v[62:65], v[134:137], v[196:199], v[62:65]
	v_mfma_f32_16x16x32_bf16 v[58:61], v[164:167], v[196:199], v[58:61]
	v_mfma_f32_16x16x32_bf16 v[46:49], v[134:137], v[204:207], v[46:49]
	v_mfma_f32_16x16x32_bf16 v[42:45], v[164:167], v[204:207], v[42:45]
	v_mfma_f32_16x16x32_bf16 v[30:33], v[134:137], v[212:215], v[30:33]
	v_mfma_f32_16x16x32_bf16 v[26:29], v[164:167], v[212:215], v[26:29]
	v_mfma_f32_16x16x32_bf16 v[14:17], v[134:137], v[220:223], v[14:17]
	v_mfma_f32_16x16x32_bf16 v[10:13], v[164:167], v[220:223], v[10:13]
	s_setprio 0
	s_setprio 1
	v_mfma_f32_16x16x32_bf16 v[54:57], v[168:171], v[184:187], v[54:57]
	v_mfma_f32_16x16x32_bf16 v[50:53], v[176:179], v[184:187], v[50:53]
	v_mfma_f32_16x16x32_bf16 v[38:41], v[168:171], v[200:203], v[38:41]
	v_mfma_f32_16x16x32_bf16 v[34:37], v[176:179], v[200:203], v[34:37]
	v_mfma_f32_16x16x32_bf16 v[22:25], v[168:171], v[208:211], v[22:25]
	v_mfma_f32_16x16x32_bf16 v[18:21], v[176:179], v[208:211], v[18:21]
	v_mfma_f32_16x16x32_bf16 v[6:9], v[168:171], v[216:219], v[6:9]
	v_mfma_f32_16x16x32_bf16 v[2:5], v[176:179], v[216:219], v[2:5]
	v_mfma_f32_16x16x32_bf16 v[54:57], v[172:175], v[196:199], v[54:57]
	v_mfma_f32_16x16x32_bf16 v[50:53], v[180:183], v[196:199], v[50:53]
	v_mfma_f32_16x16x32_bf16 v[38:41], v[172:175], v[204:207], v[38:41]
	v_mfma_f32_16x16x32_bf16 v[34:37], v[180:183], v[204:207], v[34:37]
	v_mfma_f32_16x16x32_bf16 v[22:25], v[172:175], v[212:215], v[22:25]
	v_mfma_f32_16x16x32_bf16 v[18:21], v[180:183], v[212:215], v[18:21]
	v_mfma_f32_16x16x32_bf16 v[6:9], v[172:175], v[220:223], v[6:9]
	v_mfma_f32_16x16x32_bf16 v[2:5], v[180:183], v[220:223], v[2:5]
	s_setprio 0
	s_barrier
	s_add_i32 s29, s29, 2
	s_add_u32 s8, s8, 0x100
	s_addc_u32 s9, s9, 0
	s_add_u32 s5, s5, 0x100
	s_addc_u32 s11, s11, 0
	s_cmp_gt_u32 s29, 13
	s_cbranch_scc0 .LBB0_752
	s_and_b64 vcc, exec, s[22:23]
	s_cbranch_vccnz .LBB0_757
	s_cmp_gt_i32 s10, 45
	s_mov_b64 s[8:9], -1
	s_cbranch_scc1 .LBB0_758

; #define PG8_STAGE(bufoff, gbase, voff) do { _Pragma("unroll") for (int _i = 0; _i < 2; ++_i) \
;         __builtin_amdgcn_global_load_lds((const unsigned*)((const char*)(gbase) + (voff)[_i]), (PG8_LAS unsigned*)(lds + (bufoff) + ldsw + _i * 8192), 16, 0, 0); } while (0)
; #define PG8_LDA(dst, b, h) do { _Pragma("unroll") for (int m = 0; m < 4; ++m) _Pragma("unroll") for (int k = 0; k < 2; ++k) dst[m][k] = *(const PG8_LAS bf16x8*)(lds + PG8_SA(b, h) + aoff + m * 2048 + k * 1024); } while (0)
; #define PG8_LDB(dst, b, h) do { _Pragma("unroll") for (int n = 0; n < 2; ++n) _Pragma("unroll") for (int k = 0; k < 2; ++k) dst[n][k] = *(const PG8_LAS bf16x8*)(lds + PG8_SB(b, h) + boff + n * 2048 + k * 1024); } while (0)
; #define PG8_MMA(ai, bj, At, Bt) do { __builtin_amdgcn_s_setprio(1); _Pragma("unroll") for (int m = 0; m < 4; ++m) _Pragma("unroll") for (int n = 0; n < 2; ++n) _Pragma("unroll") for (int k = 0; k < 2; ++k) \
;         acc[ai][bj][m][n] = __builtin_amdgcn_mfma_f32_16x16x32_bf16(Bt[n][k], At[m][k], acc[ai][bj][m][n], 0, 0, 0); __builtin_amdgcn_s_setprio(0); } while (0)
; template <class Epi, class Sched, bool ALIGN_EPI = false, bool SP2 = false, bool HALFM = false>
; __device__ __forceinline__ void gemm_phase(PG8_LAS unsigned char* lds, const Gemm g, const Sched& S, const Epi& E) {
;     ...
;             PG8_LDB(B0, 0, 0); PG8_LDB(B1, 0, 1); PG8_SCHED; PG8_LDA(At, 0, 0); PG8_STAGE(PG8_SA(1, 1), a1 + hstep, voffA);
;             PG8_WAIT_V(8); PG8_WAIT_L(0); PG8_BAR; PG8_MMA(0, 0, At, B0); PG8_MMA(0, 1, At, B1); PG8_BAR; PG8_SCHED;
;             PG8_LDA(At, 0, 1); PG8_STAGE(PG8_SB(0, 0), b2, voffB); PG8_STAGE(PG8_SB(0, 1), b2 + hstep, voffB); PG8_STAGE(PG8_SA(0, 0), a2, voffA);
;             PG8_WAIT_V(8); PG8_WAIT_L(0); PG8_BAR; if constexpr (!HALFM) { PG8_MMA(1, 0, At, B0); PG8_MMA(1, 1, At, B1); } PG8_BAR; PG8_SCHED;
;             PG8_LDB(B0, 1, 0); PG8_LDB(B1, 1, 1); PG8_SCHED; PG8_LDA(At, 1, 0); PG8_STAGE(PG8_SA(0, 1), a2 + hstep, voffA);
;             PG8_WAIT_V(8); PG8_WAIT_L(0); PG8_BAR; PG8_MMA(0, 0, At, B0); PG8_MMA(0, 1, At, B1); PG8_BAR; PG8_SCHED;
;             PG8_LDA(At, 1, 1); PG8_STAGE(PG8_SB(1, 0), b3, voffB); PG8_STAGE(PG8_SB(1, 1), b3 + hstep, voffB); PG8_STAGE(PG8_SA(1, 0), a3, voffA);
;             PG8_WAIT_V(8); PG8_WAIT_L(0); PG8_BAR; if constexpr (!HALFM) { PG8_MMA(1, 0, At, B0); PG8_MMA(1, 1, At, B1); } PG8_BAR; PG8_SCHED;
.LBB0_1510:
	ds_read_b128 v[130:133], v196
	ds_read_b128 v[134:137], v196 offset:1024
	ds_read_b128 v[138:141], v196 offset:2048
	ds_read_b128 v[142:145], v196 offset:3072
	ds_read_b128 v[146:149], v197
	ds_read_b128 v[150:153], v197 offset:1024
	ds_read_b128 v[154:157], v197 offset:2048
	ds_read_b128 v[158:161], v197 offset:3072
	s_add_u32 s42, s40, 0xfff80080
	s_addc_u32 s43, s41, -1
	s_cmp_eq_u32 s61, 28
	s_cselect_b32 s45, s35, s43
	s_cselect_b32 s44, s57, s42
	s_cselect_b32 s43, s31, s60
	s_cselect_b32 s42, s58, s59
	v_lshl_add_u64 v[216:217], s[40:41], 0, v[174:175]
	s_add_i32 m0, s1, 0xc000
	ds_read_b128 v[162:165], v198
	ds_read_b128 v[182:185], v198 offset:1024
	ds_read_b128 v[186:189], v198 offset:2048
	ds_read_b128 v[190:193], v198 offset:3072
	ds_read_b128 v[200:203], v198 offset:4096
	ds_read_b128 v[204:207], v198 offset:5120
	ds_read_b128 v[208:211], v198 offset:6144
	ds_read_b128 v[212:215], v198 offset:7168
	global_load_lds_dwordx4 v[216:217], off
	v_lshl_add_u64 v[216:217], s[40:41], 0, v[176:177]
	s_add_i32 m0, s1, 0xe000
	s_nop 0
	global_load_lds_dwordx4 v[216:217], off
	s_mov_b32 m0, s47
	v_lshl_add_u64 v[216:217], v[220:221], 0, s[18:19]
	global_load_lds_dwordx4 v[216:217], off
	s_mov_b32 m0, s48
	v_lshl_add_u64 v[216:217], v[222:223], 0, s[18:19]
	global_load_lds_dwordx4 v[216:217], off
	s_waitcnt vmcnt(10)
	s_waitcnt lgkmcnt(0)
	s_barrier
	s_setprio 1
	v_mfma_f32_16x16x32_bf16 v[126:129], v[130:133], v[162:165], v[126:129]
	v_mfma_f32_16x16x32_bf16 v[122:125], v[138:141], v[162:165], v[122:125]
	v_mfma_f32_16x16x32_bf16 v[114:117], v[130:133], v[186:189], v[114:117]
	v_mfma_f32_16x16x32_bf16 v[106:109], v[138:141], v[186:189], v[106:109]
	v_mfma_f32_16x16x32_bf16 v[98:101], v[130:133], v[200:203], v[98:101]
	v_mfma_f32_16x16x32_bf16 v[90:93], v[138:141], v[200:203], v[90:93]
	v_mfma_f32_16x16x32_bf16 v[82:85], v[130:133], v[208:211], v[82:85]
	v_mfma_f32_16x16x32_bf16 v[74:77], v[138:141], v[208:211], v[74:77]
	v_mfma_f32_16x16x32_bf16 v[126:129], v[134:137], v[182:185], v[126:129]
	v_mfma_f32_16x16x32_bf16 v[122:125], v[142:145], v[182:185], v[122:125]
	v_mfma_f32_16x16x32_bf16 v[114:117], v[134:137], v[190:193], v[114:117]
	v_mfma_f32_16x16x32_bf16 v[106:109], v[142:145], v[190:193], v[106:109]
	v_mfma_f32_16x16x32_bf16 v[98:101], v[134:137], v[204:207], v[98:101]
	v_mfma_f32_16x16x32_bf16 v[90:93], v[142:145], v[204:207], v[90:93]
	v_mfma_f32_16x16x32_bf16 v[82:85], v[134:137], v[212:215], v[82:85]
	v_mfma_f32_16x16x32_bf16 v[74:77], v[142:145], v[212:215], v[74:77]
	s_setprio 0
	s_setprio 1
	v_mfma_f32_16x16x32_bf16 v[118:121], v[146:149], v[162:165], v[118:121]
	v_mfma_f32_16x16x32_bf16 v[110:113], v[154:157], v[162:165], v[110:113]
	v_mfma_f32_16x16x32_bf16 v[102:105], v[146:149], v[186:189], v[102:105]
	v_mfma_f32_16x16x32_bf16 v[94:97], v[154:157], v[186:189], v[94:97]
	v_mfma_f32_16x16x32_bf16 v[86:89], v[146:149], v[200:203], v[86:89]
	v_mfma_f32_16x16x32_bf16 v[78:81], v[154:157], v[200:203], v[78:81]
	v_mfma_f32_16x16x32_bf16 v[70:73], v[146:149], v[208:211], v[70:73]
	v_mfma_f32_16x16x32_bf16 v[66:69], v[154:157], v[208:211], v[66:69]
	v_mfma_f32_16x16x32_bf16 v[118:121], v[150:153], v[182:185], v[118:121]
	v_mfma_f32_16x16x32_bf16 v[110:113], v[158:161], v[182:185], v[110:113]
	v_mfma_f32_16x16x32_bf16 v[102:105], v[150:153], v[190:193], v[102:105]
	v_mfma_f32_16x16x32_bf16 v[94:97], v[158:161], v[190:193], v[94:97]
	v_mfma_f32_16x16x32_bf16 v[86:89], v[150:153], v[204:207], v[86:89]
	v_mfma_f32_16x16x32_bf16 v[78:81], v[158:161], v[204:207], v[78:81]
	v_mfma_f32_16x16x32_bf16 v[70:73], v[150:153], v[212:215], v[70:73]
	v_mfma_f32_16x16x32_bf16 v[66:69], v[158:161], v[212:215], v[66:69]
	s_setprio 0
	s_barrier
	s_add_i32 s62, s50, s0
	v_lshl_add_u64 v[216:217], s[42:43], 0, v[168:169]
	s_mov_b32 m0, s62
	ds_read_b128 v[162:165], v198 offset:16384
	ds_read_b128 v[182:185], v198 offset:17408
	ds_read_b128 v[186:189], v198 offset:18432
	ds_read_b128 v[190:193], v198 offset:19456
	ds_read_b128 v[200:203], v198 offset:20480
	ds_read_b128 v[204:207], v198 offset:21504
	ds_read_b128 v[208:211], v198 offset:22528
	ds_read_b128 v[212:215], v198 offset:23552
	global_load_lds_dwordx4 v[216:217], off
	s_add_i32 m0, s62, 0x2000
	s_add_u32 s62, s42, 0x80000
	v_lshl_add_u64 v[218:219], s[42:43], 0, v[172:173]
	s_addc_u32 s63, s43, 0
	s_add_i32 s64, s51, s0
	global_load_lds_dwordx4 v[218:219], off
	v_lshl_add_u64 v[220:221], s[62:63], 0, v[168:169]
	s_mov_b32 m0, s64
	v_lshl_add_u64 v[222:223], s[44:45], 0, v[170:171]
	global_load_lds_dwordx4 v[220:221], off
	v_lshl_add_u64 v[220:221], s[62:63], 0, v[172:173]
	s_add_i32 m0, s64, 0x2000
	s_nop 0
	global_load_lds_dwordx4 v[220:221], off
	v_lshl_add_u64 v[220:221], s[44:45], 0, v[166:167]
	s_waitcnt vmcnt(4)
	s_waitcnt lgkmcnt(0)
	s_barrier
; #define PG8_STAGE(bufoff, gbase, voff) do { _Pragma("unroll") for (int _i = 0; _i < 2; ++_i) \
;         __builtin_amdgcn_global_load_lds((const unsigned*)((const char*)(gbase) + (voff)[_i]), (PG8_LAS unsigned*)(lds + (bufoff) + ldsw + _i * 8192), 16, 0, 0); } while (0)
; #define PG8_LDA(dst, b, h) do { _Pragma("unroll") for (int m = 0; m < 4; ++m) _Pragma("unroll") for (int k = 0; k < 2; ++k) dst[m][k] = *(const PG8_LAS bf16x8*)(lds + PG8_SA(b, h) + aoff + m * 2048 + k * 1024); } while (0)
; #define PG8_LDB(dst, b, h) do { _Pragma("unroll") for (int n = 0; n < 2; ++n) _Pragma("unroll") for (int k = 0; k < 2; ++k) dst[n][k] = *(const PG8_LAS bf16x8*)(lds + PG8_SB(b, h) + boff + n * 2048 + k * 1024); } while (0)
; #define PG8_MMA(ai, bj, At, Bt) do { __builtin_amdgcn_s_setprio(1); _Pragma("unroll") for (int m = 0; m < 4; ++m) _Pragma("unroll") for (int n = 0; n < 2; ++n) _Pragma("unroll") for (int k = 0; k < 2; ++k) \
;         acc[ai][bj][m][n] = __builtin_amdgcn_mfma_f32_16x16x32_bf16(Bt[n][k], At[m][k], acc[ai][bj][m][n], 0, 0, 0); __builtin_amdgcn_s_setprio(0); } while (0)
; template <class Epi, class Sched, bool ALIGN_EPI = false, bool SP2 = false, bool HALFM = false>
; __device__ __forceinline__ void gemm_phase(PG8_LAS unsigned char* lds, const Gemm g, const Sched& S, const Epi& E) {
;     ...
;             PG8_LDB(B0, 0, 0); PG8_LDB(B1, 0, 1); PG8_SCHED; PG8_LDA(At, 0, 0); PG8_STAGE(PG8_SA(1, 1), a1 + hstep, voffA);
;             PG8_WAIT_V(8); PG8_WAIT_L(0); PG8_BAR; PG8_MMA(0, 0, At, B0); PG8_MMA(0, 1, At, B1); PG8_BAR; PG8_SCHED;
;             PG8_LDA(At, 0, 1); PG8_STAGE(PG8_SB(0, 0), b2, voffB); PG8_STAGE(PG8_SB(0, 1), b2 + hstep, voffB); PG8_STAGE(PG8_SA(0, 0), a2, voffA);
;             PG8_WAIT_V(8); PG8_WAIT_L(0); PG8_BAR; if constexpr (!HALFM) { PG8_MMA(1, 0, At, B0); PG8_MMA(1, 1, At, B1); } PG8_BAR; PG8_SCHED;
;             PG8_LDB(B0, 1, 0); PG8_LDB(B1, 1, 1); PG8_SCHED; PG8_LDA(At, 1, 0); PG8_STAGE(PG8_SA(0, 1), a2 + hstep, voffA);
;             PG8_WAIT_V(8); PG8_WAIT_L(0); PG8_BAR; PG8_MMA(0, 0, At, B0); PG8_MMA(0, 1, At, B1); PG8_BAR; PG8_SCHED;
;             PG8_LDA(At, 1, 1); PG8_STAGE(PG8_SB(1, 0), b3, voffB); PG8_STAGE(PG8_SB(1, 1), b3 + hstep, voffB); PG8_STAGE(PG8_SA(1, 0), a3, voffA);
;             PG8_WAIT_V(8); PG8_WAIT_L(0); PG8_BAR; if constexpr (!HALFM) { PG8_MMA(1, 0, At, B0); PG8_MMA(1, 1, At, B1); } PG8_BAR; PG8_SCHED;
	s_setprio 1
	v_mfma_f32_16x16x32_bf16 v[62:65], v[130:133], v[162:165], v[62:65]
	v_mfma_f32_16x16x32_bf16 v[58:61], v[138:141], v[162:165], v[58:61]
	v_mfma_f32_16x16x32_bf16 v[50:53], v[130:133], v[186:189], v[50:53]
	v_mfma_f32_16x16x32_bf16 v[42:45], v[138:141], v[186:189], v[42:45]
	v_mfma_f32_16x16x32_bf16 v[34:37], v[130:133], v[200:203], v[34:37]
	v_mfma_f32_16x16x32_bf16 v[26:29], v[138:141], v[200:203], v[26:29]
	v_mfma_f32_16x16x32_bf16 v[18:21], v[130:133], v[208:211], v[18:21]
	v_mfma_f32_16x16x32_bf16 v[10:13], v[138:141], v[208:211], v[10:13]
	v_mfma_f32_16x16x32_bf16 v[62:65], v[134:137], v[182:185], v[62:65]
	v_mfma_f32_16x16x32_bf16 v[58:61], v[142:145], v[182:185], v[58:61]
	v_mfma_f32_16x16x32_bf16 v[50:53], v[134:137], v[190:193], v[50:53]
	v_mfma_f32_16x16x32_bf16 v[42:45], v[142:145], v[190:193], v[42:45]
	v_mfma_f32_16x16x32_bf16 v[34:37], v[134:137], v[204:207], v[34:37]
	v_mfma_f32_16x16x32_bf16 v[26:29], v[142:145], v[204:207], v[26:29]
	v_mfma_f32_16x16x32_bf16 v[18:21], v[134:137], v[212:215], v[18:21]
	v_mfma_f32_16x16x32_bf16 v[10:13], v[142:145], v[212:215], v[10:13]
	s_setprio 0
	s_setprio 1
	v_mfma_f32_16x16x32_bf16 v[54:57], v[146:149], v[162:165], v[54:57]
	v_mfma_f32_16x16x32_bf16 v[46:49], v[154:157], v[162:165], v[46:49]
	v_mfma_f32_16x16x32_bf16 v[38:41], v[146:149], v[186:189], v[38:41]
	v_mfma_f32_16x16x32_bf16 v[30:33], v[154:157], v[186:189], v[30:33]
	v_mfma_f32_16x16x32_bf16 v[22:25], v[146:149], v[200:203], v[22:25]
	v_mfma_f32_16x16x32_bf16 v[14:17], v[154:157], v[200:203], v[14:17]
	v_mfma_f32_16x16x32_bf16 v[6:9], v[146:149], v[208:211], v[6:9]
	v_mfma_f32_16x16x32_bf16 v[2:5], v[154:157], v[208:211], v[2:5]
	v_mfma_f32_16x16x32_bf16 v[54:57], v[150:153], v[182:185], v[54:57]
	v_mfma_f32_16x16x32_bf16 v[46:49], v[158:161], v[182:185], v[46:49]
	v_mfma_f32_16x16x32_bf16 v[38:41], v[150:153], v[190:193], v[38:41]
	v_mfma_f32_16x16x32_bf16 v[30:33], v[158:161], v[190:193], v[30:33]
	v_mfma_f32_16x16x32_bf16 v[22:25], v[150:153], v[204:207], v[22:25]
	v_mfma_f32_16x16x32_bf16 v[14:17], v[158:161], v[204:207], v[14:17]
	v_mfma_f32_16x16x32_bf16 v[6:9], v[150:153], v[212:215], v[6:9]
	v_mfma_f32_16x16x32_bf16 v[2:5], v[158:161], v[212:215], v[2:5]
	s_setprio 0
	s_barrier
	s_add_i32 s62, 0, 0x18000
	s_add_i32 s63, 0, 0x1c000
	v_add_u32_e32 v142, s62, v194
	v_add_u32_e32 v158, s63, v194
	ds_read_b128 v[130:133], v142
	ds_read_b128 v[134:137], v142 offset:1024
	ds_read_b128 v[138:141], v142 offset:2048
	ds_read_b128 v[142:145], v142 offset:3072
	ds_read_b128 v[146:149], v158
	ds_read_b128 v[150:153], v158 offset:1024
	ds_read_b128 v[154:157], v158 offset:2048
	ds_read_b128 v[158:161], v158 offset:3072
	s_add_u32 s44, s44, 0x80000
	s_addc_u32 s45, s45, 0
	s_mov_b32 m0, s3
	v_lshl_add_u64 v[224:225], s[44:45], 0, v[166:167]
	ds_read_b128 v[162:165], v198 offset:32768
	ds_read_b128 v[182:185], v198 offset:33792
	ds_read_b128 v[186:189], v198 offset:34816
	ds_read_b128 v[190:193], v198 offset:35840
	ds_read_b128 v[200:203], v198 offset:36864
	ds_read_b128 v[204:207], v198 offset:37888
	ds_read_b128 v[208:211], v198 offset:38912
	ds_read_b128 v[212:215], v198 offset:39936
	global_load_lds_dwordx4 v[224:225], off
	v_lshl_add_u64 v[224:225], s[44:45], 0, v[170:171]
	s_mov_b32 m0, s46
	s_nop 0
	global_load_lds_dwordx4 v[224:225], off
	s_mov_b32 m0, s1
	s_nop 0
	global_load_lds_dwordx4 v[220:221], off
	s_mov_b32 m0, s2
	s_nop 0
	global_load_lds_dwordx4 v[222:223], off
	s_waitcnt vmcnt(10)
	s_waitcnt lgkmcnt(0)
	s_barrier
; #define PG8_STAGE(bufoff, gbase, voff) do { _Pragma("unroll") for (int _i = 0; _i < 2; ++_i) \
;         __builtin_amdgcn_global_load_lds((const unsigned*)((const char*)(gbase) + (voff)[_i]), (PG8_LAS unsigned*)(lds + (bufoff) + ldsw + _i * 8192), 16, 0, 0); } while (0)
; #define PG8_LDA(dst, b, h) do { _Pragma("unroll") for (int m = 0; m < 4; ++m) _Pragma("unroll") for (int k = 0; k < 2; ++k) dst[m][k] = *(const PG8_LAS bf16x8*)(lds + PG8_SA(b, h) + aoff + m * 2048 + k * 1024); } while (0)
; #define PG8_LDB(dst, b, h) do { _Pragma("unroll") for (int n = 0; n < 2; ++n) _Pragma("unroll") for (int k = 0; k < 2; ++k) dst[n][k] = *(const PG8_LAS bf16x8*)(lds + PG8_SB(b, h) + boff + n * 2048 + k * 1024); } while (0)
; #define PG8_WAIT_V(n) asm volatile("s_waitcnt vmcnt(" #n ")" ::: "memory")
; #define PG8_WAIT_L(n) asm volatile("s_waitcnt lgkmcnt(" #n ")" ::: "memory")
; #define PG8_BAR __builtin_amdgcn_s_barrier()
; #define PG8_SCHED __builtin_amdgcn_sched_barrier(0)
; template <class Epi, class Sched, bool ALIGN_EPI = false, bool SP2 = false, bool HALFM = false>
; __device__ __forceinline__ void gemm_phase(PG8_LAS unsigned char* lds, const Gemm g, const Sched& S, const Epi& E) {
;     ...
;         for (int t = 0; t < nt; t += 2) {
;     ...
;             PG8_LDB(B0, 0, 0); PG8_LDB(B1, 0, 1); PG8_SCHED; PG8_LDA(At, 0, 0); PG8_STAGE(PG8_SA(1, 1), a1 + hstep, voffA);
;             PG8_WAIT_V(8); PG8_WAIT_L(0); PG8_BAR; PG8_MMA(0, 0, At, B0); PG8_MMA(0, 1, At, B1); PG8_BAR; PG8_SCHED;
;             PG8_LDA(At, 0, 1); PG8_STAGE(PG8_SB(0, 0), b2, voffB); PG8_STAGE(PG8_SB(0, 1), b2 + hstep, voffB); PG8_STAGE(PG8_SA(0, 0), a2, voffA);
;             PG8_WAIT_V(8); PG8_WAIT_L(0); PG8_BAR; if constexpr (!HALFM) { PG8_MMA(1, 0, At, B0); PG8_MMA(1, 1, At, B1); } PG8_BAR; PG8_SCHED;
;             PG8_LDB(B0, 1, 0); PG8_LDB(B1, 1, 1); PG8_SCHED; PG8_LDA(At, 1, 0); PG8_STAGE(PG8_SA(0, 1), a2 + hstep, voffA);
;             PG8_WAIT_V(8); PG8_WAIT_L(0); PG8_BAR; PG8_MMA(0, 0, At, B0); PG8_MMA(0, 1, At, B1); PG8_BAR; PG8_SCHED;
;             PG8_LDA(At, 1, 1); PG8_STAGE(PG8_SB(1, 0), b3, voffB); PG8_STAGE(PG8_SB(1, 1), b3 + hstep, voffB); PG8_STAGE(PG8_SA(1, 0), a3, voffA);
;             PG8_WAIT_V(8); PG8_WAIT_L(0); PG8_BAR; if constexpr (!HALFM) { PG8_MMA(1, 0, At, B0); PG8_MMA(1, 1, At, B1); } PG8_BAR; PG8_SCHED;
	s_setprio 1
	v_mfma_f32_16x16x32_bf16 v[126:129], v[130:133], v[162:165], v[126:129]
	v_mfma_f32_16x16x32_bf16 v[122:125], v[138:141], v[162:165], v[122:125]
	v_mfma_f32_16x16x32_bf16 v[114:117], v[130:133], v[186:189], v[114:117]
	v_mfma_f32_16x16x32_bf16 v[106:109], v[138:141], v[186:189], v[106:109]
	v_mfma_f32_16x16x32_bf16 v[98:101], v[130:133], v[200:203], v[98:101]
	v_mfma_f32_16x16x32_bf16 v[90:93], v[138:141], v[200:203], v[90:93]
	v_mfma_f32_16x16x32_bf16 v[82:85], v[130:133], v[208:211], v[82:85]
	v_mfma_f32_16x16x32_bf16 v[74:77], v[138:141], v[208:211], v[74:77]
	v_mfma_f32_16x16x32_bf16 v[126:129], v[134:137], v[182:185], v[126:129]
	v_mfma_f32_16x16x32_bf16 v[122:125], v[142:145], v[182:185], v[122:125]
	v_mfma_f32_16x16x32_bf16 v[114:117], v[134:137], v[190:193], v[114:117]
	v_mfma_f32_16x16x32_bf16 v[106:109], v[142:145], v[190:193], v[106:109]
	v_mfma_f32_16x16x32_bf16 v[98:101], v[134:137], v[204:207], v[98:101]
	v_mfma_f32_16x16x32_bf16 v[90:93], v[142:145], v[204:207], v[90:93]
	v_mfma_f32_16x16x32_bf16 v[82:85], v[134:137], v[212:215], v[82:85]
	v_mfma_f32_16x16x32_bf16 v[74:77], v[142:145], v[212:215], v[74:77]
	s_setprio 0
	s_setprio 1
	v_mfma_f32_16x16x32_bf16 v[118:121], v[146:149], v[162:165], v[118:121]
	v_mfma_f32_16x16x32_bf16 v[110:113], v[154:157], v[162:165], v[110:113]
	v_mfma_f32_16x16x32_bf16 v[102:105], v[146:149], v[186:189], v[102:105]
	v_mfma_f32_16x16x32_bf16 v[94:97], v[154:157], v[186:189], v[94:97]
	v_mfma_f32_16x16x32_bf16 v[86:89], v[146:149], v[200:203], v[86:89]
	v_mfma_f32_16x16x32_bf16 v[78:81], v[154:157], v[200:203], v[78:81]
	v_mfma_f32_16x16x32_bf16 v[70:73], v[146:149], v[208:211], v[70:73]
	v_mfma_f32_16x16x32_bf16 v[66:69], v[154:157], v[208:211], v[66:69]
	v_mfma_f32_16x16x32_bf16 v[118:121], v[150:153], v[182:185], v[118:121]
	v_mfma_f32_16x16x32_bf16 v[110:113], v[158:161], v[182:185], v[110:113]
	v_mfma_f32_16x16x32_bf16 v[102:105], v[150:153], v[190:193], v[102:105]
	v_mfma_f32_16x16x32_bf16 v[94:97], v[158:161], v[190:193], v[94:97]
	v_mfma_f32_16x16x32_bf16 v[86:89], v[150:153], v[204:207], v[86:89]
	v_mfma_f32_16x16x32_bf16 v[78:81], v[158:161], v[204:207], v[78:81]
	v_mfma_f32_16x16x32_bf16 v[70:73], v[150:153], v[212:215], v[70:73]
	v_mfma_f32_16x16x32_bf16 v[66:69], v[158:161], v[212:215], v[66:69]
	s_setprio 0
	s_barrier
	s_add_i32 s44, s62, s0
	v_lshl_add_u64 v[216:217], v[216:217], 0, s[18:19]
	s_mov_b32 m0, s44
	ds_read_b128 v[162:165], v198 offset:49152
	ds_read_b128 v[182:185], v198 offset:50176
	ds_read_b128 v[186:189], v198 offset:51200
	ds_read_b128 v[190:193], v198 offset:52224
	ds_read_b128 v[200:203], v198 offset:53248
	ds_read_b128 v[204:207], v198 offset:54272
	ds_read_b128 v[208:211], v198 offset:55296
	ds_read_b128 v[212:215], v198 offset:56320
	global_load_lds_dwordx4 v[216:217], off
	s_add_i32 m0, s44, 0x2000
	s_add_u32 s42, s42, 0x80080
	v_lshl_add_u64 v[216:217], v[218:219], 0, s[18:19]
	s_addc_u32 s43, s43, 0
	s_add_i32 s44, s63, s0
	global_load_lds_dwordx4 v[216:217], off
	v_lshl_add_u64 v[216:217], s[42:43], 0, v[168:169]
	s_mov_b32 m0, s44
	s_nop 0
	global_load_lds_dwordx4 v[216:217], off
	v_lshl_add_u64 v[216:217], s[42:43], 0, v[172:173]
	s_add_i32 m0, s44, 0x2000
	s_nop 0
	global_load_lds_dwordx4 v[216:217], off
	s_waitcnt vmcnt(4)
	s_waitcnt lgkmcnt(0)
	s_barrier
	s_setprio 1
	v_mfma_f32_16x16x32_bf16 v[62:65], v[130:133], v[162:165], v[62:65]
	v_mfma_f32_16x16x32_bf16 v[58:61], v[138:141], v[162:165], v[58:61]
	v_mfma_f32_16x16x32_bf16 v[50:53], v[130:133], v[186:189], v[50:53]
	v_mfma_f32_16x16x32_bf16 v[42:45], v[138:141], v[186:189], v[42:45]
	v_mfma_f32_16x16x32_bf16 v[34:37], v[130:133], v[200:203], v[34:37]
	v_mfma_f32_16x16x32_bf16 v[26:29], v[138:141], v[200:203], v[26:29]
	v_mfma_f32_16x16x32_bf16 v[18:21], v[130:133], v[208:211], v[18:21]
	v_mfma_f32_16x16x32_bf16 v[10:13], v[138:141], v[208:211], v[10:13]
	v_mfma_f32_16x16x32_bf16 v[62:65], v[134:137], v[182:185], v[62:65]
	v_mfma_f32_16x16x32_bf16 v[58:61], v[142:145], v[182:185], v[58:61]
	v_mfma_f32_16x16x32_bf16 v[50:53], v[134:137], v[190:193], v[50:53]
	v_mfma_f32_16x16x32_bf16 v[42:45], v[142:145], v[190:193], v[42:45]
	v_mfma_f32_16x16x32_bf16 v[34:37], v[134:137], v[204:207], v[34:37]
	v_mfma_f32_16x16x32_bf16 v[26:29], v[142:145], v[204:207], v[26:29]
	v_mfma_f32_16x16x32_bf16 v[18:21], v[134:137], v[212:215], v[18:21]
	v_mfma_f32_16x16x32_bf16 v[10:13], v[142:145], v[212:215], v[10:13]
	s_setprio 0
	s_setprio 1
	v_mfma_f32_16x16x32_bf16 v[54:57], v[146:149], v[162:165], v[54:57]
	v_mfma_f32_16x16x32_bf16 v[46:49], v[154:157], v[162:165], v[46:49]
	v_mfma_f32_16x16x32_bf16 v[38:41], v[146:149], v[186:189], v[38:41]
	v_mfma_f32_16x16x32_bf16 v[30:33], v[154:157], v[186:189], v[30:33]
	v_mfma_f32_16x16x32_bf16 v[22:25], v[146:149], v[200:203], v[22:25]
	v_mfma_f32_16x16x32_bf16 v[14:17], v[154:157], v[200:203], v[14:17]
	v_mfma_f32_16x16x32_bf16 v[6:9], v[146:149], v[208:211], v[6:9]
	v_mfma_f32_16x16x32_bf16 v[2:5], v[154:157], v[208:211], v[2:5]
	v_mfma_f32_16x16x32_bf16 v[54:57], v[150:153], v[182:185], v[54:57]
	v_mfma_f32_16x16x32_bf16 v[46:49], v[158:161], v[182:185], v[46:49]
	v_mfma_f32_16x16x32_bf16 v[38:41], v[150:153], v[190:193], v[38:41]
	v_mfma_f32_16x16x32_bf16 v[30:33], v[158:161], v[190:193], v[30:33]
	v_mfma_f32_16x16x32_bf16 v[22:25], v[150:153], v[204:207], v[22:25]
	v_mfma_f32_16x16x32_bf16 v[14:17], v[158:161], v[204:207], v[14:17]
	v_mfma_f32_16x16x32_bf16 v[6:9], v[150:153], v[212:215], v[6:9]
	v_mfma_f32_16x16x32_bf16 v[2:5], v[158:161], v[212:215], v[2:5]
	s_setprio 0
	s_barrier
	s_add_i32 s61, s61, 2
	s_add_u32 s40, s40, 0x100
	s_addc_u32 s41, s41, 0
	s_add_u32 s59, s59, 0x100
	s_addc_u32 s60, s60, 0
	s_cmp_gt_u32 s61, 29
	s_cbranch_scc0 .LBB0_1510
	s_and_b64 vcc, exec, s[20:21]
	s_cbranch_vccz .LBB0_1513
	s_barrier

; #define PG8_STAGE(bufoff, gbase, voff) do { _Pragma("unroll") for (int _i = 0; _i < 2; ++_i) \
;         __builtin_amdgcn_global_load_lds((const unsigned*)((const char*)(gbase) + (voff)[_i]), (PG8_LAS unsigned*)(lds + (bufoff) + ldsw + _i * 8192), 16, 0, 0); } while (0)
; #define PG8_LDA(dst, b, h) do { _Pragma("unroll") for (int m = 0; m < 4; ++m) _Pragma("unroll") for (int k = 0; k < 2; ++k) dst[m][k] = *(const PG8_LAS bf16x8*)(lds + PG8_SA(b, h) + aoff + m * 2048 + k * 1024); } while (0)
; #define PG8_LDB(dst, b, h) do { _Pragma("unroll") for (int n = 0; n < 2; ++n) _Pragma("unroll") for (int k = 0; k < 2; ++k) dst[n][k] = *(const PG8_LAS bf16x8*)(lds + PG8_SB(b, h) + boff + n * 2048 + k * 1024); } while (0)
; #define PG8_MMA(ai, bj, At, Bt) do { __builtin_amdgcn_s_setprio(1); _Pragma("unroll") for (int m = 0; m < 4; ++m) _Pragma("unroll") for (int n = 0; n < 2; ++n) _Pragma("unroll") for (int k = 0; k < 2; ++k) \
;         acc[ai][bj][m][n] = __builtin_amdgcn_mfma_f32_16x16x32_bf16(Bt[n][k], At[m][k], acc[ai][bj][m][n], 0, 0, 0); __builtin_amdgcn_s_setprio(0); } while (0)
; template <class Epi, class Sched, bool ALIGN_EPI = false, bool SP2 = false, bool HALFM = false>
; __device__ __forceinline__ void gemm_phase(PG8_LAS unsigned char* lds, const Gemm g, const Sched& S, const Epi& E) {
;     ...
;             PG8_LDB(B0, 0, 0); PG8_LDB(B1, 0, 1); PG8_SCHED; PG8_LDA(At, 0, 0); PG8_STAGE(PG8_SA(1, 1), a1 + hstep, voffA);
;             PG8_WAIT_V(8); PG8_WAIT_L(0); PG8_BAR; PG8_MMA(0, 0, At, B0); PG8_MMA(0, 1, At, B1); PG8_BAR; PG8_SCHED;
;             PG8_LDA(At, 0, 1); PG8_STAGE(PG8_SB(0, 0), b2, voffB); PG8_STAGE(PG8_SB(0, 1), b2 + hstep, voffB); PG8_STAGE(PG8_SA(0, 0), a2, voffA);
;             PG8_WAIT_V(8); PG8_WAIT_L(0); PG8_BAR; if constexpr (!HALFM) { PG8_MMA(1, 0, At, B0); PG8_MMA(1, 1, At, B1); } PG8_BAR; PG8_SCHED;
;             PG8_LDB(B0, 1, 0); PG8_LDB(B1, 1, 1); PG8_SCHED; PG8_LDA(At, 1, 0); PG8_STAGE(PG8_SA(0, 1), a2 + hstep, voffA);
;             PG8_WAIT_V(8); PG8_WAIT_L(0); PG8_BAR; PG8_MMA(0, 0, At, B0); PG8_MMA(0, 1, At, B1); PG8_BAR; PG8_SCHED;
;             PG8_LDA(At, 1, 1); PG8_STAGE(PG8_SB(1, 0), b3, voffB); PG8_STAGE(PG8_SB(1, 1), b3 + hstep, voffB); PG8_STAGE(PG8_SA(1, 0), a3, voffA);
;             PG8_WAIT_V(8); PG8_WAIT_L(0); PG8_BAR; if constexpr (!HALFM) { PG8_MMA(1, 0, At, B0); PG8_MMA(1, 1, At, B1); } PG8_BAR; PG8_SCHED;
.LBB0_1600:
	ds_read_b128 v[130:133], v178
	ds_read_b128 v[134:137], v178 offset:1024
	ds_read_b128 v[138:141], v178 offset:2048
	ds_read_b128 v[142:145], v178 offset:3072
	ds_read_b128 v[146:149], v179
	ds_read_b128 v[166:169], v179 offset:1024
	ds_read_b128 v[170:173], v179 offset:2048
	ds_read_b128 v[182:185], v179 offset:3072
	s_add_u32 s38, s36, 0xfffe0080
	s_addc_u32 s39, s37, -1
	s_cmp_eq_u32 s54, 4
	s_cselect_b32 s41, s27, s39
	s_cselect_b32 s40, s50, s38
	s_cselect_b32 s39, s25, s53
	s_cselect_b32 s38, s51, s52
	v_lshl_add_u64 v[174:175], s[36:37], 0, v[158:159]
	s_add_i32 m0, s1, 0xc000
	ds_read_b128 v[186:189], v180
	ds_read_b128 v[190:193], v180 offset:1024
	ds_read_b128 v[194:197], v180 offset:2048
	ds_read_b128 v[198:201], v180 offset:3072
	ds_read_b128 v[202:205], v180 offset:4096
	ds_read_b128 v[206:209], v180 offset:5120
	ds_read_b128 v[210:213], v180 offset:6144
	ds_read_b128 v[214:217], v180 offset:7168
	global_load_lds_dwordx4 v[174:175], off
	v_lshl_add_u64 v[174:175], s[36:37], 0, v[160:161]
	s_add_i32 m0, s1, 0xe000
	s_nop 0
	global_load_lds_dwordx4 v[174:175], off
	s_mov_b32 m0, s43
	v_lshl_add_u64 v[174:175], v[220:221], 0, s[14:15]
	global_load_lds_dwordx4 v[174:175], off
	s_mov_b32 m0, s44
	v_lshl_add_u64 v[174:175], v[222:223], 0, s[14:15]
	global_load_lds_dwordx4 v[174:175], off
	s_waitcnt vmcnt(10)
	s_waitcnt lgkmcnt(0)
	s_barrier
	s_setprio 1
	v_mfma_f32_16x16x32_bf16 v[126:129], v[130:133], v[186:189], v[126:129]
	v_mfma_f32_16x16x32_bf16 v[122:125], v[138:141], v[186:189], v[122:125]
	v_mfma_f32_16x16x32_bf16 v[110:113], v[130:133], v[194:197], v[110:113]
	v_mfma_f32_16x16x32_bf16 v[106:109], v[138:141], v[194:197], v[106:109]
	v_mfma_f32_16x16x32_bf16 v[94:97], v[130:133], v[202:205], v[94:97]
	v_mfma_f32_16x16x32_bf16 v[90:93], v[138:141], v[202:205], v[90:93]
	v_mfma_f32_16x16x32_bf16 v[78:81], v[130:133], v[210:213], v[78:81]
	v_mfma_f32_16x16x32_bf16 v[74:77], v[138:141], v[210:213], v[74:77]
	v_mfma_f32_16x16x32_bf16 v[126:129], v[134:137], v[190:193], v[126:129]
	v_mfma_f32_16x16x32_bf16 v[122:125], v[142:145], v[190:193], v[122:125]
	v_mfma_f32_16x16x32_bf16 v[110:113], v[134:137], v[198:201], v[110:113]
	v_mfma_f32_16x16x32_bf16 v[106:109], v[142:145], v[198:201], v[106:109]
	v_mfma_f32_16x16x32_bf16 v[94:97], v[134:137], v[206:209], v[94:97]
	v_mfma_f32_16x16x32_bf16 v[90:93], v[142:145], v[206:209], v[90:93]
	v_mfma_f32_16x16x32_bf16 v[78:81], v[134:137], v[214:217], v[78:81]
	v_mfma_f32_16x16x32_bf16 v[74:77], v[142:145], v[214:217], v[74:77]
	s_setprio 0
	s_setprio 1
	v_mfma_f32_16x16x32_bf16 v[118:121], v[146:149], v[186:189], v[118:121]
	v_mfma_f32_16x16x32_bf16 v[114:117], v[170:173], v[186:189], v[114:117]
	v_mfma_f32_16x16x32_bf16 v[102:105], v[146:149], v[194:197], v[102:105]
	v_mfma_f32_16x16x32_bf16 v[98:101], v[170:173], v[194:197], v[98:101]
	v_mfma_f32_16x16x32_bf16 v[86:89], v[146:149], v[202:205], v[86:89]
	v_mfma_f32_16x16x32_bf16 v[82:85], v[170:173], v[202:205], v[82:85]
	v_mfma_f32_16x16x32_bf16 v[70:73], v[146:149], v[210:213], v[70:73]
	v_mfma_f32_16x16x32_bf16 v[66:69], v[170:173], v[210:213], v[66:69]
	v_mfma_f32_16x16x32_bf16 v[118:121], v[166:169], v[190:193], v[118:121]
	v_mfma_f32_16x16x32_bf16 v[114:117], v[182:185], v[190:193], v[114:117]
	v_mfma_f32_16x16x32_bf16 v[102:105], v[166:169], v[198:201], v[102:105]
	v_mfma_f32_16x16x32_bf16 v[98:101], v[182:185], v[198:201], v[98:101]
	v_mfma_f32_16x16x32_bf16 v[86:89], v[166:169], v[206:209], v[86:89]
	v_mfma_f32_16x16x32_bf16 v[82:85], v[182:185], v[206:209], v[82:85]
	v_mfma_f32_16x16x32_bf16 v[70:73], v[166:169], v[214:217], v[70:73]
	v_mfma_f32_16x16x32_bf16 v[66:69], v[182:185], v[214:217], v[66:69]
	s_setprio 0
	s_barrier
	s_add_i32 s55, s46, s0
	v_lshl_add_u64 v[174:175], s[38:39], 0, v[152:153]
	s_mov_b32 m0, s55
	ds_read_b128 v[186:189], v180 offset:16384
	ds_read_b128 v[190:193], v180 offset:17408
	ds_read_b128 v[194:197], v180 offset:18432
	ds_read_b128 v[198:201], v180 offset:19456
	ds_read_b128 v[202:205], v180 offset:20480
	ds_read_b128 v[206:209], v180 offset:21504
	ds_read_b128 v[210:213], v180 offset:22528
	ds_read_b128 v[214:217], v180 offset:23552
	global_load_lds_dwordx4 v[174:175], off
	s_add_i32 m0, s55, 0x2000
	s_add_u32 s56, s38, 0x20000
	v_lshl_add_u64 v[218:219], s[38:39], 0, v[156:157]
	s_addc_u32 s57, s39, 0
	s_add_i32 s55, s47, s0
	global_load_lds_dwordx4 v[218:219], off
	v_lshl_add_u64 v[220:221], s[56:57], 0, v[152:153]
	s_mov_b32 m0, s55
	v_lshl_add_u64 v[222:223], s[40:41], 0, v[154:155]
	global_load_lds_dwordx4 v[220:221], off
	v_lshl_add_u64 v[220:221], s[56:57], 0, v[156:157]
	s_add_i32 m0, s55, 0x2000
	s_nop 0
	global_load_lds_dwordx4 v[220:221], off
	v_lshl_add_u64 v[220:221], s[40:41], 0, v[150:151]
	s_waitcnt vmcnt(4)
	s_waitcnt lgkmcnt(0)
	s_barrier
; #define PG8_STAGE(bufoff, gbase, voff) do { _Pragma("unroll") for (int _i = 0; _i < 2; ++_i) \
;         __builtin_amdgcn_global_load_lds((const unsigned*)((const char*)(gbase) + (voff)[_i]), (PG8_LAS unsigned*)(lds + (bufoff) + ldsw + _i * 8192), 16, 0, 0); } while (0)
; #define PG8_LDA(dst, b, h) do { _Pragma("unroll") for (int m = 0; m < 4; ++m) _Pragma("unroll") for (int k = 0; k < 2; ++k) dst[m][k] = *(const PG8_LAS bf16x8*)(lds + PG8_SA(b, h) + aoff + m * 2048 + k * 1024); } while (0)
; #define PG8_LDB(dst, b, h) do { _Pragma("unroll") for (int n = 0; n < 2; ++n) _Pragma("unroll") for (int k = 0; k < 2; ++k) dst[n][k] = *(const PG8_LAS bf16x8*)(lds + PG8_SB(b, h) + boff + n * 2048 + k * 1024); } while (0)
; #define PG8_MMA(ai, bj, At, Bt) do { __builtin_amdgcn_s_setprio(1); _Pragma("unroll") for (int m = 0; m < 4; ++m) _Pragma("unroll") for (int n = 0; n < 2; ++n) _Pragma("unroll") for (int k = 0; k < 2; ++k) \
;         acc[ai][bj][m][n] = __builtin_amdgcn_mfma_f32_16x16x32_bf16(Bt[n][k], At[m][k], acc[ai][bj][m][n], 0, 0, 0); __builtin_amdgcn_s_setprio(0); } while (0)
; template <class Epi, class Sched, bool ALIGN_EPI = false, bool SP2 = false, bool HALFM = false>
; __device__ __forceinline__ void gemm_phase(PG8_LAS unsigned char* lds, const Gemm g, const Sched& S, const Epi& E) {
;     ...
;             PG8_LDB(B0, 0, 0); PG8_LDB(B1, 0, 1); PG8_SCHED; PG8_LDA(At, 0, 0); PG8_STAGE(PG8_SA(1, 1), a1 + hstep, voffA);
;             PG8_WAIT_V(8); PG8_WAIT_L(0); PG8_BAR; PG8_MMA(0, 0, At, B0); PG8_MMA(0, 1, At, B1); PG8_BAR; PG8_SCHED;
;             PG8_LDA(At, 0, 1); PG8_STAGE(PG8_SB(0, 0), b2, voffB); PG8_STAGE(PG8_SB(0, 1), b2 + hstep, voffB); PG8_STAGE(PG8_SA(0, 0), a2, voffA);
;             PG8_WAIT_V(8); PG8_WAIT_L(0); PG8_BAR; if constexpr (!HALFM) { PG8_MMA(1, 0, At, B0); PG8_MMA(1, 1, At, B1); } PG8_BAR; PG8_SCHED;
;             PG8_LDB(B0, 1, 0); PG8_LDB(B1, 1, 1); PG8_SCHED; PG8_LDA(At, 1, 0); PG8_STAGE(PG8_SA(0, 1), a2 + hstep, voffA);
;             PG8_WAIT_V(8); PG8_WAIT_L(0); PG8_BAR; PG8_MMA(0, 0, At, B0); PG8_MMA(0, 1, At, B1); PG8_BAR; PG8_SCHED;
;             PG8_LDA(At, 1, 1); PG8_STAGE(PG8_SB(1, 0), b3, voffB); PG8_STAGE(PG8_SB(1, 1), b3 + hstep, voffB); PG8_STAGE(PG8_SA(1, 0), a3, voffA);
;             PG8_WAIT_V(8); PG8_WAIT_L(0); PG8_BAR; if constexpr (!HALFM) { PG8_MMA(1, 0, At, B0); PG8_MMA(1, 1, At, B1); } PG8_BAR; PG8_SCHED;
	s_setprio 1
	v_mfma_f32_16x16x32_bf16 v[62:65], v[130:133], v[186:189], v[62:65]
	v_mfma_f32_16x16x32_bf16 v[58:61], v[138:141], v[186:189], v[58:61]
	v_mfma_f32_16x16x32_bf16 v[46:49], v[130:133], v[194:197], v[46:49]
	v_mfma_f32_16x16x32_bf16 v[42:45], v[138:141], v[194:197], v[42:45]
	v_mfma_f32_16x16x32_bf16 v[30:33], v[130:133], v[202:205], v[30:33]
	v_mfma_f32_16x16x32_bf16 v[26:29], v[138:141], v[202:205], v[26:29]
	v_mfma_f32_16x16x32_bf16 v[14:17], v[130:133], v[210:213], v[14:17]
	v_mfma_f32_16x16x32_bf16 v[10:13], v[138:141], v[210:213], v[10:13]
	v_mfma_f32_16x16x32_bf16 v[62:65], v[134:137], v[190:193], v[62:65]
	v_mfma_f32_16x16x32_bf16 v[58:61], v[142:145], v[190:193], v[58:61]
	v_mfma_f32_16x16x32_bf16 v[46:49], v[134:137], v[198:201], v[46:49]
	v_mfma_f32_16x16x32_bf16 v[42:45], v[142:145], v[198:201], v[42:45]
	v_mfma_f32_16x16x32_bf16 v[30:33], v[134:137], v[206:209], v[30:33]
	v_mfma_f32_16x16x32_bf16 v[26:29], v[142:145], v[206:209], v[26:29]
	v_mfma_f32_16x16x32_bf16 v[14:17], v[134:137], v[214:217], v[14:17]
	v_mfma_f32_16x16x32_bf16 v[10:13], v[142:145], v[214:217], v[10:13]
	s_setprio 0
	s_setprio 1
	v_mfma_f32_16x16x32_bf16 v[54:57], v[146:149], v[186:189], v[54:57]
	v_mfma_f32_16x16x32_bf16 v[50:53], v[170:173], v[186:189], v[50:53]
	v_mfma_f32_16x16x32_bf16 v[38:41], v[146:149], v[194:197], v[38:41]
	v_mfma_f32_16x16x32_bf16 v[34:37], v[170:173], v[194:197], v[34:37]
	v_mfma_f32_16x16x32_bf16 v[22:25], v[146:149], v[202:205], v[22:25]
	v_mfma_f32_16x16x32_bf16 v[18:21], v[170:173], v[202:205], v[18:21]
	v_mfma_f32_16x16x32_bf16 v[6:9], v[146:149], v[210:213], v[6:9]
	v_mfma_f32_16x16x32_bf16 v[2:5], v[170:173], v[210:213], v[2:5]
	v_mfma_f32_16x16x32_bf16 v[54:57], v[166:169], v[190:193], v[54:57]
	v_mfma_f32_16x16x32_bf16 v[50:53], v[182:185], v[190:193], v[50:53]
	v_mfma_f32_16x16x32_bf16 v[38:41], v[166:169], v[198:201], v[38:41]
	v_mfma_f32_16x16x32_bf16 v[34:37], v[182:185], v[198:201], v[34:37]
	v_mfma_f32_16x16x32_bf16 v[22:25], v[166:169], v[206:209], v[22:25]
	v_mfma_f32_16x16x32_bf16 v[18:21], v[182:185], v[206:209], v[18:21]
	v_mfma_f32_16x16x32_bf16 v[6:9], v[166:169], v[214:217], v[6:9]
	v_mfma_f32_16x16x32_bf16 v[2:5], v[182:185], v[214:217], v[2:5]
	s_setprio 0
	s_barrier
	s_add_i32 s55, 0, 0x18000
	s_add_i32 s56, 0, 0x1c000
	v_add_u32_e32 v142, s55, v176
	v_add_u32_e32 v181, s56, v176
	ds_read_b128 v[130:133], v142
	ds_read_b128 v[134:137], v142 offset:1024
	ds_read_b128 v[138:141], v142 offset:2048
	ds_read_b128 v[142:145], v142 offset:3072
	ds_read_b128 v[146:149], v181
	ds_read_b128 v[166:169], v181 offset:1024
	ds_read_b128 v[170:173], v181 offset:2048
	ds_read_b128 v[182:185], v181 offset:3072
	s_add_u32 s40, s40, 0x20000
	s_addc_u32 s41, s41, 0
	s_mov_b32 m0, s3
	v_lshl_add_u64 v[224:225], s[40:41], 0, v[150:151]
	ds_read_b128 v[186:189], v180 offset:32768
	ds_read_b128 v[190:193], v180 offset:33792
	ds_read_b128 v[194:197], v180 offset:34816
	ds_read_b128 v[198:201], v180 offset:35840
	ds_read_b128 v[202:205], v180 offset:36864
	ds_read_b128 v[206:209], v180 offset:37888
	ds_read_b128 v[210:213], v180 offset:38912
	ds_read_b128 v[214:217], v180 offset:39936
	global_load_lds_dwordx4 v[224:225], off
	v_lshl_add_u64 v[224:225], s[40:41], 0, v[154:155]
	s_mov_b32 m0, s35
	s_nop 0
	global_load_lds_dwordx4 v[224:225], off
	s_mov_b32 m0, s1
	s_nop 0
	global_load_lds_dwordx4 v[220:221], off
	s_mov_b32 m0, s2
	s_nop 0
	global_load_lds_dwordx4 v[222:223], off
	s_waitcnt vmcnt(10)
	s_waitcnt lgkmcnt(0)
	s_barrier
; #define PG8_STAGE(bufoff, gbase, voff) do { _Pragma("unroll") for (int _i = 0; _i < 2; ++_i) \
;         __builtin_amdgcn_global_load_lds((const unsigned*)((const char*)(gbase) + (voff)[_i]), (PG8_LAS unsigned*)(lds + (bufoff) + ldsw + _i * 8192), 16, 0, 0); } while (0)
; #define PG8_LDA(dst, b, h) do { _Pragma("unroll") for (int m = 0; m < 4; ++m) _Pragma("unroll") for (int k = 0; k < 2; ++k) dst[m][k] = *(const PG8_LAS bf16x8*)(lds + PG8_SA(b, h) + aoff + m * 2048 + k * 1024); } while (0)
; #define PG8_LDB(dst, b, h) do { _Pragma("unroll") for (int n = 0; n < 2; ++n) _Pragma("unroll") for (int k = 0; k < 2; ++k) dst[n][k] = *(const PG8_LAS bf16x8*)(lds + PG8_SB(b, h) + boff + n * 2048 + k * 1024); } while (0)
; #define PG8_WAIT_V(n) asm volatile("s_waitcnt vmcnt(" #n ")" ::: "memory")
; #define PG8_WAIT_L(n) asm volatile("s_waitcnt lgkmcnt(" #n ")" ::: "memory")
; #define PG8_BAR __builtin_amdgcn_s_barrier()
; #define PG8_SCHED __builtin_amdgcn_sched_barrier(0)
; template <class Epi, class Sched, bool ALIGN_EPI = false, bool SP2 = false, bool HALFM = false>
; __device__ __forceinline__ void gemm_phase(PG8_LAS unsigned char* lds, const Gemm g, const Sched& S, const Epi& E) {
;     ...
;         for (int t = 0; t < nt; t += 2) {
;     ...
;             PG8_LDB(B0, 0, 0); PG8_LDB(B1, 0, 1); PG8_SCHED; PG8_LDA(At, 0, 0); PG8_STAGE(PG8_SA(1, 1), a1 + hstep, voffA);
;             PG8_WAIT_V(8); PG8_WAIT_L(0); PG8_BAR; PG8_MMA(0, 0, At, B0); PG8_MMA(0, 1, At, B1); PG8_BAR; PG8_SCHED;
;             PG8_LDA(At, 0, 1); PG8_STAGE(PG8_SB(0, 0), b2, voffB); PG8_STAGE(PG8_SB(0, 1), b2 + hstep, voffB); PG8_STAGE(PG8_SA(0, 0), a2, voffA);
;             PG8_WAIT_V(8); PG8_WAIT_L(0); PG8_BAR; if constexpr (!HALFM) { PG8_MMA(1, 0, At, B0); PG8_MMA(1, 1, At, B1); } PG8_BAR; PG8_SCHED;
;             PG8_LDB(B0, 1, 0); PG8_LDB(B1, 1, 1); PG8_SCHED; PG8_LDA(At, 1, 0); PG8_STAGE(PG8_SA(0, 1), a2 + hstep, voffA);
;             PG8_WAIT_V(8); PG8_WAIT_L(0); PG8_BAR; PG8_MMA(0, 0, At, B0); PG8_MMA(0, 1, At, B1); PG8_BAR; PG8_SCHED;
;             PG8_LDA(At, 1, 1); PG8_STAGE(PG8_SB(1, 0), b3, voffB); PG8_STAGE(PG8_SB(1, 1), b3 + hstep, voffB); PG8_STAGE(PG8_SA(1, 0), a3, voffA);
;             PG8_WAIT_V(8); PG8_WAIT_L(0); PG8_BAR; if constexpr (!HALFM) { PG8_MMA(1, 0, At, B0); PG8_MMA(1, 1, At, B1); } PG8_BAR; PG8_SCHED;
	s_setprio 1
	v_mfma_f32_16x16x32_bf16 v[126:129], v[130:133], v[186:189], v[126:129]
	v_mfma_f32_16x16x32_bf16 v[122:125], v[138:141], v[186:189], v[122:125]
	v_mfma_f32_16x16x32_bf16 v[110:113], v[130:133], v[194:197], v[110:113]
	v_mfma_f32_16x16x32_bf16 v[106:109], v[138:141], v[194:197], v[106:109]
	v_mfma_f32_16x16x32_bf16 v[94:97], v[130:133], v[202:205], v[94:97]
	v_mfma_f32_16x16x32_bf16 v[90:93], v[138:141], v[202:205], v[90:93]
	v_mfma_f32_16x16x32_bf16 v[78:81], v[130:133], v[210:213], v[78:81]
	v_mfma_f32_16x16x32_bf16 v[74:77], v[138:141], v[210:213], v[74:77]
	v_mfma_f32_16x16x32_bf16 v[126:129], v[134:137], v[190:193], v[126:129]
	v_mfma_f32_16x16x32_bf16 v[122:125], v[142:145], v[190:193], v[122:125]
	v_mfma_f32_16x16x32_bf16 v[110:113], v[134:137], v[198:201], v[110:113]
	v_mfma_f32_16x16x32_bf16 v[106:109], v[142:145], v[198:201], v[106:109]
	v_mfma_f32_16x16x32_bf16 v[94:97], v[134:137], v[206:209], v[94:97]
	v_mfma_f32_16x16x32_bf16 v[90:93], v[142:145], v[206:209], v[90:93]
	v_mfma_f32_16x16x32_bf16 v[78:81], v[134:137], v[214:217], v[78:81]
	v_mfma_f32_16x16x32_bf16 v[74:77], v[142:145], v[214:217], v[74:77]
	s_setprio 0
	s_setprio 1
	v_mfma_f32_16x16x32_bf16 v[118:121], v[146:149], v[186:189], v[118:121]
	v_mfma_f32_16x16x32_bf16 v[114:117], v[170:173], v[186:189], v[114:117]
	v_mfma_f32_16x16x32_bf16 v[102:105], v[146:149], v[194:197], v[102:105]
	v_mfma_f32_16x16x32_bf16 v[98:101], v[170:173], v[194:197], v[98:101]
	v_mfma_f32_16x16x32_bf16 v[86:89], v[146:149], v[202:205], v[86:89]
	v_mfma_f32_16x16x32_bf16 v[82:85], v[170:173], v[202:205], v[82:85]
	v_mfma_f32_16x16x32_bf16 v[70:73], v[146:149], v[210:213], v[70:73]
	v_mfma_f32_16x16x32_bf16 v[66:69], v[170:173], v[210:213], v[66:69]
	v_mfma_f32_16x16x32_bf16 v[118:121], v[166:169], v[190:193], v[118:121]
	v_mfma_f32_16x16x32_bf16 v[114:117], v[182:185], v[190:193], v[114:117]
	v_mfma_f32_16x16x32_bf16 v[102:105], v[166:169], v[198:201], v[102:105]
	v_mfma_f32_16x16x32_bf16 v[98:101], v[182:185], v[198:201], v[98:101]
	v_mfma_f32_16x16x32_bf16 v[86:89], v[166:169], v[206:209], v[86:89]
	v_mfma_f32_16x16x32_bf16 v[82:85], v[182:185], v[206:209], v[82:85]
	v_mfma_f32_16x16x32_bf16 v[70:73], v[166:169], v[214:217], v[70:73]
	v_mfma_f32_16x16x32_bf16 v[66:69], v[182:185], v[214:217], v[66:69]
	s_setprio 0
	s_barrier
	s_add_i32 s40, s55, s0
	v_lshl_add_u64 v[174:175], v[174:175], 0, s[14:15]
	s_mov_b32 m0, s40
	ds_read_b128 v[186:189], v180 offset:49152
	ds_read_b128 v[190:193], v180 offset:50176
	ds_read_b128 v[194:197], v180 offset:51200
	ds_read_b128 v[198:201], v180 offset:52224
	ds_read_b128 v[202:205], v180 offset:53248
	ds_read_b128 v[206:209], v180 offset:54272
	ds_read_b128 v[210:213], v180 offset:55296
	ds_read_b128 v[214:217], v180 offset:56320
	global_load_lds_dwordx4 v[174:175], off
	s_add_i32 m0, s40, 0x2000
	s_add_u32 s38, s38, 0x20080
	v_lshl_add_u64 v[174:175], v[218:219], 0, s[14:15]
	s_addc_u32 s39, s39, 0
	s_add_i32 s40, s56, s0
	global_load_lds_dwordx4 v[174:175], off
	v_lshl_add_u64 v[174:175], s[38:39], 0, v[152:153]
	s_mov_b32 m0, s40
	s_nop 0
	global_load_lds_dwordx4 v[174:175], off
	v_lshl_add_u64 v[174:175], s[38:39], 0, v[156:157]
	s_add_i32 m0, s40, 0x2000
	s_nop 0
	global_load_lds_dwordx4 v[174:175], off
	s_waitcnt vmcnt(4)
	s_waitcnt lgkmcnt(0)
	s_barrier
	s_setprio 1
	v_mfma_f32_16x16x32_bf16 v[62:65], v[130:133], v[186:189], v[62:65]
	v_mfma_f32_16x16x32_bf16 v[58:61], v[138:141], v[186:189], v[58:61]
	v_mfma_f32_16x16x32_bf16 v[46:49], v[130:133], v[194:197], v[46:49]
	v_mfma_f32_16x16x32_bf16 v[42:45], v[138:141], v[194:197], v[42:45]
	v_mfma_f32_16x16x32_bf16 v[30:33], v[130:133], v[202:205], v[30:33]
	v_mfma_f32_16x16x32_bf16 v[26:29], v[138:141], v[202:205], v[26:29]
	v_mfma_f32_16x16x32_bf16 v[14:17], v[130:133], v[210:213], v[14:17]
	v_mfma_f32_16x16x32_bf16 v[10:13], v[138:141], v[210:213], v[10:13]
	v_mfma_f32_16x16x32_bf16 v[62:65], v[134:137], v[190:193], v[62:65]
	v_mfma_f32_16x16x32_bf16 v[58:61], v[142:145], v[190:193], v[58:61]
	v_mfma_f32_16x16x32_bf16 v[46:49], v[134:137], v[198:201], v[46:49]
	v_mfma_f32_16x16x32_bf16 v[42:45], v[142:145], v[198:201], v[42:45]
	v_mfma_f32_16x16x32_bf16 v[30:33], v[134:137], v[206:209], v[30:33]
	v_mfma_f32_16x16x32_bf16 v[26:29], v[142:145], v[206:209], v[26:29]
	v_mfma_f32_16x16x32_bf16 v[14:17], v[134:137], v[214:217], v[14:17]
	v_mfma_f32_16x16x32_bf16 v[10:13], v[142:145], v[214:217], v[10:13]
	s_setprio 0
	s_setprio 1
	v_mfma_f32_16x16x32_bf16 v[54:57], v[146:149], v[186:189], v[54:57]
	v_mfma_f32_16x16x32_bf16 v[50:53], v[170:173], v[186:189], v[50:53]
	v_mfma_f32_16x16x32_bf16 v[38:41], v[146:149], v[194:197], v[38:41]
	v_mfma_f32_16x16x32_bf16 v[34:37], v[170:173], v[194:197], v[34:37]
	v_mfma_f32_16x16x32_bf16 v[22:25], v[146:149], v[202:205], v[22:25]
	v_mfma_f32_16x16x32_bf16 v[18:21], v[170:173], v[202:205], v[18:21]
	v_mfma_f32_16x16x32_bf16 v[6:9], v[146:149], v[210:213], v[6:9]
	v_mfma_f32_16x16x32_bf16 v[2:5], v[170:173], v[210:213], v[2:5]
	v_mfma_f32_16x16x32_bf16 v[54:57], v[166:169], v[190:193], v[54:57]
	v_mfma_f32_16x16x32_bf16 v[50:53], v[182:185], v[190:193], v[50:53]
	v_mfma_f32_16x16x32_bf16 v[38:41], v[166:169], v[198:201], v[38:41]
	v_mfma_f32_16x16x32_bf16 v[34:37], v[182:185], v[198:201], v[34:37]
	v_mfma_f32_16x16x32_bf16 v[22:25], v[166:169], v[206:209], v[22:25]
	v_mfma_f32_16x16x32_bf16 v[18:21], v[182:185], v[206:209], v[18:21]
	v_mfma_f32_16x16x32_bf16 v[6:9], v[166:169], v[214:217], v[6:9]
	v_mfma_f32_16x16x32_bf16 v[2:5], v[182:185], v[214:217], v[2:5]
	s_setprio 0
	s_barrier
	s_add_i32 s54, s54, 2
	s_add_u32 s36, s36, 0x100
	s_addc_u32 s37, s37, 0
	s_add_u32 s52, s52, 0x100
	s_addc_u32 s53, s53, 0
	s_cmp_gt_u32 s54, 5
	s_cbranch_scc0 .LBB0_1600
	s_and_b64 vcc, exec, s[20:21]
	s_cbranch_vccz .LBB0_1603
	s_barrier

; #define PG8_STAGE(bufoff, gbase, voff) do { _Pragma("unroll") for (int _i = 0; _i < 2; ++_i) \
;         __builtin_amdgcn_global_load_lds((const unsigned*)((const char*)(gbase) + (voff)[_i]), (PG8_LAS unsigned*)(lds + (bufoff) + ldsw + _i * 8192), 16, 0, 0); } while (0)
; #define PG8_LDA(dst, b, h) do { _Pragma("unroll") for (int m = 0; m < 4; ++m) _Pragma("unroll") for (int k = 0; k < 2; ++k) dst[m][k] = *(const PG8_LAS bf16x8*)(lds + PG8_SA(b, h) + aoff + m * 2048 + k * 1024); } while (0)
; #define PG8_LDB(dst, b, h) do { _Pragma("unroll") for (int n = 0; n < 2; ++n) _Pragma("unroll") for (int k = 0; k < 2; ++k) dst[n][k] = *(const PG8_LAS bf16x8*)(lds + PG8_SB(b, h) + boff + n * 2048 + k * 1024); } while (0)
; #define PG8_MMA(ai, bj, At, Bt) do { __builtin_amdgcn_s_setprio(1); _Pragma("unroll") for (int m = 0; m < 4; ++m) _Pragma("unroll") for (int n = 0; n < 2; ++n) _Pragma("unroll") for (int k = 0; k < 2; ++k) \
;         acc[ai][bj][m][n] = __builtin_amdgcn_mfma_f32_16x16x32_bf16(Bt[n][k], At[m][k], acc[ai][bj][m][n], 0, 0, 0); __builtin_amdgcn_s_setprio(0); } while (0)
; template <class Epi, class Sched, bool ALIGN_EPI = false, bool SP2 = false, bool HALFM = false>
; __device__ __forceinline__ void gemm_phase(PG8_LAS unsigned char* lds, const Gemm g, const Sched& S, const Epi& E) {
;     ...
;             PG8_LDB(B0, 0, 0); PG8_LDB(B1, 0, 1); PG8_SCHED; PG8_LDA(At, 0, 0); PG8_STAGE(PG8_SA(1, 1), a1 + hstep, voffA);
;             PG8_WAIT_V(8); PG8_WAIT_L(0); PG8_BAR; PG8_MMA(0, 0, At, B0); PG8_MMA(0, 1, At, B1); PG8_BAR; PG8_SCHED;
;             PG8_LDA(At, 0, 1); PG8_STAGE(PG8_SB(0, 0), b2, voffB); PG8_STAGE(PG8_SB(0, 1), b2 + hstep, voffB); PG8_STAGE(PG8_SA(0, 0), a2, voffA);
;             PG8_WAIT_V(8); PG8_WAIT_L(0); PG8_BAR; if constexpr (!HALFM) { PG8_MMA(1, 0, At, B0); PG8_MMA(1, 1, At, B1); } PG8_BAR; PG8_SCHED;
;             PG8_LDB(B0, 1, 0); PG8_LDB(B1, 1, 1); PG8_SCHED; PG8_LDA(At, 1, 0); PG8_STAGE(PG8_SA(0, 1), a2 + hstep, voffA);
;             PG8_WAIT_V(8); PG8_WAIT_L(0); PG8_BAR; PG8_MMA(0, 0, At, B0); PG8_MMA(0, 1, At, B1); PG8_BAR; PG8_SCHED;
;             PG8_LDA(At, 1, 1); PG8_STAGE(PG8_SB(1, 0), b3, voffB); PG8_STAGE(PG8_SB(1, 1), b3 + hstep, voffB); PG8_STAGE(PG8_SA(1, 0), a3, voffA);
;             PG8_WAIT_V(8); PG8_WAIT_L(0); PG8_BAR; if constexpr (!HALFM) { PG8_MMA(1, 0, At, B0); PG8_MMA(1, 1, At, B1); } PG8_BAR; PG8_SCHED;
.LBB0_1692:
	ds_read_b128 v[114:117], v246
	ds_read_b128 v[118:121], v246 offset:1024
	ds_read_b128 v[130:133], v246 offset:2048
	ds_read_b128 v[134:137], v246 offset:3072
	ds_read_b128 v[138:141], v247
	ds_read_b128 v[142:145], v247 offset:1024
	ds_read_b128 v[146:149], v247 offset:2048
	ds_read_b128 v[158:161], v247 offset:3072
	s_add_u32 s38, s36, 0xfffc0080
	s_addc_u32 s39, s37, -1
	s_cmp_eq_u32 s53, 12
	s_cselect_b32 s41, s25, s39
	s_cselect_b32 s40, s31, s38
	s_cselect_b32 s39, s23, s52
	s_cselect_b32 s38, s50, s51
	v_lshl_add_u64 v[206:207], s[36:37], 0, v[202:203]
	s_add_i32 m0, s1, 0xc000
	ds_read_b128 v[162:165], v248
	ds_read_b128 v[166:169], v248 offset:1024
	ds_read_b128 v[170:173], v248 offset:2048
	ds_read_b128 v[174:177], v248 offset:3072
	ds_read_b128 v[178:181], v248 offset:4096
	ds_read_b128 v[182:185], v248 offset:5120
	ds_read_b128 v[186:189], v248 offset:6144
	ds_read_b128 v[190:193], v248 offset:7168
	global_load_lds_dwordx4 v[206:207], off
	v_lshl_add_u64 v[206:207], s[36:37], 0, v[204:205]
	s_add_i32 m0, s1, 0xe000
	s_nop 0
	global_load_lds_dwordx4 v[206:207], off
	s_mov_b32 m0, s43
	v_lshl_add_u64 v[206:207], v[210:211], 0, s[10:11]
	global_load_lds_dwordx4 v[206:207], off
	s_mov_b32 m0, s44
	v_lshl_add_u64 v[206:207], v[212:213], 0, s[10:11]
	global_load_lds_dwordx4 v[206:207], off
	s_waitcnt vmcnt(10)
	s_waitcnt lgkmcnt(0)
	s_barrier
	s_setprio 1
	v_mfma_f32_16x16x32_bf16 v[154:157], v[114:117], v[162:165], v[154:157]
	v_mfma_f32_16x16x32_bf16 v[150:153], v[130:133], v[162:165], v[150:153]
	v_mfma_f32_16x16x32_bf16 v[110:113], v[114:117], v[170:173], v[110:113]
	v_mfma_f32_16x16x32_bf16 v[106:109], v[130:133], v[170:173], v[106:109]
	v_mfma_f32_16x16x32_bf16 v[94:97], v[114:117], v[178:181], v[94:97]
	v_mfma_f32_16x16x32_bf16 v[90:93], v[130:133], v[178:181], v[90:93]
	v_mfma_f32_16x16x32_bf16 v[78:81], v[114:117], v[186:189], v[78:81]
	v_mfma_f32_16x16x32_bf16 v[74:77], v[130:133], v[186:189], v[74:77]
	v_mfma_f32_16x16x32_bf16 v[154:157], v[118:121], v[166:169], v[154:157]
	v_mfma_f32_16x16x32_bf16 v[150:153], v[134:137], v[166:169], v[150:153]
	v_mfma_f32_16x16x32_bf16 v[110:113], v[118:121], v[174:177], v[110:113]
	v_mfma_f32_16x16x32_bf16 v[106:109], v[134:137], v[174:177], v[106:109]
	v_mfma_f32_16x16x32_bf16 v[94:97], v[118:121], v[182:185], v[94:97]
	v_mfma_f32_16x16x32_bf16 v[90:93], v[134:137], v[182:185], v[90:93]
	v_mfma_f32_16x16x32_bf16 v[78:81], v[118:121], v[190:193], v[78:81]
	v_mfma_f32_16x16x32_bf16 v[74:77], v[134:137], v[190:193], v[74:77]
	s_setprio 0
	s_setprio 1
	v_mfma_f32_16x16x32_bf16 v[126:129], v[138:141], v[162:165], v[126:129]
	v_mfma_f32_16x16x32_bf16 v[122:125], v[146:149], v[162:165], v[122:125]
	v_mfma_f32_16x16x32_bf16 v[102:105], v[138:141], v[170:173], v[102:105]
	v_mfma_f32_16x16x32_bf16 v[98:101], v[146:149], v[170:173], v[98:101]
	v_mfma_f32_16x16x32_bf16 v[86:89], v[138:141], v[178:181], v[86:89]
	v_mfma_f32_16x16x32_bf16 v[82:85], v[146:149], v[178:181], v[82:85]
	v_mfma_f32_16x16x32_bf16 v[70:73], v[138:141], v[186:189], v[70:73]
	v_mfma_f32_16x16x32_bf16 v[66:69], v[146:149], v[186:189], v[66:69]
	v_mfma_f32_16x16x32_bf16 v[126:129], v[142:145], v[166:169], v[126:129]
	v_mfma_f32_16x16x32_bf16 v[122:125], v[158:161], v[166:169], v[122:125]
	v_mfma_f32_16x16x32_bf16 v[102:105], v[142:145], v[174:177], v[102:105]
	v_mfma_f32_16x16x32_bf16 v[98:101], v[158:161], v[174:177], v[98:101]
	v_mfma_f32_16x16x32_bf16 v[86:89], v[142:145], v[182:185], v[86:89]
	v_mfma_f32_16x16x32_bf16 v[82:85], v[158:161], v[182:185], v[82:85]
	v_mfma_f32_16x16x32_bf16 v[70:73], v[142:145], v[190:193], v[70:73]
	v_mfma_f32_16x16x32_bf16 v[66:69], v[158:161], v[190:193], v[66:69]
	s_setprio 0
	s_barrier
	s_add_i32 s54, s46, s0
	v_lshl_add_u64 v[206:207], s[38:39], 0, v[196:197]
	s_mov_b32 m0, s54
	ds_read_b128 v[162:165], v248 offset:16384
	ds_read_b128 v[166:169], v248 offset:17408
	ds_read_b128 v[170:173], v248 offset:18432
	ds_read_b128 v[174:177], v248 offset:19456
	ds_read_b128 v[178:181], v248 offset:20480
	ds_read_b128 v[182:185], v248 offset:21504
	ds_read_b128 v[186:189], v248 offset:22528
	ds_read_b128 v[190:193], v248 offset:23552
	global_load_lds_dwordx4 v[206:207], off
	s_add_i32 m0, s54, 0x2000
	s_add_u32 s54, s38, 0x40000
	v_lshl_add_u64 v[208:209], s[38:39], 0, v[200:201]
	s_addc_u32 s55, s39, 0
	s_add_i32 s56, s47, s0
	global_load_lds_dwordx4 v[208:209], off
	v_lshl_add_u64 v[210:211], s[54:55], 0, v[196:197]
	s_mov_b32 m0, s56
	v_lshl_add_u64 v[212:213], s[40:41], 0, v[198:199]
	global_load_lds_dwordx4 v[210:211], off
	v_lshl_add_u64 v[210:211], s[54:55], 0, v[200:201]
	s_add_i32 m0, s56, 0x2000
	s_nop 0
	global_load_lds_dwordx4 v[210:211], off
	v_lshl_add_u64 v[210:211], s[40:41], 0, v[194:195]
	s_waitcnt vmcnt(4)
	s_waitcnt lgkmcnt(0)
	s_barrier
; #define PG8_STAGE(bufoff, gbase, voff) do { _Pragma("unroll") for (int _i = 0; _i < 2; ++_i) \
;         __builtin_amdgcn_global_load_lds((const unsigned*)((const char*)(gbase) + (voff)[_i]), (PG8_LAS unsigned*)(lds + (bufoff) + ldsw + _i * 8192), 16, 0, 0); } while (0)
; #define PG8_LDA(dst, b, h) do { _Pragma("unroll") for (int m = 0; m < 4; ++m) _Pragma("unroll") for (int k = 0; k < 2; ++k) dst[m][k] = *(const PG8_LAS bf16x8*)(lds + PG8_SA(b, h) + aoff + m * 2048 + k * 1024); } while (0)
; #define PG8_LDB(dst, b, h) do { _Pragma("unroll") for (int n = 0; n < 2; ++n) _Pragma("unroll") for (int k = 0; k < 2; ++k) dst[n][k] = *(const PG8_LAS bf16x8*)(lds + PG8_SB(b, h) + boff + n * 2048 + k * 1024); } while (0)
; #define PG8_MMA(ai, bj, At, Bt) do { __builtin_amdgcn_s_setprio(1); _Pragma("unroll") for (int m = 0; m < 4; ++m) _Pragma("unroll") for (int n = 0; n < 2; ++n) _Pragma("unroll") for (int k = 0; k < 2; ++k) \
;         acc[ai][bj][m][n] = __builtin_amdgcn_mfma_f32_16x16x32_bf16(Bt[n][k], At[m][k], acc[ai][bj][m][n], 0, 0, 0); __builtin_amdgcn_s_setprio(0); } while (0)
; template <class Epi, class Sched, bool ALIGN_EPI = false, bool SP2 = false, bool HALFM = false>
; __device__ __forceinline__ void gemm_phase(PG8_LAS unsigned char* lds, const Gemm g, const Sched& S, const Epi& E) {
;     ...
;             PG8_LDB(B0, 0, 0); PG8_LDB(B1, 0, 1); PG8_SCHED; PG8_LDA(At, 0, 0); PG8_STAGE(PG8_SA(1, 1), a1 + hstep, voffA);
;             PG8_WAIT_V(8); PG8_WAIT_L(0); PG8_BAR; PG8_MMA(0, 0, At, B0); PG8_MMA(0, 1, At, B1); PG8_BAR; PG8_SCHED;
;             PG8_LDA(At, 0, 1); PG8_STAGE(PG8_SB(0, 0), b2, voffB); PG8_STAGE(PG8_SB(0, 1), b2 + hstep, voffB); PG8_STAGE(PG8_SA(0, 0), a2, voffA);
;             PG8_WAIT_V(8); PG8_WAIT_L(0); PG8_BAR; if constexpr (!HALFM) { PG8_MMA(1, 0, At, B0); PG8_MMA(1, 1, At, B1); } PG8_BAR; PG8_SCHED;
;             PG8_LDB(B0, 1, 0); PG8_LDB(B1, 1, 1); PG8_SCHED; PG8_LDA(At, 1, 0); PG8_STAGE(PG8_SA(0, 1), a2 + hstep, voffA);
;             PG8_WAIT_V(8); PG8_WAIT_L(0); PG8_BAR; PG8_MMA(0, 0, At, B0); PG8_MMA(0, 1, At, B1); PG8_BAR; PG8_SCHED;
;             PG8_LDA(At, 1, 1); PG8_STAGE(PG8_SB(1, 0), b3, voffB); PG8_STAGE(PG8_SB(1, 1), b3 + hstep, voffB); PG8_STAGE(PG8_SA(1, 0), a3, voffA);
;             PG8_WAIT_V(8); PG8_WAIT_L(0); PG8_BAR; if constexpr (!HALFM) { PG8_MMA(1, 0, At, B0); PG8_MMA(1, 1, At, B1); } PG8_BAR; PG8_SCHED;
	s_setprio 1
	v_mfma_f32_16x16x32_bf16 v[62:65], v[114:117], v[162:165], v[62:65]
	v_mfma_f32_16x16x32_bf16 v[58:61], v[130:133], v[162:165], v[58:61]
	v_mfma_f32_16x16x32_bf16 v[46:49], v[114:117], v[170:173], v[46:49]
	v_mfma_f32_16x16x32_bf16 v[42:45], v[130:133], v[170:173], v[42:45]
	v_mfma_f32_16x16x32_bf16 v[30:33], v[114:117], v[178:181], v[30:33]
	v_mfma_f32_16x16x32_bf16 v[26:29], v[130:133], v[178:181], v[26:29]
	v_mfma_f32_16x16x32_bf16 v[14:17], v[114:117], v[186:189], v[14:17]
	v_mfma_f32_16x16x32_bf16 v[10:13], v[130:133], v[186:189], v[10:13]
	v_mfma_f32_16x16x32_bf16 v[62:65], v[118:121], v[166:169], v[62:65]
	v_mfma_f32_16x16x32_bf16 v[58:61], v[134:137], v[166:169], v[58:61]
	v_mfma_f32_16x16x32_bf16 v[46:49], v[118:121], v[174:177], v[46:49]
	v_mfma_f32_16x16x32_bf16 v[42:45], v[134:137], v[174:177], v[42:45]
	v_mfma_f32_16x16x32_bf16 v[30:33], v[118:121], v[182:185], v[30:33]
	v_mfma_f32_16x16x32_bf16 v[26:29], v[134:137], v[182:185], v[26:29]
	v_mfma_f32_16x16x32_bf16 v[14:17], v[118:121], v[190:193], v[14:17]
	v_mfma_f32_16x16x32_bf16 v[10:13], v[134:137], v[190:193], v[10:13]
	s_setprio 0
	s_setprio 1
	v_mfma_f32_16x16x32_bf16 v[54:57], v[138:141], v[162:165], v[54:57]
	v_mfma_f32_16x16x32_bf16 v[50:53], v[146:149], v[162:165], v[50:53]
	v_mfma_f32_16x16x32_bf16 v[38:41], v[138:141], v[170:173], v[38:41]
	v_mfma_f32_16x16x32_bf16 v[34:37], v[146:149], v[170:173], v[34:37]
	v_mfma_f32_16x16x32_bf16 v[22:25], v[138:141], v[178:181], v[22:25]
	v_mfma_f32_16x16x32_bf16 v[18:21], v[146:149], v[178:181], v[18:21]
	v_mfma_f32_16x16x32_bf16 v[6:9], v[138:141], v[186:189], v[6:9]
	v_mfma_f32_16x16x32_bf16 v[2:5], v[146:149], v[186:189], v[2:5]
	v_mfma_f32_16x16x32_bf16 v[54:57], v[142:145], v[166:169], v[54:57]
	v_mfma_f32_16x16x32_bf16 v[50:53], v[158:161], v[166:169], v[50:53]
	v_mfma_f32_16x16x32_bf16 v[38:41], v[142:145], v[174:177], v[38:41]
	v_mfma_f32_16x16x32_bf16 v[34:37], v[158:161], v[174:177], v[34:37]
	v_mfma_f32_16x16x32_bf16 v[22:25], v[142:145], v[182:185], v[22:25]
	v_mfma_f32_16x16x32_bf16 v[18:21], v[158:161], v[182:185], v[18:21]
	v_mfma_f32_16x16x32_bf16 v[6:9], v[142:145], v[190:193], v[6:9]
	v_mfma_f32_16x16x32_bf16 v[2:5], v[158:161], v[190:193], v[2:5]
	s_setprio 0
	s_barrier
	s_add_i32 s54, 0, 0x18000
	s_add_i32 s55, 0, 0x1c000
	v_add_u32_e32 v134, s54, v244
	v_add_u32_e32 v158, s55, v244
	ds_read_b128 v[114:117], v134
	ds_read_b128 v[118:121], v134 offset:1024
	ds_read_b128 v[130:133], v134 offset:2048
	ds_read_b128 v[134:137], v134 offset:3072
	ds_read_b128 v[138:141], v158
	ds_read_b128 v[142:145], v158 offset:1024
	ds_read_b128 v[146:149], v158 offset:2048
	ds_read_b128 v[158:161], v158 offset:3072
	s_add_u32 s40, s40, 0x40000
	s_addc_u32 s41, s41, 0
	s_mov_b32 m0, s3
	v_lshl_add_u64 v[214:215], s[40:41], 0, v[194:195]
	ds_read_b128 v[162:165], v248 offset:32768
	ds_read_b128 v[166:169], v248 offset:33792
	ds_read_b128 v[170:173], v248 offset:34816
	ds_read_b128 v[174:177], v248 offset:35840
	ds_read_b128 v[178:181], v248 offset:36864
	ds_read_b128 v[182:185], v248 offset:37888
	ds_read_b128 v[186:189], v248 offset:38912
	ds_read_b128 v[190:193], v248 offset:39936
	global_load_lds_dwordx4 v[214:215], off
	v_lshl_add_u64 v[214:215], s[40:41], 0, v[198:199]
	s_mov_b32 m0, s35
	s_nop 0
	global_load_lds_dwordx4 v[214:215], off
	s_mov_b32 m0, s1
	s_nop 0
	global_load_lds_dwordx4 v[210:211], off
	s_mov_b32 m0, s2
	s_nop 0
	global_load_lds_dwordx4 v[212:213], off
	s_waitcnt vmcnt(10)
	s_waitcnt lgkmcnt(0)
	s_barrier
; #define PG8_STAGE(bufoff, gbase, voff) do { _Pragma("unroll") for (int _i = 0; _i < 2; ++_i) \
;         __builtin_amdgcn_global_load_lds((const unsigned*)((const char*)(gbase) + (voff)[_i]), (PG8_LAS unsigned*)(lds + (bufoff) + ldsw + _i * 8192), 16, 0, 0); } while (0)
; #define PG8_LDA(dst, b, h) do { _Pragma("unroll") for (int m = 0; m < 4; ++m) _Pragma("unroll") for (int k = 0; k < 2; ++k) dst[m][k] = *(const PG8_LAS bf16x8*)(lds + PG8_SA(b, h) + aoff + m * 2048 + k * 1024); } while (0)
; #define PG8_LDB(dst, b, h) do { _Pragma("unroll") for (int n = 0; n < 2; ++n) _Pragma("unroll") for (int k = 0; k < 2; ++k) dst[n][k] = *(const PG8_LAS bf16x8*)(lds + PG8_SB(b, h) + boff + n * 2048 + k * 1024); } while (0)
; #define PG8_WAIT_V(n) asm volatile("s_waitcnt vmcnt(" #n ")" ::: "memory")
; #define PG8_WAIT_L(n) asm volatile("s_waitcnt lgkmcnt(" #n ")" ::: "memory")
; #define PG8_BAR __builtin_amdgcn_s_barrier()
; #define PG8_SCHED __builtin_amdgcn_sched_barrier(0)
; template <class Epi, class Sched, bool ALIGN_EPI = false, bool SP2 = false, bool HALFM = false>
; __device__ __forceinline__ void gemm_phase(PG8_LAS unsigned char* lds, const Gemm g, const Sched& S, const Epi& E) {
;     ...
;         for (int t = 0; t < nt; t += 2) {
;     ...
;             PG8_LDB(B0, 0, 0); PG8_LDB(B1, 0, 1); PG8_SCHED; PG8_LDA(At, 0, 0); PG8_STAGE(PG8_SA(1, 1), a1 + hstep, voffA);
;             PG8_WAIT_V(8); PG8_WAIT_L(0); PG8_BAR; PG8_MMA(0, 0, At, B0); PG8_MMA(0, 1, At, B1); PG8_BAR; PG8_SCHED;
;             PG8_LDA(At, 0, 1); PG8_STAGE(PG8_SB(0, 0), b2, voffB); PG8_STAGE(PG8_SB(0, 1), b2 + hstep, voffB); PG8_STAGE(PG8_SA(0, 0), a2, voffA);
;             PG8_WAIT_V(8); PG8_WAIT_L(0); PG8_BAR; if constexpr (!HALFM) { PG8_MMA(1, 0, At, B0); PG8_MMA(1, 1, At, B1); } PG8_BAR; PG8_SCHED;
;             PG8_LDB(B0, 1, 0); PG8_LDB(B1, 1, 1); PG8_SCHED; PG8_LDA(At, 1, 0); PG8_STAGE(PG8_SA(0, 1), a2 + hstep, voffA);
;             PG8_WAIT_V(8); PG8_WAIT_L(0); PG8_BAR; PG8_MMA(0, 0, At, B0); PG8_MMA(0, 1, At, B1); PG8_BAR; PG8_SCHED;
;             PG8_LDA(At, 1, 1); PG8_STAGE(PG8_SB(1, 0), b3, voffB); PG8_STAGE(PG8_SB(1, 1), b3 + hstep, voffB); PG8_STAGE(PG8_SA(1, 0), a3, voffA);
;             PG8_WAIT_V(8); PG8_WAIT_L(0); PG8_BAR; if constexpr (!HALFM) { PG8_MMA(1, 0, At, B0); PG8_MMA(1, 1, At, B1); } PG8_BAR; PG8_SCHED;
	s_setprio 1
	v_mfma_f32_16x16x32_bf16 v[154:157], v[114:117], v[162:165], v[154:157]
	v_mfma_f32_16x16x32_bf16 v[150:153], v[130:133], v[162:165], v[150:153]
	v_mfma_f32_16x16x32_bf16 v[110:113], v[114:117], v[170:173], v[110:113]
	v_mfma_f32_16x16x32_bf16 v[106:109], v[130:133], v[170:173], v[106:109]
	v_mfma_f32_16x16x32_bf16 v[94:97], v[114:117], v[178:181], v[94:97]
	v_mfma_f32_16x16x32_bf16 v[90:93], v[130:133], v[178:181], v[90:93]
	v_mfma_f32_16x16x32_bf16 v[78:81], v[114:117], v[186:189], v[78:81]
	v_mfma_f32_16x16x32_bf16 v[74:77], v[130:133], v[186:189], v[74:77]
	v_mfma_f32_16x16x32_bf16 v[154:157], v[118:121], v[166:169], v[154:157]
	v_mfma_f32_16x16x32_bf16 v[150:153], v[134:137], v[166:169], v[150:153]
	v_mfma_f32_16x16x32_bf16 v[110:113], v[118:121], v[174:177], v[110:113]
	v_mfma_f32_16x16x32_bf16 v[106:109], v[134:137], v[174:177], v[106:109]
	v_mfma_f32_16x16x32_bf16 v[94:97], v[118:121], v[182:185], v[94:97]
	v_mfma_f32_16x16x32_bf16 v[90:93], v[134:137], v[182:185], v[90:93]
	v_mfma_f32_16x16x32_bf16 v[78:81], v[118:121], v[190:193], v[78:81]
	v_mfma_f32_16x16x32_bf16 v[74:77], v[134:137], v[190:193], v[74:77]
	s_setprio 0
	s_setprio 1
	v_mfma_f32_16x16x32_bf16 v[126:129], v[138:141], v[162:165], v[126:129]
	v_mfma_f32_16x16x32_bf16 v[122:125], v[146:149], v[162:165], v[122:125]
	v_mfma_f32_16x16x32_bf16 v[102:105], v[138:141], v[170:173], v[102:105]
	v_mfma_f32_16x16x32_bf16 v[98:101], v[146:149], v[170:173], v[98:101]
	v_mfma_f32_16x16x32_bf16 v[86:89], v[138:141], v[178:181], v[86:89]
	v_mfma_f32_16x16x32_bf16 v[82:85], v[146:149], v[178:181], v[82:85]
	v_mfma_f32_16x16x32_bf16 v[70:73], v[138:141], v[186:189], v[70:73]
	v_mfma_f32_16x16x32_bf16 v[66:69], v[146:149], v[186:189], v[66:69]
	v_mfma_f32_16x16x32_bf16 v[126:129], v[142:145], v[166:169], v[126:129]
	v_mfma_f32_16x16x32_bf16 v[122:125], v[158:161], v[166:169], v[122:125]
	v_mfma_f32_16x16x32_bf16 v[102:105], v[142:145], v[174:177], v[102:105]
	v_mfma_f32_16x16x32_bf16 v[98:101], v[158:161], v[174:177], v[98:101]
	v_mfma_f32_16x16x32_bf16 v[86:89], v[142:145], v[182:185], v[86:89]
	v_mfma_f32_16x16x32_bf16 v[82:85], v[158:161], v[182:185], v[82:85]
	v_mfma_f32_16x16x32_bf16 v[70:73], v[142:145], v[190:193], v[70:73]
	v_mfma_f32_16x16x32_bf16 v[66:69], v[158:161], v[190:193], v[66:69]
	s_setprio 0
	s_barrier
	s_add_i32 s40, s54, s0
	v_lshl_add_u64 v[206:207], v[206:207], 0, s[10:11]
	s_mov_b32 m0, s40
	ds_read_b128 v[162:165], v248 offset:49152
	ds_read_b128 v[166:169], v248 offset:50176
	ds_read_b128 v[170:173], v248 offset:51200
	ds_read_b128 v[174:177], v248 offset:52224
	ds_read_b128 v[178:181], v248 offset:53248
	ds_read_b128 v[182:185], v248 offset:54272
	ds_read_b128 v[186:189], v248 offset:55296
	ds_read_b128 v[190:193], v248 offset:56320
	global_load_lds_dwordx4 v[206:207], off
	s_add_i32 m0, s40, 0x2000
	s_add_u32 s38, s38, 0x40080
	v_lshl_add_u64 v[206:207], v[208:209], 0, s[10:11]
	s_addc_u32 s39, s39, 0
	s_add_i32 s40, s55, s0
	global_load_lds_dwordx4 v[206:207], off
	v_lshl_add_u64 v[206:207], s[38:39], 0, v[196:197]
	s_mov_b32 m0, s40
	s_nop 0
	global_load_lds_dwordx4 v[206:207], off
	v_lshl_add_u64 v[206:207], s[38:39], 0, v[200:201]
	s_add_i32 m0, s40, 0x2000
	s_nop 0
	global_load_lds_dwordx4 v[206:207], off
	s_waitcnt vmcnt(4)
	s_waitcnt lgkmcnt(0)
	s_barrier
	s_setprio 1
	v_mfma_f32_16x16x32_bf16 v[62:65], v[114:117], v[162:165], v[62:65]
	v_mfma_f32_16x16x32_bf16 v[58:61], v[130:133], v[162:165], v[58:61]
	v_mfma_f32_16x16x32_bf16 v[46:49], v[114:117], v[170:173], v[46:49]
	v_mfma_f32_16x16x32_bf16 v[42:45], v[130:133], v[170:173], v[42:45]
	v_mfma_f32_16x16x32_bf16 v[30:33], v[114:117], v[178:181], v[30:33]
	v_mfma_f32_16x16x32_bf16 v[26:29], v[130:133], v[178:181], v[26:29]
	v_mfma_f32_16x16x32_bf16 v[14:17], v[114:117], v[186:189], v[14:17]
	v_mfma_f32_16x16x32_bf16 v[10:13], v[130:133], v[186:189], v[10:13]
	v_mfma_f32_16x16x32_bf16 v[62:65], v[118:121], v[166:169], v[62:65]
	v_mfma_f32_16x16x32_bf16 v[58:61], v[134:137], v[166:169], v[58:61]
	v_mfma_f32_16x16x32_bf16 v[46:49], v[118:121], v[174:177], v[46:49]
	v_mfma_f32_16x16x32_bf16 v[42:45], v[134:137], v[174:177], v[42:45]
	v_mfma_f32_16x16x32_bf16 v[30:33], v[118:121], v[182:185], v[30:33]
	v_mfma_f32_16x16x32_bf16 v[26:29], v[134:137], v[182:185], v[26:29]
	v_mfma_f32_16x16x32_bf16 v[14:17], v[118:121], v[190:193], v[14:17]
	v_mfma_f32_16x16x32_bf16 v[10:13], v[134:137], v[190:193], v[10:13]
	s_setprio 0
	s_setprio 1
	v_mfma_f32_16x16x32_bf16 v[54:57], v[138:141], v[162:165], v[54:57]
	v_mfma_f32_16x16x32_bf16 v[50:53], v[146:149], v[162:165], v[50:53]
	v_mfma_f32_16x16x32_bf16 v[38:41], v[138:141], v[170:173], v[38:41]
	v_mfma_f32_16x16x32_bf16 v[34:37], v[146:149], v[170:173], v[34:37]
	v_mfma_f32_16x16x32_bf16 v[22:25], v[138:141], v[178:181], v[22:25]
	v_mfma_f32_16x16x32_bf16 v[18:21], v[146:149], v[178:181], v[18:21]
	v_mfma_f32_16x16x32_bf16 v[6:9], v[138:141], v[186:189], v[6:9]
	v_mfma_f32_16x16x32_bf16 v[2:5], v[146:149], v[186:189], v[2:5]
	v_mfma_f32_16x16x32_bf16 v[54:57], v[142:145], v[166:169], v[54:57]
	v_mfma_f32_16x16x32_bf16 v[50:53], v[158:161], v[166:169], v[50:53]
	v_mfma_f32_16x16x32_bf16 v[38:41], v[142:145], v[174:177], v[38:41]
	v_mfma_f32_16x16x32_bf16 v[34:37], v[158:161], v[174:177], v[34:37]
	v_mfma_f32_16x16x32_bf16 v[22:25], v[142:145], v[182:185], v[22:25]
	v_mfma_f32_16x16x32_bf16 v[18:21], v[158:161], v[182:185], v[18:21]
	v_mfma_f32_16x16x32_bf16 v[6:9], v[142:145], v[190:193], v[6:9]
	v_mfma_f32_16x16x32_bf16 v[2:5], v[158:161], v[190:193], v[2:5]
	s_setprio 0
	s_barrier
	s_add_i32 s53, s53, 2
	s_add_u32 s36, s36, 0x100
	s_addc_u32 s37, s37, 0
	s_add_u32 s51, s51, 0x100
	s_addc_u32 s52, s52, 0
	s_cmp_gt_u32 s53, 13
	s_cbranch_scc0 .LBB0_1692
	s_and_b64 vcc, exec, s[14:15]
	s_cbranch_vccz .LBB0_1695
	s_barrier

; #define PG8_STAGE(bufoff, gbase, voff) do { _Pragma("unroll") for (int _i = 0; _i < 2; ++_i) \
;         __builtin_amdgcn_global_load_lds((const unsigned*)((const char*)(gbase) + (voff)[_i]), (PG8_LAS unsigned*)(lds + (bufoff) + ldsw + _i * 8192), 16, 0, 0); } while (0)
; #define PG8_LDA(dst, b, h) do { _Pragma("unroll") for (int m = 0; m < 4; ++m) _Pragma("unroll") for (int k = 0; k < 2; ++k) dst[m][k] = *(const PG8_LAS bf16x8*)(lds + PG8_SA(b, h) + aoff + m * 2048 + k * 1024); } while (0)
; #define PG8_LDB(dst, b, h) do { _Pragma("unroll") for (int n = 0; n < 2; ++n) _Pragma("unroll") for (int k = 0; k < 2; ++k) dst[n][k] = *(const PG8_LAS bf16x8*)(lds + PG8_SB(b, h) + boff + n * 2048 + k * 1024); } while (0)
; #define PG8_MMA(ai, bj, At, Bt) do { __builtin_amdgcn_s_setprio(1); _Pragma("unroll") for (int m = 0; m < 4; ++m) _Pragma("unroll") for (int n = 0; n < 2; ++n) _Pragma("unroll") for (int k = 0; k < 2; ++k) \
;         acc[ai][bj][m][n] = __builtin_amdgcn_mfma_f32_16x16x32_bf16(Bt[n][k], At[m][k], acc[ai][bj][m][n], 0, 0, 0); __builtin_amdgcn_s_setprio(0); } while (0)
; template <class Epi, class Sched, bool ALIGN_EPI = false, bool SP2 = false, bool HALFM = false>
; __device__ __forceinline__ void gemm_phase(PG8_LAS unsigned char* lds, const Gemm g, const Sched& S, const Epi& E) {
;     ...
;             PG8_LDB(B0, 0, 0); PG8_LDB(B1, 0, 1); PG8_SCHED; PG8_LDA(At, 0, 0); PG8_STAGE(PG8_SA(1, 1), a1 + hstep, voffA);
;             PG8_WAIT_V(8); PG8_WAIT_L(0); PG8_BAR; PG8_MMA(0, 0, At, B0); PG8_MMA(0, 1, At, B1); PG8_BAR; PG8_SCHED;
;             PG8_LDA(At, 0, 1); PG8_STAGE(PG8_SB(0, 0), b2, voffB); PG8_STAGE(PG8_SB(0, 1), b2 + hstep, voffB); PG8_STAGE(PG8_SA(0, 0), a2, voffA);
;             PG8_WAIT_V(8); PG8_WAIT_L(0); PG8_BAR; if constexpr (!HALFM) { PG8_MMA(1, 0, At, B0); PG8_MMA(1, 1, At, B1); } PG8_BAR; PG8_SCHED;
;             PG8_LDB(B0, 1, 0); PG8_LDB(B1, 1, 1); PG8_SCHED; PG8_LDA(At, 1, 0); PG8_STAGE(PG8_SA(0, 1), a2 + hstep, voffA);
;             PG8_WAIT_V(8); PG8_WAIT_L(0); PG8_BAR; PG8_MMA(0, 0, At, B0); PG8_MMA(0, 1, At, B1); PG8_BAR; PG8_SCHED;
;             PG8_LDA(At, 1, 1); PG8_STAGE(PG8_SB(1, 0), b3, voffB); PG8_STAGE(PG8_SB(1, 1), b3 + hstep, voffB); PG8_STAGE(PG8_SA(1, 0), a3, voffA);
;             PG8_WAIT_V(8); PG8_WAIT_L(0); PG8_BAR; if constexpr (!HALFM) { PG8_MMA(1, 0, At, B0); PG8_MMA(1, 1, At, B1); } PG8_BAR; PG8_SCHED;
.LBB0_1805:
	ds_read_b128 v[154:157], v150
	ds_read_b128 v[158:161], v150 offset:1024
	ds_read_b128 v[162:165], v150 offset:2048
	ds_read_b128 v[166:169], v150 offset:3072
	ds_read_b128 v[170:173], v151
	ds_read_b128 v[174:177], v151 offset:1024
	ds_read_b128 v[178:181], v151 offset:2048
	ds_read_b128 v[182:185], v151 offset:3072
	s_add_u32 s38, s36, 0xfffc0080
	s_addc_u32 s39, s37, -1
	s_cmp_eq_u32 s57, 12
	s_cselect_b32 s41, s27, s39
	s_cselect_b32 s40, s53, s38
	s_cselect_b32 s39, s25, s56
	s_cselect_b32 s38, s54, s55
	v_lshl_add_u64 v[146:147], s[36:37], 0, v[138:139]
	s_add_i32 m0, s2, 0xc000
	ds_read_b128 v[186:189], v152
	ds_read_b128 v[190:193], v152 offset:1024
	ds_read_b128 v[194:197], v152 offset:2048
	ds_read_b128 v[198:201], v152 offset:3072
	ds_read_b128 v[202:205], v152 offset:4096
	ds_read_b128 v[206:209], v152 offset:5120
	ds_read_b128 v[210:213], v152 offset:6144
	ds_read_b128 v[214:217], v152 offset:7168
	global_load_lds_dwordx4 v[146:147], off
	v_lshl_add_u64 v[146:147], s[36:37], 0, v[140:141]
	s_add_i32 m0, s2, 0xe000
	s_nop 0
	global_load_lds_dwordx4 v[146:147], off
	s_mov_b32 m0, s44
	v_lshl_add_u64 v[146:147], v[220:221], 0, s[14:15]
	global_load_lds_dwordx4 v[146:147], off
	s_mov_b32 m0, s45
	v_lshl_add_u64 v[146:147], v[222:223], 0, s[14:15]
	global_load_lds_dwordx4 v[146:147], off
	s_waitcnt vmcnt(10)
	s_waitcnt lgkmcnt(0)
	s_barrier
	s_setprio 1
	v_mfma_f32_16x16x32_bf16 v[118:121], v[154:157], v[186:189], v[118:121]
	v_mfma_f32_16x16x32_bf16 v[114:117], v[162:165], v[186:189], v[114:117]
	v_mfma_f32_16x16x32_bf16 v[110:113], v[154:157], v[194:197], v[110:113]
	v_mfma_f32_16x16x32_bf16 v[106:109], v[162:165], v[194:197], v[106:109]
	v_mfma_f32_16x16x32_bf16 v[94:97], v[154:157], v[202:205], v[94:97]
	v_mfma_f32_16x16x32_bf16 v[90:93], v[162:165], v[202:205], v[90:93]
	v_mfma_f32_16x16x32_bf16 v[78:81], v[154:157], v[210:213], v[78:81]
	v_mfma_f32_16x16x32_bf16 v[74:77], v[162:165], v[210:213], v[74:77]
	v_mfma_f32_16x16x32_bf16 v[118:121], v[158:161], v[190:193], v[118:121]
	v_mfma_f32_16x16x32_bf16 v[114:117], v[166:169], v[190:193], v[114:117]
	v_mfma_f32_16x16x32_bf16 v[110:113], v[158:161], v[198:201], v[110:113]
	v_mfma_f32_16x16x32_bf16 v[106:109], v[166:169], v[198:201], v[106:109]
	v_mfma_f32_16x16x32_bf16 v[94:97], v[158:161], v[206:209], v[94:97]
	v_mfma_f32_16x16x32_bf16 v[90:93], v[166:169], v[206:209], v[90:93]
	v_mfma_f32_16x16x32_bf16 v[78:81], v[158:161], v[214:217], v[78:81]
	v_mfma_f32_16x16x32_bf16 v[74:77], v[166:169], v[214:217], v[74:77]
	s_setprio 0
	s_setprio 1
	v_mfma_f32_16x16x32_bf16 v[126:129], v[170:173], v[186:189], v[126:129]
	v_mfma_f32_16x16x32_bf16 v[122:125], v[178:181], v[186:189], v[122:125]
	v_mfma_f32_16x16x32_bf16 v[102:105], v[170:173], v[194:197], v[102:105]
	v_mfma_f32_16x16x32_bf16 v[98:101], v[178:181], v[194:197], v[98:101]
	v_mfma_f32_16x16x32_bf16 v[86:89], v[170:173], v[202:205], v[86:89]
	v_mfma_f32_16x16x32_bf16 v[82:85], v[178:181], v[202:205], v[82:85]
	v_mfma_f32_16x16x32_bf16 v[70:73], v[170:173], v[210:213], v[70:73]
	v_mfma_f32_16x16x32_bf16 v[66:69], v[178:181], v[210:213], v[66:69]
	v_mfma_f32_16x16x32_bf16 v[126:129], v[174:177], v[190:193], v[126:129]
	v_mfma_f32_16x16x32_bf16 v[122:125], v[182:185], v[190:193], v[122:125]
	v_mfma_f32_16x16x32_bf16 v[102:105], v[174:177], v[198:201], v[102:105]
	v_mfma_f32_16x16x32_bf16 v[98:101], v[182:185], v[198:201], v[98:101]
	v_mfma_f32_16x16x32_bf16 v[86:89], v[174:177], v[206:209], v[86:89]
	v_mfma_f32_16x16x32_bf16 v[82:85], v[182:185], v[206:209], v[82:85]
	v_mfma_f32_16x16x32_bf16 v[70:73], v[174:177], v[214:217], v[70:73]
	v_mfma_f32_16x16x32_bf16 v[66:69], v[182:185], v[214:217], v[66:69]
	s_setprio 0
	s_barrier
	s_add_i32 s58, s49, s0
	v_lshl_add_u64 v[146:147], s[38:39], 0, v[134:135]
	s_mov_b32 m0, s58
	ds_read_b128 v[186:189], v152 offset:16384
	ds_read_b128 v[190:193], v152 offset:17408
	ds_read_b128 v[194:197], v152 offset:18432
	ds_read_b128 v[198:201], v152 offset:19456
	ds_read_b128 v[202:205], v152 offset:20480
	ds_read_b128 v[206:209], v152 offset:21504
	ds_read_b128 v[210:213], v152 offset:22528
	ds_read_b128 v[214:217], v152 offset:23552
	global_load_lds_dwordx4 v[146:147], off
	s_add_i32 m0, s58, 0x2000
	s_add_u32 s58, s38, 0x40000
	v_lshl_add_u64 v[218:219], s[38:39], 0, v[130:131]
	s_addc_u32 s59, s39, 0
	s_add_i32 s60, s50, s0
	global_load_lds_dwordx4 v[218:219], off
	v_lshl_add_u64 v[220:221], s[58:59], 0, v[134:135]
	s_mov_b32 m0, s60
	v_lshl_add_u64 v[222:223], s[40:41], 0, v[132:133]
	global_load_lds_dwordx4 v[220:221], off
	v_lshl_add_u64 v[220:221], s[58:59], 0, v[130:131]
	s_add_i32 m0, s60, 0x2000
	s_nop 0
	global_load_lds_dwordx4 v[220:221], off
	v_lshl_add_u64 v[220:221], s[40:41], 0, v[136:137]
	s_waitcnt vmcnt(4)
	s_waitcnt lgkmcnt(0)
	s_barrier
; #define PG8_STAGE(bufoff, gbase, voff) do { _Pragma("unroll") for (int _i = 0; _i < 2; ++_i) \
;         __builtin_amdgcn_global_load_lds((const unsigned*)((const char*)(gbase) + (voff)[_i]), (PG8_LAS unsigned*)(lds + (bufoff) + ldsw + _i * 8192), 16, 0, 0); } while (0)
; #define PG8_LDA(dst, b, h) do { _Pragma("unroll") for (int m = 0; m < 4; ++m) _Pragma("unroll") for (int k = 0; k < 2; ++k) dst[m][k] = *(const PG8_LAS bf16x8*)(lds + PG8_SA(b, h) + aoff + m * 2048 + k * 1024); } while (0)
; #define PG8_LDB(dst, b, h) do { _Pragma("unroll") for (int n = 0; n < 2; ++n) _Pragma("unroll") for (int k = 0; k < 2; ++k) dst[n][k] = *(const PG8_LAS bf16x8*)(lds + PG8_SB(b, h) + boff + n * 2048 + k * 1024); } while (0)
; #define PG8_MMA(ai, bj, At, Bt) do { __builtin_amdgcn_s_setprio(1); _Pragma("unroll") for (int m = 0; m < 4; ++m) _Pragma("unroll") for (int n = 0; n < 2; ++n) _Pragma("unroll") for (int k = 0; k < 2; ++k) \
;         acc[ai][bj][m][n] = __builtin_amdgcn_mfma_f32_16x16x32_bf16(Bt[n][k], At[m][k], acc[ai][bj][m][n], 0, 0, 0); __builtin_amdgcn_s_setprio(0); } while (0)
; template <class Epi, class Sched, bool ALIGN_EPI = false, bool SP2 = false, bool HALFM = false>
; __device__ __forceinline__ void gemm_phase(PG8_LAS unsigned char* lds, const Gemm g, const Sched& S, const Epi& E) {
;     ...
;             PG8_LDB(B0, 0, 0); PG8_LDB(B1, 0, 1); PG8_SCHED; PG8_LDA(At, 0, 0); PG8_STAGE(PG8_SA(1, 1), a1 + hstep, voffA);
;             PG8_WAIT_V(8); PG8_WAIT_L(0); PG8_BAR; PG8_MMA(0, 0, At, B0); PG8_MMA(0, 1, At, B1); PG8_BAR; PG8_SCHED;
;             PG8_LDA(At, 0, 1); PG8_STAGE(PG8_SB(0, 0), b2, voffB); PG8_STAGE(PG8_SB(0, 1), b2 + hstep, voffB); PG8_STAGE(PG8_SA(0, 0), a2, voffA);
;             PG8_WAIT_V(8); PG8_WAIT_L(0); PG8_BAR; if constexpr (!HALFM) { PG8_MMA(1, 0, At, B0); PG8_MMA(1, 1, At, B1); } PG8_BAR; PG8_SCHED;
;             PG8_LDB(B0, 1, 0); PG8_LDB(B1, 1, 1); PG8_SCHED; PG8_LDA(At, 1, 0); PG8_STAGE(PG8_SA(0, 1), a2 + hstep, voffA);
;             PG8_WAIT_V(8); PG8_WAIT_L(0); PG8_BAR; PG8_MMA(0, 0, At, B0); PG8_MMA(0, 1, At, B1); PG8_BAR; PG8_SCHED;
;             PG8_LDA(At, 1, 1); PG8_STAGE(PG8_SB(1, 0), b3, voffB); PG8_STAGE(PG8_SB(1, 1), b3 + hstep, voffB); PG8_STAGE(PG8_SA(1, 0), a3, voffA);
;             PG8_WAIT_V(8); PG8_WAIT_L(0); PG8_BAR; if constexpr (!HALFM) { PG8_MMA(1, 0, At, B0); PG8_MMA(1, 1, At, B1); } PG8_BAR; PG8_SCHED;
	s_setprio 1
	v_mfma_f32_16x16x32_bf16 v[62:65], v[154:157], v[186:189], v[62:65]
	v_mfma_f32_16x16x32_bf16 v[58:61], v[162:165], v[186:189], v[58:61]
	v_mfma_f32_16x16x32_bf16 v[46:49], v[154:157], v[194:197], v[46:49]
	v_mfma_f32_16x16x32_bf16 v[42:45], v[162:165], v[194:197], v[42:45]
	v_mfma_f32_16x16x32_bf16 v[30:33], v[154:157], v[202:205], v[30:33]
	v_mfma_f32_16x16x32_bf16 v[26:29], v[162:165], v[202:205], v[26:29]
	v_mfma_f32_16x16x32_bf16 v[14:17], v[154:157], v[210:213], v[14:17]
	v_mfma_f32_16x16x32_bf16 v[10:13], v[162:165], v[210:213], v[10:13]
	v_mfma_f32_16x16x32_bf16 v[62:65], v[158:161], v[190:193], v[62:65]
	v_mfma_f32_16x16x32_bf16 v[58:61], v[166:169], v[190:193], v[58:61]
	v_mfma_f32_16x16x32_bf16 v[46:49], v[158:161], v[198:201], v[46:49]
	v_mfma_f32_16x16x32_bf16 v[42:45], v[166:169], v[198:201], v[42:45]
	v_mfma_f32_16x16x32_bf16 v[30:33], v[158:161], v[206:209], v[30:33]
	v_mfma_f32_16x16x32_bf16 v[26:29], v[166:169], v[206:209], v[26:29]
	v_mfma_f32_16x16x32_bf16 v[14:17], v[158:161], v[214:217], v[14:17]
	v_mfma_f32_16x16x32_bf16 v[10:13], v[166:169], v[214:217], v[10:13]
	s_setprio 0
	s_setprio 1
	v_mfma_f32_16x16x32_bf16 v[54:57], v[170:173], v[186:189], v[54:57]
	v_mfma_f32_16x16x32_bf16 v[50:53], v[178:181], v[186:189], v[50:53]
	v_mfma_f32_16x16x32_bf16 v[38:41], v[170:173], v[194:197], v[38:41]
	v_mfma_f32_16x16x32_bf16 v[34:37], v[178:181], v[194:197], v[34:37]
	v_mfma_f32_16x16x32_bf16 v[22:25], v[170:173], v[202:205], v[22:25]
	v_mfma_f32_16x16x32_bf16 v[18:21], v[178:181], v[202:205], v[18:21]
	v_mfma_f32_16x16x32_bf16 v[6:9], v[170:173], v[210:213], v[6:9]
	v_mfma_f32_16x16x32_bf16 v[2:5], v[178:181], v[210:213], v[2:5]
	v_mfma_f32_16x16x32_bf16 v[54:57], v[174:177], v[190:193], v[54:57]
	v_mfma_f32_16x16x32_bf16 v[50:53], v[182:185], v[190:193], v[50:53]
	v_mfma_f32_16x16x32_bf16 v[38:41], v[174:177], v[198:201], v[38:41]
	v_mfma_f32_16x16x32_bf16 v[34:37], v[182:185], v[198:201], v[34:37]
	v_mfma_f32_16x16x32_bf16 v[22:25], v[174:177], v[206:209], v[22:25]
	v_mfma_f32_16x16x32_bf16 v[18:21], v[182:185], v[206:209], v[18:21]
	v_mfma_f32_16x16x32_bf16 v[6:9], v[174:177], v[214:217], v[6:9]
	v_mfma_f32_16x16x32_bf16 v[2:5], v[182:185], v[214:217], v[2:5]
	s_setprio 0
	s_barrier
	s_add_i32 s58, 0, 0x18000
	s_add_i32 s59, 0, 0x1c000
	v_add_u32_e32 v166, s58, v148
	v_add_u32_e32 v182, s59, v148
	ds_read_b128 v[154:157], v166
	ds_read_b128 v[158:161], v166 offset:1024
	ds_read_b128 v[162:165], v166 offset:2048
	ds_read_b128 v[166:169], v166 offset:3072
	ds_read_b128 v[170:173], v182
	ds_read_b128 v[174:177], v182 offset:1024
	ds_read_b128 v[178:181], v182 offset:2048
	ds_read_b128 v[182:185], v182 offset:3072
	s_add_u32 s40, s40, 0x40000
	s_addc_u32 s41, s41, 0
	s_mov_b32 m0, s35
	v_lshl_add_u64 v[224:225], s[40:41], 0, v[136:137]
	ds_read_b128 v[186:189], v152 offset:32768
	ds_read_b128 v[190:193], v152 offset:33792
	ds_read_b128 v[194:197], v152 offset:34816
	ds_read_b128 v[198:201], v152 offset:35840
	ds_read_b128 v[202:205], v152 offset:36864
	ds_read_b128 v[206:209], v152 offset:37888
	ds_read_b128 v[210:213], v152 offset:38912
	ds_read_b128 v[214:217], v152 offset:39936
	global_load_lds_dwordx4 v[224:225], off
	v_lshl_add_u64 v[224:225], s[40:41], 0, v[132:133]
	s_mov_b32 m0, s42
	s_nop 0
	global_load_lds_dwordx4 v[224:225], off
	s_mov_b32 m0, s2
	s_nop 0
	global_load_lds_dwordx4 v[220:221], off
	s_mov_b32 m0, s3
	s_nop 0
	global_load_lds_dwordx4 v[222:223], off
	s_waitcnt vmcnt(10)
	s_waitcnt lgkmcnt(0)
	s_barrier
; #define PG8_STAGE(bufoff, gbase, voff) do { _Pragma("unroll") for (int _i = 0; _i < 2; ++_i) \
;         __builtin_amdgcn_global_load_lds((const unsigned*)((const char*)(gbase) + (voff)[_i]), (PG8_LAS unsigned*)(lds + (bufoff) + ldsw + _i * 8192), 16, 0, 0); } while (0)
; #define PG8_LDA(dst, b, h) do { _Pragma("unroll") for (int m = 0; m < 4; ++m) _Pragma("unroll") for (int k = 0; k < 2; ++k) dst[m][k] = *(const PG8_LAS bf16x8*)(lds + PG8_SA(b, h) + aoff + m * 2048 + k * 1024); } while (0)
; #define PG8_LDB(dst, b, h) do { _Pragma("unroll") for (int n = 0; n < 2; ++n) _Pragma("unroll") for (int k = 0; k < 2; ++k) dst[n][k] = *(const PG8_LAS bf16x8*)(lds + PG8_SB(b, h) + boff + n * 2048 + k * 1024); } while (0)
; #define PG8_WAIT_V(n) asm volatile("s_waitcnt vmcnt(" #n ")" ::: "memory")
; #define PG8_WAIT_L(n) asm volatile("s_waitcnt lgkmcnt(" #n ")" ::: "memory")
; #define PG8_BAR __builtin_amdgcn_s_barrier()
; #define PG8_SCHED __builtin_amdgcn_sched_barrier(0)
; template <class Epi, class Sched, bool ALIGN_EPI = false, bool SP2 = false, bool HALFM = false>
; __device__ __forceinline__ void gemm_phase(PG8_LAS unsigned char* lds, const Gemm g, const Sched& S, const Epi& E) {
;     ...
;         for (int t = 0; t < nt; t += 2) {
;     ...
;             PG8_LDB(B0, 0, 0); PG8_LDB(B1, 0, 1); PG8_SCHED; PG8_LDA(At, 0, 0); PG8_STAGE(PG8_SA(1, 1), a1 + hstep, voffA);
;             PG8_WAIT_V(8); PG8_WAIT_L(0); PG8_BAR; PG8_MMA(0, 0, At, B0); PG8_MMA(0, 1, At, B1); PG8_BAR; PG8_SCHED;
;             PG8_LDA(At, 0, 1); PG8_STAGE(PG8_SB(0, 0), b2, voffB); PG8_STAGE(PG8_SB(0, 1), b2 + hstep, voffB); PG8_STAGE(PG8_SA(0, 0), a2, voffA);
;             PG8_WAIT_V(8); PG8_WAIT_L(0); PG8_BAR; if constexpr (!HALFM) { PG8_MMA(1, 0, At, B0); PG8_MMA(1, 1, At, B1); } PG8_BAR; PG8_SCHED;
;             PG8_LDB(B0, 1, 0); PG8_LDB(B1, 1, 1); PG8_SCHED; PG8_LDA(At, 1, 0); PG8_STAGE(PG8_SA(0, 1), a2 + hstep, voffA);
;             PG8_WAIT_V(8); PG8_WAIT_L(0); PG8_BAR; PG8_MMA(0, 0, At, B0); PG8_MMA(0, 1, At, B1); PG8_BAR; PG8_SCHED;
;             PG8_LDA(At, 1, 1); PG8_STAGE(PG8_SB(1, 0), b3, voffB); PG8_STAGE(PG8_SB(1, 1), b3 + hstep, voffB); PG8_STAGE(PG8_SA(1, 0), a3, voffA);
;             PG8_WAIT_V(8); PG8_WAIT_L(0); PG8_BAR; if constexpr (!HALFM) { PG8_MMA(1, 0, At, B0); PG8_MMA(1, 1, At, B1); } PG8_BAR; PG8_SCHED;
	s_setprio 1
	v_mfma_f32_16x16x32_bf16 v[118:121], v[154:157], v[186:189], v[118:121]
	v_mfma_f32_16x16x32_bf16 v[114:117], v[162:165], v[186:189], v[114:117]
	v_mfma_f32_16x16x32_bf16 v[110:113], v[154:157], v[194:197], v[110:113]
	v_mfma_f32_16x16x32_bf16 v[106:109], v[162:165], v[194:197], v[106:109]
	v_mfma_f32_16x16x32_bf16 v[94:97], v[154:157], v[202:205], v[94:97]
	v_mfma_f32_16x16x32_bf16 v[90:93], v[162:165], v[202:205], v[90:93]
	v_mfma_f32_16x16x32_bf16 v[78:81], v[154:157], v[210:213], v[78:81]
	v_mfma_f32_16x16x32_bf16 v[74:77], v[162:165], v[210:213], v[74:77]
	v_mfma_f32_16x16x32_bf16 v[118:121], v[158:161], v[190:193], v[118:121]
	v_mfma_f32_16x16x32_bf16 v[114:117], v[166:169], v[190:193], v[114:117]
	v_mfma_f32_16x16x32_bf16 v[110:113], v[158:161], v[198:201], v[110:113]
	v_mfma_f32_16x16x32_bf16 v[106:109], v[166:169], v[198:201], v[106:109]
	v_mfma_f32_16x16x32_bf16 v[94:97], v[158:161], v[206:209], v[94:97]
	v_mfma_f32_16x16x32_bf16 v[90:93], v[166:169], v[206:209], v[90:93]
	v_mfma_f32_16x16x32_bf16 v[78:81], v[158:161], v[214:217], v[78:81]
	v_mfma_f32_16x16x32_bf16 v[74:77], v[166:169], v[214:217], v[74:77]
	s_setprio 0
	s_setprio 1
	v_mfma_f32_16x16x32_bf16 v[126:129], v[170:173], v[186:189], v[126:129]
	v_mfma_f32_16x16x32_bf16 v[122:125], v[178:181], v[186:189], v[122:125]
	v_mfma_f32_16x16x32_bf16 v[102:105], v[170:173], v[194:197], v[102:105]
	v_mfma_f32_16x16x32_bf16 v[98:101], v[178:181], v[194:197], v[98:101]
	v_mfma_f32_16x16x32_bf16 v[86:89], v[170:173], v[202:205], v[86:89]
	v_mfma_f32_16x16x32_bf16 v[82:85], v[178:181], v[202:205], v[82:85]
	v_mfma_f32_16x16x32_bf16 v[70:73], v[170:173], v[210:213], v[70:73]
	v_mfma_f32_16x16x32_bf16 v[66:69], v[178:181], v[210:213], v[66:69]
	v_mfma_f32_16x16x32_bf16 v[126:129], v[174:177], v[190:193], v[126:129]
	v_mfma_f32_16x16x32_bf16 v[122:125], v[182:185], v[190:193], v[122:125]
	v_mfma_f32_16x16x32_bf16 v[102:105], v[174:177], v[198:201], v[102:105]
	v_mfma_f32_16x16x32_bf16 v[98:101], v[182:185], v[198:201], v[98:101]
	v_mfma_f32_16x16x32_bf16 v[86:89], v[174:177], v[206:209], v[86:89]
	v_mfma_f32_16x16x32_bf16 v[82:85], v[182:185], v[206:209], v[82:85]
	v_mfma_f32_16x16x32_bf16 v[70:73], v[174:177], v[214:217], v[70:73]
	v_mfma_f32_16x16x32_bf16 v[66:69], v[182:185], v[214:217], v[66:69]
	s_setprio 0
	s_barrier
	s_add_i32 s40, s58, s0
	v_lshl_add_u64 v[146:147], v[146:147], 0, s[14:15]
	s_mov_b32 m0, s40
	ds_read_b128 v[186:189], v152 offset:49152
	ds_read_b128 v[190:193], v152 offset:50176
	ds_read_b128 v[194:197], v152 offset:51200
	ds_read_b128 v[198:201], v152 offset:52224
	ds_read_b128 v[202:205], v152 offset:53248
	ds_read_b128 v[206:209], v152 offset:54272
	ds_read_b128 v[210:213], v152 offset:55296
	ds_read_b128 v[214:217], v152 offset:56320
	global_load_lds_dwordx4 v[146:147], off
	s_add_i32 m0, s40, 0x2000
	s_add_u32 s38, s38, 0x40080
	v_lshl_add_u64 v[146:147], v[218:219], 0, s[14:15]
	s_addc_u32 s39, s39, 0
	s_add_i32 s40, s59, s0
	global_load_lds_dwordx4 v[146:147], off
	v_lshl_add_u64 v[146:147], s[38:39], 0, v[134:135]
	s_mov_b32 m0, s40
	s_nop 0
	global_load_lds_dwordx4 v[146:147], off
	v_lshl_add_u64 v[146:147], s[38:39], 0, v[130:131]
	s_add_i32 m0, s40, 0x2000
	s_nop 0
	global_load_lds_dwordx4 v[146:147], off
	s_waitcnt vmcnt(4)
	s_waitcnt lgkmcnt(0)
	s_barrier
	s_setprio 1
	v_mfma_f32_16x16x32_bf16 v[62:65], v[154:157], v[186:189], v[62:65]
	v_mfma_f32_16x16x32_bf16 v[58:61], v[162:165], v[186:189], v[58:61]
	v_mfma_f32_16x16x32_bf16 v[46:49], v[154:157], v[194:197], v[46:49]
	v_mfma_f32_16x16x32_bf16 v[42:45], v[162:165], v[194:197], v[42:45]
	v_mfma_f32_16x16x32_bf16 v[30:33], v[154:157], v[202:205], v[30:33]
	v_mfma_f32_16x16x32_bf16 v[26:29], v[162:165], v[202:205], v[26:29]
	v_mfma_f32_16x16x32_bf16 v[14:17], v[154:157], v[210:213], v[14:17]
	v_mfma_f32_16x16x32_bf16 v[10:13], v[162:165], v[210:213], v[10:13]
	v_mfma_f32_16x16x32_bf16 v[62:65], v[158:161], v[190:193], v[62:65]
	v_mfma_f32_16x16x32_bf16 v[58:61], v[166:169], v[190:193], v[58:61]
	v_mfma_f32_16x16x32_bf16 v[46:49], v[158:161], v[198:201], v[46:49]
	v_mfma_f32_16x16x32_bf16 v[42:45], v[166:169], v[198:201], v[42:45]
	v_mfma_f32_16x16x32_bf16 v[30:33], v[158:161], v[206:209], v[30:33]
	v_mfma_f32_16x16x32_bf16 v[26:29], v[166:169], v[206:209], v[26:29]
	v_mfma_f32_16x16x32_bf16 v[14:17], v[158:161], v[214:217], v[14:17]
	v_mfma_f32_16x16x32_bf16 v[10:13], v[166:169], v[214:217], v[10:13]
	s_setprio 0
	s_setprio 1
	v_mfma_f32_16x16x32_bf16 v[54:57], v[170:173], v[186:189], v[54:57]
	v_mfma_f32_16x16x32_bf16 v[50:53], v[178:181], v[186:189], v[50:53]
	v_mfma_f32_16x16x32_bf16 v[38:41], v[170:173], v[194:197], v[38:41]
	v_mfma_f32_16x16x32_bf16 v[34:37], v[178:181], v[194:197], v[34:37]
	v_mfma_f32_16x16x32_bf16 v[22:25], v[170:173], v[202:205], v[22:25]
	v_mfma_f32_16x16x32_bf16 v[18:21], v[178:181], v[202:205], v[18:21]
	v_mfma_f32_16x16x32_bf16 v[6:9], v[170:173], v[210:213], v[6:9]
	v_mfma_f32_16x16x32_bf16 v[2:5], v[178:181], v[210:213], v[2:5]
	v_mfma_f32_16x16x32_bf16 v[54:57], v[174:177], v[190:193], v[54:57]
	v_mfma_f32_16x16x32_bf16 v[50:53], v[182:185], v[190:193], v[50:53]
	v_mfma_f32_16x16x32_bf16 v[38:41], v[174:177], v[198:201], v[38:41]
	v_mfma_f32_16x16x32_bf16 v[34:37], v[182:185], v[198:201], v[34:37]
	v_mfma_f32_16x16x32_bf16 v[22:25], v[174:177], v[206:209], v[22:25]
	v_mfma_f32_16x16x32_bf16 v[18:21], v[182:185], v[206:209], v[18:21]
	v_mfma_f32_16x16x32_bf16 v[6:9], v[174:177], v[214:217], v[6:9]
	v_mfma_f32_16x16x32_bf16 v[2:5], v[182:185], v[214:217], v[2:5]
	s_setprio 0
	s_barrier
	s_add_i32 s57, s57, 2
	s_add_u32 s36, s36, 0x100
	s_addc_u32 s37, s37, 0
	s_add_u32 s55, s55, 0x100
	s_addc_u32 s56, s56, 0
	s_cmp_gt_u32 s57, 13
	s_cbranch_scc0 .LBB0_1805
	s_and_b64 vcc, exec, s[22:23]
	s_cbranch_vccz .LBB0_1808
	s_barrier

; #define PG8_STAGE(bufoff, gbase, voff) do { _Pragma("unroll") for (int _i = 0; _i < 2; ++_i) \
;         __builtin_amdgcn_global_load_lds((const unsigned*)((const char*)(gbase) + (voff)[_i]), (PG8_LAS unsigned*)(lds + (bufoff) + ldsw + _i * 8192), 16, 0, 0); } while (0)
; #define PG8_LDA(dst, b, h) do { _Pragma("unroll") for (int m = 0; m < 4; ++m) _Pragma("unroll") for (int k = 0; k < 2; ++k) dst[m][k] = *(const PG8_LAS bf16x8*)(lds + PG8_SA(b, h) + aoff + m * 2048 + k * 1024); } while (0)
; #define PG8_LDB(dst, b, h) do { _Pragma("unroll") for (int n = 0; n < 2; ++n) _Pragma("unroll") for (int k = 0; k < 2; ++k) dst[n][k] = *(const PG8_LAS bf16x8*)(lds + PG8_SB(b, h) + boff + n * 2048 + k * 1024); } while (0)
; #define PG8_MMA(ai, bj, At, Bt) do { __builtin_amdgcn_s_setprio(1); _Pragma("unroll") for (int m = 0; m < 4; ++m) _Pragma("unroll") for (int n = 0; n < 2; ++n) _Pragma("unroll") for (int k = 0; k < 2; ++k) \
;         acc[ai][bj][m][n] = __builtin_amdgcn_mfma_f32_16x16x32_bf16(Bt[n][k], At[m][k], acc[ai][bj][m][n], 0, 0, 0); __builtin_amdgcn_s_setprio(0); } while (0)
; template <class Epi, class Sched, bool ALIGN_EPI = false, bool SP2 = false, bool HALFM = false>
; __device__ __forceinline__ void gemm_phase(PG8_LAS unsigned char* lds, const Gemm g, const Sched& S, const Epi& E) {
;     ...
;             PG8_LDB(B0, 0, 0); PG8_LDB(B1, 0, 1); PG8_SCHED; PG8_LDA(At, 0, 0); PG8_STAGE(PG8_SA(1, 1), a1 + hstep, voffA);
;             PG8_WAIT_V(8); PG8_WAIT_L(0); PG8_BAR; PG8_MMA(0, 0, At, B0); PG8_MMA(0, 1, At, B1); PG8_BAR; PG8_SCHED;
;             PG8_LDA(At, 0, 1); PG8_STAGE(PG8_SB(0, 0), b2, voffB); PG8_STAGE(PG8_SB(0, 1), b2 + hstep, voffB); PG8_STAGE(PG8_SA(0, 0), a2, voffA);
;             PG8_WAIT_V(8); PG8_WAIT_L(0); PG8_BAR; if constexpr (!HALFM) { PG8_MMA(1, 0, At, B0); PG8_MMA(1, 1, At, B1); } PG8_BAR; PG8_SCHED;
;             PG8_LDB(B0, 1, 0); PG8_LDB(B1, 1, 1); PG8_SCHED; PG8_LDA(At, 1, 0); PG8_STAGE(PG8_SA(0, 1), a2 + hstep, voffA);
;             PG8_WAIT_V(8); PG8_WAIT_L(0); PG8_BAR; PG8_MMA(0, 0, At, B0); PG8_MMA(0, 1, At, B1); PG8_BAR; PG8_SCHED;
;             PG8_LDA(At, 1, 1); PG8_STAGE(PG8_SB(1, 0), b3, voffB); PG8_STAGE(PG8_SB(1, 1), b3 + hstep, voffB); PG8_STAGE(PG8_SA(1, 0), a3, voffA);
;             PG8_WAIT_V(8); PG8_WAIT_L(0); PG8_BAR; if constexpr (!HALFM) { PG8_MMA(1, 0, At, B0); PG8_MMA(1, 1, At, B1); } PG8_BAR; PG8_SCHED;
.LBB0_1928:
	ds_read_b128 v[114:117], v246
	ds_read_b128 v[118:121], v246 offset:1024
	ds_read_b128 v[130:133], v246 offset:2048
	ds_read_b128 v[134:137], v246 offset:3072
	ds_read_b128 v[138:141], v247
	ds_read_b128 v[142:145], v247 offset:1024
	ds_read_b128 v[146:149], v247 offset:2048
	ds_read_b128 v[158:161], v247 offset:3072
	s_add_u32 s34, s30, 0x100
	s_addc_u32 s35, s31, 0
	s_cmp_eq_u32 s55, 40
	s_cselect_b32 s39, s15, s35
	s_cselect_b32 s38, s14, s34
	s_cselect_b32 s37, s29, s54
	s_cselect_b32 s36, s28, s53
	v_lshl_add_u64 v[206:207], s[30:31], 0, v[202:203]
	s_add_i32 m0, s1, 0xc000
	ds_read_b128 v[162:165], v248
	ds_read_b128 v[166:169], v248 offset:1024
	ds_read_b128 v[170:173], v248 offset:2048
	ds_read_b128 v[174:177], v248 offset:3072
	ds_read_b128 v[178:181], v248 offset:4096
	ds_read_b128 v[182:185], v248 offset:5120
	ds_read_b128 v[186:189], v248 offset:6144
	ds_read_b128 v[190:193], v248 offset:7168
	global_load_lds_dwordx4 v[206:207], off
	v_lshl_add_u64 v[206:207], s[30:31], 0, v[204:205]
	s_add_i32 m0, s1, 0xe000
	s_nop 0
	global_load_lds_dwordx4 v[206:207], off
	s_mov_b32 m0, s44
	v_lshl_add_u64 v[206:207], v[210:211], 0, s[24:25]
	global_load_lds_dwordx4 v[206:207], off
	s_mov_b32 m0, s45
	v_lshl_add_u64 v[206:207], v[212:213], 0, s[24:25]
	global_load_lds_dwordx4 v[206:207], off
	s_waitcnt vmcnt(10)
	s_waitcnt lgkmcnt(0)
	s_barrier
	s_setprio 1
	v_mfma_f32_16x16x32_bf16 v[154:157], v[114:117], v[162:165], v[154:157]
	v_mfma_f32_16x16x32_bf16 v[150:153], v[130:133], v[162:165], v[150:153]
	v_mfma_f32_16x16x32_bf16 v[110:113], v[114:117], v[170:173], v[110:113]
	v_mfma_f32_16x16x32_bf16 v[106:109], v[130:133], v[170:173], v[106:109]
	v_mfma_f32_16x16x32_bf16 v[94:97], v[114:117], v[178:181], v[94:97]
	v_mfma_f32_16x16x32_bf16 v[90:93], v[130:133], v[178:181], v[90:93]
	v_mfma_f32_16x16x32_bf16 v[78:81], v[114:117], v[186:189], v[78:81]
	v_mfma_f32_16x16x32_bf16 v[74:77], v[130:133], v[186:189], v[74:77]
	v_mfma_f32_16x16x32_bf16 v[154:157], v[118:121], v[166:169], v[154:157]
	v_mfma_f32_16x16x32_bf16 v[150:153], v[134:137], v[166:169], v[150:153]
	v_mfma_f32_16x16x32_bf16 v[110:113], v[118:121], v[174:177], v[110:113]
	v_mfma_f32_16x16x32_bf16 v[106:109], v[134:137], v[174:177], v[106:109]
	v_mfma_f32_16x16x32_bf16 v[94:97], v[118:121], v[182:185], v[94:97]
	v_mfma_f32_16x16x32_bf16 v[90:93], v[134:137], v[182:185], v[90:93]
	v_mfma_f32_16x16x32_bf16 v[78:81], v[118:121], v[190:193], v[78:81]
	v_mfma_f32_16x16x32_bf16 v[74:77], v[134:137], v[190:193], v[74:77]
	s_setprio 0
	s_setprio 1
	v_mfma_f32_16x16x32_bf16 v[126:129], v[138:141], v[162:165], v[126:129]
	v_mfma_f32_16x16x32_bf16 v[122:125], v[146:149], v[162:165], v[122:125]
	v_mfma_f32_16x16x32_bf16 v[102:105], v[138:141], v[170:173], v[102:105]
	v_mfma_f32_16x16x32_bf16 v[98:101], v[146:149], v[170:173], v[98:101]
	v_mfma_f32_16x16x32_bf16 v[86:89], v[138:141], v[178:181], v[86:89]
	v_mfma_f32_16x16x32_bf16 v[82:85], v[146:149], v[178:181], v[82:85]
	v_mfma_f32_16x16x32_bf16 v[70:73], v[138:141], v[186:189], v[70:73]
	v_mfma_f32_16x16x32_bf16 v[66:69], v[146:149], v[186:189], v[66:69]
	v_mfma_f32_16x16x32_bf16 v[126:129], v[142:145], v[166:169], v[126:129]
	v_mfma_f32_16x16x32_bf16 v[122:125], v[158:161], v[166:169], v[122:125]
	v_mfma_f32_16x16x32_bf16 v[102:105], v[142:145], v[174:177], v[102:105]
	v_mfma_f32_16x16x32_bf16 v[98:101], v[158:161], v[174:177], v[98:101]
	v_mfma_f32_16x16x32_bf16 v[86:89], v[142:145], v[182:185], v[86:89]
	v_mfma_f32_16x16x32_bf16 v[82:85], v[158:161], v[182:185], v[82:85]
	v_mfma_f32_16x16x32_bf16 v[70:73], v[142:145], v[190:193], v[70:73]
	v_mfma_f32_16x16x32_bf16 v[66:69], v[158:161], v[190:193], v[66:69]
	s_setprio 0
	s_barrier
	s_add_i32 s30, s47, s0
	v_lshl_add_u64 v[206:207], s[36:37], 0, v[196:197]
	s_mov_b32 m0, s30
	ds_read_b128 v[162:165], v248 offset:16384
	ds_read_b128 v[166:169], v248 offset:17408
	ds_read_b128 v[170:173], v248 offset:18432
	ds_read_b128 v[174:177], v248 offset:19456
	ds_read_b128 v[178:181], v248 offset:20480
	ds_read_b128 v[182:185], v248 offset:21504
	ds_read_b128 v[186:189], v248 offset:22528
	ds_read_b128 v[190:193], v248 offset:23552
	global_load_lds_dwordx4 v[206:207], off
	s_add_i32 m0, s30, 0x2000
	s_add_u32 s30, s36, 0xb0000
	v_lshl_add_u64 v[208:209], s[36:37], 0, v[200:201]
	s_addc_u32 s31, s37, 0
	s_add_i32 s56, s48, s0
	global_load_lds_dwordx4 v[208:209], off
	v_lshl_add_u64 v[210:211], s[30:31], 0, v[196:197]
	s_mov_b32 m0, s56
	v_lshl_add_u64 v[212:213], s[38:39], 0, v[198:199]
	global_load_lds_dwordx4 v[210:211], off
	v_lshl_add_u64 v[210:211], s[30:31], 0, v[200:201]
	s_add_i32 m0, s56, 0x2000
	s_nop 0
	global_load_lds_dwordx4 v[210:211], off
	v_lshl_add_u64 v[210:211], s[38:39], 0, v[194:195]
	s_waitcnt vmcnt(4)
	s_waitcnt lgkmcnt(0)
	s_barrier
; #define PG8_STAGE(bufoff, gbase, voff) do { _Pragma("unroll") for (int _i = 0; _i < 2; ++_i) \
;         __builtin_amdgcn_global_load_lds((const unsigned*)((const char*)(gbase) + (voff)[_i]), (PG8_LAS unsigned*)(lds + (bufoff) + ldsw + _i * 8192), 16, 0, 0); } while (0)
; #define PG8_LDA(dst, b, h) do { _Pragma("unroll") for (int m = 0; m < 4; ++m) _Pragma("unroll") for (int k = 0; k < 2; ++k) dst[m][k] = *(const PG8_LAS bf16x8*)(lds + PG8_SA(b, h) + aoff + m * 2048 + k * 1024); } while (0)
; #define PG8_LDB(dst, b, h) do { _Pragma("unroll") for (int n = 0; n < 2; ++n) _Pragma("unroll") for (int k = 0; k < 2; ++k) dst[n][k] = *(const PG8_LAS bf16x8*)(lds + PG8_SB(b, h) + boff + n * 2048 + k * 1024); } while (0)
; #define PG8_MMA(ai, bj, At, Bt) do { __builtin_amdgcn_s_setprio(1); _Pragma("unroll") for (int m = 0; m < 4; ++m) _Pragma("unroll") for (int n = 0; n < 2; ++n) _Pragma("unroll") for (int k = 0; k < 2; ++k) \
;         acc[ai][bj][m][n] = __builtin_amdgcn_mfma_f32_16x16x32_bf16(Bt[n][k], At[m][k], acc[ai][bj][m][n], 0, 0, 0); __builtin_amdgcn_s_setprio(0); } while (0)
; template <class Epi, class Sched, bool ALIGN_EPI = false, bool SP2 = false, bool HALFM = false>
; __device__ __forceinline__ void gemm_phase(PG8_LAS unsigned char* lds, const Gemm g, const Sched& S, const Epi& E) {
;     ...
;             PG8_LDB(B0, 0, 0); PG8_LDB(B1, 0, 1); PG8_SCHED; PG8_LDA(At, 0, 0); PG8_STAGE(PG8_SA(1, 1), a1 + hstep, voffA);
;             PG8_WAIT_V(8); PG8_WAIT_L(0); PG8_BAR; PG8_MMA(0, 0, At, B0); PG8_MMA(0, 1, At, B1); PG8_BAR; PG8_SCHED;
;             PG8_LDA(At, 0, 1); PG8_STAGE(PG8_SB(0, 0), b2, voffB); PG8_STAGE(PG8_SB(0, 1), b2 + hstep, voffB); PG8_STAGE(PG8_SA(0, 0), a2, voffA);
;             PG8_WAIT_V(8); PG8_WAIT_L(0); PG8_BAR; if constexpr (!HALFM) { PG8_MMA(1, 0, At, B0); PG8_MMA(1, 1, At, B1); } PG8_BAR; PG8_SCHED;
;             PG8_LDB(B0, 1, 0); PG8_LDB(B1, 1, 1); PG8_SCHED; PG8_LDA(At, 1, 0); PG8_STAGE(PG8_SA(0, 1), a2 + hstep, voffA);
;             PG8_WAIT_V(8); PG8_WAIT_L(0); PG8_BAR; PG8_MMA(0, 0, At, B0); PG8_MMA(0, 1, At, B1); PG8_BAR; PG8_SCHED;
;             PG8_LDA(At, 1, 1); PG8_STAGE(PG8_SB(1, 0), b3, voffB); PG8_STAGE(PG8_SB(1, 1), b3 + hstep, voffB); PG8_STAGE(PG8_SA(1, 0), a3, voffA);
;             PG8_WAIT_V(8); PG8_WAIT_L(0); PG8_BAR; if constexpr (!HALFM) { PG8_MMA(1, 0, At, B0); PG8_MMA(1, 1, At, B1); } PG8_BAR; PG8_SCHED;
	s_setprio 1
	v_mfma_f32_16x16x32_bf16 v[62:65], v[114:117], v[162:165], v[62:65]
	v_mfma_f32_16x16x32_bf16 v[58:61], v[130:133], v[162:165], v[58:61]
	v_mfma_f32_16x16x32_bf16 v[46:49], v[114:117], v[170:173], v[46:49]
	v_mfma_f32_16x16x32_bf16 v[42:45], v[130:133], v[170:173], v[42:45]
	v_mfma_f32_16x16x32_bf16 v[30:33], v[114:117], v[178:181], v[30:33]
	v_mfma_f32_16x16x32_bf16 v[26:29], v[130:133], v[178:181], v[26:29]
	v_mfma_f32_16x16x32_bf16 v[14:17], v[114:117], v[186:189], v[14:17]
	v_mfma_f32_16x16x32_bf16 v[10:13], v[130:133], v[186:189], v[10:13]
	v_mfma_f32_16x16x32_bf16 v[62:65], v[118:121], v[166:169], v[62:65]
	v_mfma_f32_16x16x32_bf16 v[58:61], v[134:137], v[166:169], v[58:61]
	v_mfma_f32_16x16x32_bf16 v[46:49], v[118:121], v[174:177], v[46:49]
	v_mfma_f32_16x16x32_bf16 v[42:45], v[134:137], v[174:177], v[42:45]
	v_mfma_f32_16x16x32_bf16 v[30:33], v[118:121], v[182:185], v[30:33]
	v_mfma_f32_16x16x32_bf16 v[26:29], v[134:137], v[182:185], v[26:29]
	v_mfma_f32_16x16x32_bf16 v[14:17], v[118:121], v[190:193], v[14:17]
	v_mfma_f32_16x16x32_bf16 v[10:13], v[134:137], v[190:193], v[10:13]
	s_setprio 0
	s_setprio 1
	v_mfma_f32_16x16x32_bf16 v[54:57], v[138:141], v[162:165], v[54:57]
	v_mfma_f32_16x16x32_bf16 v[50:53], v[146:149], v[162:165], v[50:53]
	v_mfma_f32_16x16x32_bf16 v[38:41], v[138:141], v[170:173], v[38:41]
	v_mfma_f32_16x16x32_bf16 v[34:37], v[146:149], v[170:173], v[34:37]
	v_mfma_f32_16x16x32_bf16 v[22:25], v[138:141], v[178:181], v[22:25]
	v_mfma_f32_16x16x32_bf16 v[18:21], v[146:149], v[178:181], v[18:21]
	v_mfma_f32_16x16x32_bf16 v[6:9], v[138:141], v[186:189], v[6:9]
	v_mfma_f32_16x16x32_bf16 v[2:5], v[146:149], v[186:189], v[2:5]
	v_mfma_f32_16x16x32_bf16 v[54:57], v[142:145], v[166:169], v[54:57]
	v_mfma_f32_16x16x32_bf16 v[50:53], v[158:161], v[166:169], v[50:53]
	v_mfma_f32_16x16x32_bf16 v[38:41], v[142:145], v[174:177], v[38:41]
	v_mfma_f32_16x16x32_bf16 v[34:37], v[158:161], v[174:177], v[34:37]
	v_mfma_f32_16x16x32_bf16 v[22:25], v[142:145], v[182:185], v[22:25]
	v_mfma_f32_16x16x32_bf16 v[18:21], v[158:161], v[182:185], v[18:21]
	v_mfma_f32_16x16x32_bf16 v[6:9], v[142:145], v[190:193], v[6:9]
	v_mfma_f32_16x16x32_bf16 v[2:5], v[158:161], v[190:193], v[2:5]
	s_setprio 0
	s_barrier
	s_add_i32 s56, 0, 0x18000
	s_add_i32 s57, 0, 0x1c000
	v_add_u32_e32 v134, s56, v244
	v_add_u32_e32 v158, s57, v244
	ds_read_b128 v[114:117], v134
	ds_read_b128 v[118:121], v134 offset:1024
	ds_read_b128 v[130:133], v134 offset:2048
	ds_read_b128 v[134:137], v134 offset:3072
	ds_read_b128 v[138:141], v158
	ds_read_b128 v[142:145], v158 offset:1024
	ds_read_b128 v[146:149], v158 offset:2048
	ds_read_b128 v[158:161], v158 offset:3072
	s_add_u32 s30, s38, 0xb0000
	s_addc_u32 s31, s39, 0
	s_mov_b32 m0, s3
	v_lshl_add_u64 v[214:215], s[30:31], 0, v[194:195]
	ds_read_b128 v[162:165], v248 offset:32768
	ds_read_b128 v[166:169], v248 offset:33792
	ds_read_b128 v[170:173], v248 offset:34816
	ds_read_b128 v[174:177], v248 offset:35840
	ds_read_b128 v[178:181], v248 offset:36864
	ds_read_b128 v[182:185], v248 offset:37888
	ds_read_b128 v[186:189], v248 offset:38912
	ds_read_b128 v[190:193], v248 offset:39936
	global_load_lds_dwordx4 v[214:215], off
	v_lshl_add_u64 v[214:215], s[30:31], 0, v[198:199]
	s_mov_b32 m0, s40
	s_nop 0
	global_load_lds_dwordx4 v[214:215], off
	s_mov_b32 m0, s1
	s_nop 0
	global_load_lds_dwordx4 v[210:211], off
	s_mov_b32 m0, s2
	s_nop 0
	global_load_lds_dwordx4 v[212:213], off
	s_waitcnt vmcnt(10)
	s_waitcnt lgkmcnt(0)
	s_barrier
; #define PG8_STAGE(bufoff, gbase, voff) do { _Pragma("unroll") for (int _i = 0; _i < 2; ++_i) \
;         __builtin_amdgcn_global_load_lds((const unsigned*)((const char*)(gbase) + (voff)[_i]), (PG8_LAS unsigned*)(lds + (bufoff) + ldsw + _i * 8192), 16, 0, 0); } while (0)
; #define PG8_LDA(dst, b, h) do { _Pragma("unroll") for (int m = 0; m < 4; ++m) _Pragma("unroll") for (int k = 0; k < 2; ++k) dst[m][k] = *(const PG8_LAS bf16x8*)(lds + PG8_SA(b, h) + aoff + m * 2048 + k * 1024); } while (0)
; #define PG8_LDB(dst, b, h) do { _Pragma("unroll") for (int n = 0; n < 2; ++n) _Pragma("unroll") for (int k = 0; k < 2; ++k) dst[n][k] = *(const PG8_LAS bf16x8*)(lds + PG8_SB(b, h) + boff + n * 2048 + k * 1024); } while (0)
; #define PG8_WAIT_V(n) asm volatile("s_waitcnt vmcnt(" #n ")" ::: "memory")
; #define PG8_WAIT_L(n) asm volatile("s_waitcnt lgkmcnt(" #n ")" ::: "memory")
; #define PG8_BAR __builtin_amdgcn_s_barrier()
; #define PG8_SCHED __builtin_amdgcn_sched_barrier(0)
; template <class Epi, class Sched, bool ALIGN_EPI = false, bool SP2 = false, bool HALFM = false>
; __device__ __forceinline__ void gemm_phase(PG8_LAS unsigned char* lds, const Gemm g, const Sched& S, const Epi& E) {
;     ...
;         for (int t = 0; t < nt; t += 2) {
;     ...
;             PG8_LDB(B0, 0, 0); PG8_LDB(B1, 0, 1); PG8_SCHED; PG8_LDA(At, 0, 0); PG8_STAGE(PG8_SA(1, 1), a1 + hstep, voffA);
;             PG8_WAIT_V(8); PG8_WAIT_L(0); PG8_BAR; PG8_MMA(0, 0, At, B0); PG8_MMA(0, 1, At, B1); PG8_BAR; PG8_SCHED;
;             PG8_LDA(At, 0, 1); PG8_STAGE(PG8_SB(0, 0), b2, voffB); PG8_STAGE(PG8_SB(0, 1), b2 + hstep, voffB); PG8_STAGE(PG8_SA(0, 0), a2, voffA);
;             PG8_WAIT_V(8); PG8_WAIT_L(0); PG8_BAR; if constexpr (!HALFM) { PG8_MMA(1, 0, At, B0); PG8_MMA(1, 1, At, B1); } PG8_BAR; PG8_SCHED;
;             PG8_LDB(B0, 1, 0); PG8_LDB(B1, 1, 1); PG8_SCHED; PG8_LDA(At, 1, 0); PG8_STAGE(PG8_SA(0, 1), a2 + hstep, voffA);
;             PG8_WAIT_V(8); PG8_WAIT_L(0); PG8_BAR; PG8_MMA(0, 0, At, B0); PG8_MMA(0, 1, At, B1); PG8_BAR; PG8_SCHED;
;             PG8_LDA(At, 1, 1); PG8_STAGE(PG8_SB(1, 0), b3, voffB); PG8_STAGE(PG8_SB(1, 1), b3 + hstep, voffB); PG8_STAGE(PG8_SA(1, 0), a3, voffA);
;             PG8_WAIT_V(8); PG8_WAIT_L(0); PG8_BAR; if constexpr (!HALFM) { PG8_MMA(1, 0, At, B0); PG8_MMA(1, 1, At, B1); } PG8_BAR; PG8_SCHED;
	s_setprio 1
	v_mfma_f32_16x16x32_bf16 v[154:157], v[114:117], v[162:165], v[154:157]
	v_mfma_f32_16x16x32_bf16 v[150:153], v[130:133], v[162:165], v[150:153]
	v_mfma_f32_16x16x32_bf16 v[110:113], v[114:117], v[170:173], v[110:113]
	v_mfma_f32_16x16x32_bf16 v[106:109], v[130:133], v[170:173], v[106:109]
	v_mfma_f32_16x16x32_bf16 v[94:97], v[114:117], v[178:181], v[94:97]
	v_mfma_f32_16x16x32_bf16 v[90:93], v[130:133], v[178:181], v[90:93]
	v_mfma_f32_16x16x32_bf16 v[78:81], v[114:117], v[186:189], v[78:81]
	v_mfma_f32_16x16x32_bf16 v[74:77], v[130:133], v[186:189], v[74:77]
	v_mfma_f32_16x16x32_bf16 v[154:157], v[118:121], v[166:169], v[154:157]
	v_mfma_f32_16x16x32_bf16 v[150:153], v[134:137], v[166:169], v[150:153]
	v_mfma_f32_16x16x32_bf16 v[110:113], v[118:121], v[174:177], v[110:113]
	v_mfma_f32_16x16x32_bf16 v[106:109], v[134:137], v[174:177], v[106:109]
	v_mfma_f32_16x16x32_bf16 v[94:97], v[118:121], v[182:185], v[94:97]
	v_mfma_f32_16x16x32_bf16 v[90:93], v[134:137], v[182:185], v[90:93]
	v_mfma_f32_16x16x32_bf16 v[78:81], v[118:121], v[190:193], v[78:81]
	v_mfma_f32_16x16x32_bf16 v[74:77], v[134:137], v[190:193], v[74:77]
	s_setprio 0
	s_setprio 1
	v_mfma_f32_16x16x32_bf16 v[126:129], v[138:141], v[162:165], v[126:129]
	v_mfma_f32_16x16x32_bf16 v[122:125], v[146:149], v[162:165], v[122:125]
	v_mfma_f32_16x16x32_bf16 v[102:105], v[138:141], v[170:173], v[102:105]
	v_mfma_f32_16x16x32_bf16 v[98:101], v[146:149], v[170:173], v[98:101]
	v_mfma_f32_16x16x32_bf16 v[86:89], v[138:141], v[178:181], v[86:89]
	v_mfma_f32_16x16x32_bf16 v[82:85], v[146:149], v[178:181], v[82:85]
	v_mfma_f32_16x16x32_bf16 v[70:73], v[138:141], v[186:189], v[70:73]
	v_mfma_f32_16x16x32_bf16 v[66:69], v[146:149], v[186:189], v[66:69]
	v_mfma_f32_16x16x32_bf16 v[126:129], v[142:145], v[166:169], v[126:129]
	v_mfma_f32_16x16x32_bf16 v[122:125], v[158:161], v[166:169], v[122:125]
	v_mfma_f32_16x16x32_bf16 v[102:105], v[142:145], v[174:177], v[102:105]
	v_mfma_f32_16x16x32_bf16 v[98:101], v[158:161], v[174:177], v[98:101]
	v_mfma_f32_16x16x32_bf16 v[86:89], v[142:145], v[182:185], v[86:89]
	v_mfma_f32_16x16x32_bf16 v[82:85], v[158:161], v[182:185], v[82:85]
	v_mfma_f32_16x16x32_bf16 v[70:73], v[142:145], v[190:193], v[70:73]
	v_mfma_f32_16x16x32_bf16 v[66:69], v[158:161], v[190:193], v[66:69]
	s_setprio 0
	s_barrier
	s_add_i32 s30, s56, s0
	v_lshl_add_u64 v[206:207], v[206:207], 0, s[24:25]
	s_mov_b32 m0, s30
	ds_read_b128 v[162:165], v248 offset:49152
	ds_read_b128 v[166:169], v248 offset:50176
	ds_read_b128 v[170:173], v248 offset:51200
	ds_read_b128 v[174:177], v248 offset:52224
	ds_read_b128 v[178:181], v248 offset:53248
	ds_read_b128 v[182:185], v248 offset:54272
	ds_read_b128 v[186:189], v248 offset:55296
	ds_read_b128 v[190:193], v248 offset:56320
	global_load_lds_dwordx4 v[206:207], off
	s_add_i32 m0, s30, 0x2000
	s_add_u32 s30, s36, 0xb0080
	v_lshl_add_u64 v[206:207], v[208:209], 0, s[24:25]
	s_addc_u32 s31, s37, 0
	s_add_i32 s36, s57, s0
	global_load_lds_dwordx4 v[206:207], off
	v_lshl_add_u64 v[206:207], s[30:31], 0, v[196:197]
	s_mov_b32 m0, s36
	s_nop 0
	global_load_lds_dwordx4 v[206:207], off
	v_lshl_add_u64 v[206:207], s[30:31], 0, v[200:201]
	s_add_i32 m0, s36, 0x2000
	s_nop 0
	global_load_lds_dwordx4 v[206:207], off
	s_waitcnt vmcnt(4)
	s_waitcnt lgkmcnt(0)
	s_barrier
	s_setprio 1
	v_mfma_f32_16x16x32_bf16 v[62:65], v[114:117], v[162:165], v[62:65]
	v_mfma_f32_16x16x32_bf16 v[58:61], v[130:133], v[162:165], v[58:61]
	v_mfma_f32_16x16x32_bf16 v[46:49], v[114:117], v[170:173], v[46:49]
	v_mfma_f32_16x16x32_bf16 v[42:45], v[130:133], v[170:173], v[42:45]
	v_mfma_f32_16x16x32_bf16 v[30:33], v[114:117], v[178:181], v[30:33]
	v_mfma_f32_16x16x32_bf16 v[26:29], v[130:133], v[178:181], v[26:29]
	v_mfma_f32_16x16x32_bf16 v[14:17], v[114:117], v[186:189], v[14:17]
	v_mfma_f32_16x16x32_bf16 v[10:13], v[130:133], v[186:189], v[10:13]
	v_mfma_f32_16x16x32_bf16 v[62:65], v[118:121], v[166:169], v[62:65]
	v_mfma_f32_16x16x32_bf16 v[58:61], v[134:137], v[166:169], v[58:61]
	v_mfma_f32_16x16x32_bf16 v[46:49], v[118:121], v[174:177], v[46:49]
	v_mfma_f32_16x16x32_bf16 v[42:45], v[134:137], v[174:177], v[42:45]
	v_mfma_f32_16x16x32_bf16 v[30:33], v[118:121], v[182:185], v[30:33]
	v_mfma_f32_16x16x32_bf16 v[26:29], v[134:137], v[182:185], v[26:29]
	v_mfma_f32_16x16x32_bf16 v[14:17], v[118:121], v[190:193], v[14:17]
	v_mfma_f32_16x16x32_bf16 v[10:13], v[134:137], v[190:193], v[10:13]
	s_setprio 0
	s_setprio 1
	v_mfma_f32_16x16x32_bf16 v[54:57], v[138:141], v[162:165], v[54:57]
	v_mfma_f32_16x16x32_bf16 v[50:53], v[146:149], v[162:165], v[50:53]
	v_mfma_f32_16x16x32_bf16 v[38:41], v[138:141], v[170:173], v[38:41]
	v_mfma_f32_16x16x32_bf16 v[34:37], v[146:149], v[170:173], v[34:37]
	v_mfma_f32_16x16x32_bf16 v[22:25], v[138:141], v[178:181], v[22:25]
	v_mfma_f32_16x16x32_bf16 v[18:21], v[146:149], v[178:181], v[18:21]
	v_mfma_f32_16x16x32_bf16 v[6:9], v[138:141], v[186:189], v[6:9]
	v_mfma_f32_16x16x32_bf16 v[2:5], v[146:149], v[186:189], v[2:5]
	v_mfma_f32_16x16x32_bf16 v[54:57], v[142:145], v[166:169], v[54:57]
	v_mfma_f32_16x16x32_bf16 v[50:53], v[158:161], v[166:169], v[50:53]
	v_mfma_f32_16x16x32_bf16 v[38:41], v[142:145], v[174:177], v[38:41]
	v_mfma_f32_16x16x32_bf16 v[34:37], v[158:161], v[174:177], v[34:37]
	v_mfma_f32_16x16x32_bf16 v[22:25], v[142:145], v[182:185], v[22:25]
	v_mfma_f32_16x16x32_bf16 v[18:21], v[158:161], v[182:185], v[18:21]
	v_mfma_f32_16x16x32_bf16 v[6:9], v[142:145], v[190:193], v[6:9]
	v_mfma_f32_16x16x32_bf16 v[2:5], v[158:161], v[190:193], v[2:5]
	s_setprio 0
	s_barrier
	s_add_i32 s55, s55, 2
	s_add_u32 s53, s53, 0x100
	s_addc_u32 s54, s54, 0
	s_cmp_gt_u32 s55, 41
	s_mov_b64 s[30:31], s[34:35]
	s_cbranch_scc0 .LBB0_1928
	s_and_b64 vcc, exec, s[26:27]
	s_cbranch_vccz .LBB0_1931
	s_barrier

; #define PG8_STAGE(bufoff, gbase, voff) do { _Pragma("unroll") for (int _i = 0; _i < 2; ++_i) \
;         __builtin_amdgcn_global_load_lds((const unsigned*)((const char*)(gbase) + (voff)[_i]), (PG8_LAS unsigned*)(lds + (bufoff) + ldsw + _i * 8192), 16, 0, 0); } while (0)
; #define PG8_LDA(dst, b, h) do { _Pragma("unroll") for (int m = 0; m < 4; ++m) _Pragma("unroll") for (int k = 0; k < 2; ++k) dst[m][k] = *(const PG8_LAS bf16x8*)(lds + PG8_SA(b, h) + aoff + m * 2048 + k * 1024); } while (0)
; #define PG8_LDB(dst, b, h) do { _Pragma("unroll") for (int n = 0; n < 2; ++n) _Pragma("unroll") for (int k = 0; k < 2; ++k) dst[n][k] = *(const PG8_LAS bf16x8*)(lds + PG8_SB(b, h) + boff + n * 2048 + k * 1024); } while (0)
; #define PG8_MMA(ai, bj, At, Bt) do { __builtin_amdgcn_s_setprio(1); _Pragma("unroll") for (int m = 0; m < 4; ++m) _Pragma("unroll") for (int n = 0; n < 2; ++n) _Pragma("unroll") for (int k = 0; k < 2; ++k) \
;         acc[ai][bj][m][n] = __builtin_amdgcn_mfma_f32_16x16x32_bf16(Bt[n][k], At[m][k], acc[ai][bj][m][n], 0, 0, 0); __builtin_amdgcn_s_setprio(0); } while (0)
; template <class Epi, class Sched, bool ALIGN_EPI = false, bool SP2 = false, bool HALFM = false>
; __device__ __forceinline__ void gemm_phase(PG8_LAS unsigned char* lds, const Gemm g, const Sched& S, const Epi& E) {
;     ...
;             PG8_LDB(B0, 0, 0); PG8_LDB(B1, 0, 1); PG8_SCHED; PG8_LDA(At, 0, 0); PG8_STAGE(PG8_SA(1, 1), a1 + hstep, voffA);
;             PG8_WAIT_V(8); PG8_WAIT_L(0); PG8_BAR; PG8_MMA(0, 0, At, B0); PG8_MMA(0, 1, At, B1); PG8_BAR; PG8_SCHED;
;             PG8_LDA(At, 0, 1); PG8_STAGE(PG8_SB(0, 0), b2, voffB); PG8_STAGE(PG8_SB(0, 1), b2 + hstep, voffB); PG8_STAGE(PG8_SA(0, 0), a2, voffA);
;             PG8_WAIT_V(8); PG8_WAIT_L(0); PG8_BAR; if constexpr (!HALFM) { PG8_MMA(1, 0, At, B0); PG8_MMA(1, 1, At, B1); } PG8_BAR; PG8_SCHED;
;             PG8_LDB(B0, 1, 0); PG8_LDB(B1, 1, 1); PG8_SCHED; PG8_LDA(At, 1, 0); PG8_STAGE(PG8_SA(0, 1), a2 + hstep, voffA);
;             PG8_WAIT_V(8); PG8_WAIT_L(0); PG8_BAR; PG8_MMA(0, 0, At, B0); PG8_MMA(0, 1, At, B1); PG8_BAR; PG8_SCHED;
;             PG8_LDA(At, 1, 1); PG8_STAGE(PG8_SB(1, 0), b3, voffB); PG8_STAGE(PG8_SB(1, 1), b3 + hstep, voffB); PG8_STAGE(PG8_SA(1, 0), a3, voffA);
;             PG8_WAIT_V(8); PG8_WAIT_L(0); PG8_BAR; if constexpr (!HALFM) { PG8_MMA(1, 0, At, B0); PG8_MMA(1, 1, At, B1); } PG8_BAR; PG8_SCHED;
.LBB0_2049:
	ds_read_b128 v[126:129], v212
	ds_read_b128 v[130:133], v212 offset:1024
	ds_read_b128 v[138:141], v212 offset:2048
	ds_read_b128 v[142:145], v212 offset:3072
	ds_read_b128 v[146:149], v213
	ds_read_b128 v[150:153], v213 offset:1024
	ds_read_b128 v[154:157], v213 offset:2048
	ds_read_b128 v[158:161], v213 offset:3072
	s_add_u32 s38, s36, 0xfffc0080
	s_addc_u32 s39, s37, -1
	s_cmp_eq_u32 s56, 12
	s_cselect_b32 s41, s27, s39
	s_cselect_b32 s40, s52, s38
	s_cselect_b32 s39, s25, s55
	s_cselect_b32 s38, s53, s54
	v_lshl_add_u64 v[216:217], s[36:37], 0, v[186:187]
	s_add_i32 m0, s1, 0xc000
	ds_read_b128 v[162:165], v214
	ds_read_b128 v[166:169], v214 offset:1024
	ds_read_b128 v[170:173], v214 offset:2048
	ds_read_b128 v[174:177], v214 offset:3072
	ds_read_b128 v[194:197], v214 offset:4096
	ds_read_b128 v[198:201], v214 offset:5120
	ds_read_b128 v[202:205], v214 offset:6144
	ds_read_b128 v[206:209], v214 offset:7168
	global_load_lds_dwordx4 v[216:217], off
	v_lshl_add_u64 v[216:217], s[36:37], 0, v[188:189]
	s_add_i32 m0, s1, 0xe000
	s_nop 0
	global_load_lds_dwordx4 v[216:217], off
	s_mov_b32 m0, s43
	v_lshl_add_u64 v[216:217], v[220:221], 0, s[10:11]
	global_load_lds_dwordx4 v[216:217], off
	s_mov_b32 m0, s46
	v_lshl_add_u64 v[216:217], v[222:223], 0, s[10:11]
	global_load_lds_dwordx4 v[216:217], off
	s_waitcnt vmcnt(10)
	s_waitcnt lgkmcnt(0)
	s_barrier
	s_setprio 1
	v_mfma_f32_16x16x32_bf16 v[134:137], v[126:129], v[162:165], v[134:137]
	v_mfma_f32_16x16x32_bf16 v[122:125], v[138:141], v[162:165], v[122:125]
	v_mfma_f32_16x16x32_bf16 v[110:113], v[126:129], v[170:173], v[110:113]
	v_mfma_f32_16x16x32_bf16 v[106:109], v[138:141], v[170:173], v[106:109]
	v_mfma_f32_16x16x32_bf16 v[94:97], v[126:129], v[194:197], v[94:97]
	v_mfma_f32_16x16x32_bf16 v[90:93], v[138:141], v[194:197], v[90:93]
	v_mfma_f32_16x16x32_bf16 v[78:81], v[126:129], v[202:205], v[78:81]
	v_mfma_f32_16x16x32_bf16 v[74:77], v[138:141], v[202:205], v[74:77]
	v_mfma_f32_16x16x32_bf16 v[134:137], v[130:133], v[166:169], v[134:137]
	v_mfma_f32_16x16x32_bf16 v[122:125], v[142:145], v[166:169], v[122:125]
	v_mfma_f32_16x16x32_bf16 v[110:113], v[130:133], v[174:177], v[110:113]
	v_mfma_f32_16x16x32_bf16 v[106:109], v[142:145], v[174:177], v[106:109]
	v_mfma_f32_16x16x32_bf16 v[94:97], v[130:133], v[198:201], v[94:97]
	v_mfma_f32_16x16x32_bf16 v[90:93], v[142:145], v[198:201], v[90:93]
	v_mfma_f32_16x16x32_bf16 v[78:81], v[130:133], v[206:209], v[78:81]
	v_mfma_f32_16x16x32_bf16 v[74:77], v[142:145], v[206:209], v[74:77]
	s_setprio 0
	s_setprio 1
	v_mfma_f32_16x16x32_bf16 v[118:121], v[146:149], v[162:165], v[118:121]
	v_mfma_f32_16x16x32_bf16 v[114:117], v[154:157], v[162:165], v[114:117]
	v_mfma_f32_16x16x32_bf16 v[102:105], v[146:149], v[170:173], v[102:105]
	v_mfma_f32_16x16x32_bf16 v[98:101], v[154:157], v[170:173], v[98:101]
	v_mfma_f32_16x16x32_bf16 v[86:89], v[146:149], v[194:197], v[86:89]
	v_mfma_f32_16x16x32_bf16 v[82:85], v[154:157], v[194:197], v[82:85]
	v_mfma_f32_16x16x32_bf16 v[70:73], v[146:149], v[202:205], v[70:73]
	v_mfma_f32_16x16x32_bf16 v[66:69], v[154:157], v[202:205], v[66:69]
	v_mfma_f32_16x16x32_bf16 v[118:121], v[150:153], v[166:169], v[118:121]
	v_mfma_f32_16x16x32_bf16 v[114:117], v[158:161], v[166:169], v[114:117]
	v_mfma_f32_16x16x32_bf16 v[102:105], v[150:153], v[174:177], v[102:105]
	v_mfma_f32_16x16x32_bf16 v[98:101], v[158:161], v[174:177], v[98:101]
	v_mfma_f32_16x16x32_bf16 v[86:89], v[150:153], v[198:201], v[86:89]
	v_mfma_f32_16x16x32_bf16 v[82:85], v[158:161], v[198:201], v[82:85]
	v_mfma_f32_16x16x32_bf16 v[70:73], v[150:153], v[206:209], v[70:73]
	v_mfma_f32_16x16x32_bf16 v[66:69], v[158:161], v[206:209], v[66:69]
	s_setprio 0
	s_barrier
	s_add_i32 s57, s48, s0
	v_lshl_add_u64 v[216:217], s[38:39], 0, v[180:181]
	s_mov_b32 m0, s57
	ds_read_b128 v[162:165], v214 offset:16384
	ds_read_b128 v[166:169], v214 offset:17408
	ds_read_b128 v[170:173], v214 offset:18432
	ds_read_b128 v[174:177], v214 offset:19456
	ds_read_b128 v[194:197], v214 offset:20480
	ds_read_b128 v[198:201], v214 offset:21504
	ds_read_b128 v[202:205], v214 offset:22528
	ds_read_b128 v[206:209], v214 offset:23552
	global_load_lds_dwordx4 v[216:217], off
	s_add_i32 m0, s57, 0x2000
	s_add_u32 s58, s38, 0x40000
	v_lshl_add_u64 v[218:219], s[38:39], 0, v[184:185]
	s_addc_u32 s59, s39, 0
	s_add_i32 s57, s49, s0
	global_load_lds_dwordx4 v[218:219], off
	v_lshl_add_u64 v[220:221], s[58:59], 0, v[180:181]
	s_mov_b32 m0, s57
	v_lshl_add_u64 v[222:223], s[40:41], 0, v[182:183]
	global_load_lds_dwordx4 v[220:221], off
	v_lshl_add_u64 v[220:221], s[58:59], 0, v[184:185]
	s_add_i32 m0, s57, 0x2000
	s_nop 0
	global_load_lds_dwordx4 v[220:221], off
	v_lshl_add_u64 v[220:221], s[40:41], 0, v[178:179]
	s_waitcnt vmcnt(4)
	s_waitcnt lgkmcnt(0)
	s_barrier
; #define PG8_STAGE(bufoff, gbase, voff) do { _Pragma("unroll") for (int _i = 0; _i < 2; ++_i) \
;         __builtin_amdgcn_global_load_lds((const unsigned*)((const char*)(gbase) + (voff)[_i]), (PG8_LAS unsigned*)(lds + (bufoff) + ldsw + _i * 8192), 16, 0, 0); } while (0)
; #define PG8_LDA(dst, b, h) do { _Pragma("unroll") for (int m = 0; m < 4; ++m) _Pragma("unroll") for (int k = 0; k < 2; ++k) dst[m][k] = *(const PG8_LAS bf16x8*)(lds + PG8_SA(b, h) + aoff + m * 2048 + k * 1024); } while (0)
; #define PG8_LDB(dst, b, h) do { _Pragma("unroll") for (int n = 0; n < 2; ++n) _Pragma("unroll") for (int k = 0; k < 2; ++k) dst[n][k] = *(const PG8_LAS bf16x8*)(lds + PG8_SB(b, h) + boff + n * 2048 + k * 1024); } while (0)
; #define PG8_MMA(ai, bj, At, Bt) do { __builtin_amdgcn_s_setprio(1); _Pragma("unroll") for (int m = 0; m < 4; ++m) _Pragma("unroll") for (int n = 0; n < 2; ++n) _Pragma("unroll") for (int k = 0; k < 2; ++k) \
;         acc[ai][bj][m][n] = __builtin_amdgcn_mfma_f32_16x16x32_bf16(Bt[n][k], At[m][k], acc[ai][bj][m][n], 0, 0, 0); __builtin_amdgcn_s_setprio(0); } while (0)
; template <class Epi, class Sched, bool ALIGN_EPI = false, bool SP2 = false, bool HALFM = false>
; __device__ __forceinline__ void gemm_phase(PG8_LAS unsigned char* lds, const Gemm g, const Sched& S, const Epi& E) {
;     ...
;             PG8_LDB(B0, 0, 0); PG8_LDB(B1, 0, 1); PG8_SCHED; PG8_LDA(At, 0, 0); PG8_STAGE(PG8_SA(1, 1), a1 + hstep, voffA);
;             PG8_WAIT_V(8); PG8_WAIT_L(0); PG8_BAR; PG8_MMA(0, 0, At, B0); PG8_MMA(0, 1, At, B1); PG8_BAR; PG8_SCHED;
;             PG8_LDA(At, 0, 1); PG8_STAGE(PG8_SB(0, 0), b2, voffB); PG8_STAGE(PG8_SB(0, 1), b2 + hstep, voffB); PG8_STAGE(PG8_SA(0, 0), a2, voffA);
;             PG8_WAIT_V(8); PG8_WAIT_L(0); PG8_BAR; if constexpr (!HALFM) { PG8_MMA(1, 0, At, B0); PG8_MMA(1, 1, At, B1); } PG8_BAR; PG8_SCHED;
;             PG8_LDB(B0, 1, 0); PG8_LDB(B1, 1, 1); PG8_SCHED; PG8_LDA(At, 1, 0); PG8_STAGE(PG8_SA(0, 1), a2 + hstep, voffA);
;             PG8_WAIT_V(8); PG8_WAIT_L(0); PG8_BAR; PG8_MMA(0, 0, At, B0); PG8_MMA(0, 1, At, B1); PG8_BAR; PG8_SCHED;
;             PG8_LDA(At, 1, 1); PG8_STAGE(PG8_SB(1, 0), b3, voffB); PG8_STAGE(PG8_SB(1, 1), b3 + hstep, voffB); PG8_STAGE(PG8_SA(1, 0), a3, voffA);
;             PG8_WAIT_V(8); PG8_WAIT_L(0); PG8_BAR; if constexpr (!HALFM) { PG8_MMA(1, 0, At, B0); PG8_MMA(1, 1, At, B1); } PG8_BAR; PG8_SCHED;
	s_setprio 1
	v_mfma_f32_16x16x32_bf16 v[62:65], v[126:129], v[162:165], v[62:65]
	v_mfma_f32_16x16x32_bf16 v[58:61], v[138:141], v[162:165], v[58:61]
	v_mfma_f32_16x16x32_bf16 v[46:49], v[126:129], v[170:173], v[46:49]
	v_mfma_f32_16x16x32_bf16 v[42:45], v[138:141], v[170:173], v[42:45]
	v_mfma_f32_16x16x32_bf16 v[30:33], v[126:129], v[194:197], v[30:33]
	v_mfma_f32_16x16x32_bf16 v[26:29], v[138:141], v[194:197], v[26:29]
	v_mfma_f32_16x16x32_bf16 v[14:17], v[126:129], v[202:205], v[14:17]
	v_mfma_f32_16x16x32_bf16 v[10:13], v[138:141], v[202:205], v[10:13]
	v_mfma_f32_16x16x32_bf16 v[62:65], v[130:133], v[166:169], v[62:65]
	v_mfma_f32_16x16x32_bf16 v[58:61], v[142:145], v[166:169], v[58:61]
	v_mfma_f32_16x16x32_bf16 v[46:49], v[130:133], v[174:177], v[46:49]
	v_mfma_f32_16x16x32_bf16 v[42:45], v[142:145], v[174:177], v[42:45]
	v_mfma_f32_16x16x32_bf16 v[30:33], v[130:133], v[198:201], v[30:33]
	v_mfma_f32_16x16x32_bf16 v[26:29], v[142:145], v[198:201], v[26:29]
	v_mfma_f32_16x16x32_bf16 v[14:17], v[130:133], v[206:209], v[14:17]
	v_mfma_f32_16x16x32_bf16 v[10:13], v[142:145], v[206:209], v[10:13]
	s_setprio 0
	s_setprio 1
	v_mfma_f32_16x16x32_bf16 v[54:57], v[146:149], v[162:165], v[54:57]
	v_mfma_f32_16x16x32_bf16 v[50:53], v[154:157], v[162:165], v[50:53]
	v_mfma_f32_16x16x32_bf16 v[38:41], v[146:149], v[170:173], v[38:41]
	v_mfma_f32_16x16x32_bf16 v[34:37], v[154:157], v[170:173], v[34:37]
	v_mfma_f32_16x16x32_bf16 v[22:25], v[146:149], v[194:197], v[22:25]
	v_mfma_f32_16x16x32_bf16 v[18:21], v[154:157], v[194:197], v[18:21]
	v_mfma_f32_16x16x32_bf16 v[6:9], v[146:149], v[202:205], v[6:9]
	v_mfma_f32_16x16x32_bf16 v[2:5], v[154:157], v[202:205], v[2:5]
	v_mfma_f32_16x16x32_bf16 v[54:57], v[150:153], v[166:169], v[54:57]
	v_mfma_f32_16x16x32_bf16 v[50:53], v[158:161], v[166:169], v[50:53]
	v_mfma_f32_16x16x32_bf16 v[38:41], v[150:153], v[174:177], v[38:41]
	v_mfma_f32_16x16x32_bf16 v[34:37], v[158:161], v[174:177], v[34:37]
	v_mfma_f32_16x16x32_bf16 v[22:25], v[150:153], v[198:201], v[22:25]
	v_mfma_f32_16x16x32_bf16 v[18:21], v[158:161], v[198:201], v[18:21]
	v_mfma_f32_16x16x32_bf16 v[6:9], v[150:153], v[206:209], v[6:9]
	v_mfma_f32_16x16x32_bf16 v[2:5], v[158:161], v[206:209], v[2:5]
	s_setprio 0
	s_barrier
	s_add_i32 s57, 0, 0x18000
	s_add_i32 s58, 0, 0x1c000
	v_add_u32_e32 v142, s57, v210
	v_add_u32_e32 v158, s58, v210
	ds_read_b128 v[126:129], v142
	ds_read_b128 v[130:133], v142 offset:1024
	ds_read_b128 v[138:141], v142 offset:2048
	ds_read_b128 v[142:145], v142 offset:3072
	ds_read_b128 v[146:149], v158
	ds_read_b128 v[150:153], v158 offset:1024
	ds_read_b128 v[154:157], v158 offset:2048
	ds_read_b128 v[158:161], v158 offset:3072
	s_add_u32 s40, s40, 0x40000
	s_addc_u32 s41, s41, 0
	s_mov_b32 m0, s3
	v_lshl_add_u64 v[224:225], s[40:41], 0, v[178:179]
	ds_read_b128 v[162:165], v214 offset:32768
	ds_read_b128 v[166:169], v214 offset:33792
	ds_read_b128 v[170:173], v214 offset:34816
	ds_read_b128 v[174:177], v214 offset:35840
	ds_read_b128 v[194:197], v214 offset:36864
	ds_read_b128 v[198:201], v214 offset:37888
	ds_read_b128 v[202:205], v214 offset:38912
	ds_read_b128 v[206:209], v214 offset:39936
	global_load_lds_dwordx4 v[224:225], off
	v_lshl_add_u64 v[224:225], s[40:41], 0, v[182:183]
	s_mov_b32 m0, s35
	s_nop 0
	global_load_lds_dwordx4 v[224:225], off
	s_mov_b32 m0, s1
	s_nop 0
	global_load_lds_dwordx4 v[220:221], off
	s_mov_b32 m0, s2
	s_nop 0
	global_load_lds_dwordx4 v[222:223], off
	s_waitcnt vmcnt(10)
	s_waitcnt lgkmcnt(0)
	s_barrier
; #define PG8_STAGE(bufoff, gbase, voff) do { _Pragma("unroll") for (int _i = 0; _i < 2; ++_i) \
;         __builtin_amdgcn_global_load_lds((const unsigned*)((const char*)(gbase) + (voff)[_i]), (PG8_LAS unsigned*)(lds + (bufoff) + ldsw + _i * 8192), 16, 0, 0); } while (0)
; #define PG8_LDA(dst, b, h) do { _Pragma("unroll") for (int m = 0; m < 4; ++m) _Pragma("unroll") for (int k = 0; k < 2; ++k) dst[m][k] = *(const PG8_LAS bf16x8*)(lds + PG8_SA(b, h) + aoff + m * 2048 + k * 1024); } while (0)
; #define PG8_LDB(dst, b, h) do { _Pragma("unroll") for (int n = 0; n < 2; ++n) _Pragma("unroll") for (int k = 0; k < 2; ++k) dst[n][k] = *(const PG8_LAS bf16x8*)(lds + PG8_SB(b, h) + boff + n * 2048 + k * 1024); } while (0)
; #define PG8_WAIT_V(n) asm volatile("s_waitcnt vmcnt(" #n ")" ::: "memory")
; #define PG8_WAIT_L(n) asm volatile("s_waitcnt lgkmcnt(" #n ")" ::: "memory")
; #define PG8_BAR __builtin_amdgcn_s_barrier()
; #define PG8_SCHED __builtin_amdgcn_sched_barrier(0)
; template <class Epi, class Sched, bool ALIGN_EPI = false, bool SP2 = false, bool HALFM = false>
; __device__ __forceinline__ void gemm_phase(PG8_LAS unsigned char* lds, const Gemm g, const Sched& S, const Epi& E) {
;     ...
;         for (int t = 0; t < nt; t += 2) {
;     ...
;             PG8_LDB(B0, 0, 0); PG8_LDB(B1, 0, 1); PG8_SCHED; PG8_LDA(At, 0, 0); PG8_STAGE(PG8_SA(1, 1), a1 + hstep, voffA);
;             PG8_WAIT_V(8); PG8_WAIT_L(0); PG8_BAR; PG8_MMA(0, 0, At, B0); PG8_MMA(0, 1, At, B1); PG8_BAR; PG8_SCHED;
;             PG8_LDA(At, 0, 1); PG8_STAGE(PG8_SB(0, 0), b2, voffB); PG8_STAGE(PG8_SB(0, 1), b2 + hstep, voffB); PG8_STAGE(PG8_SA(0, 0), a2, voffA);
;             PG8_WAIT_V(8); PG8_WAIT_L(0); PG8_BAR; if constexpr (!HALFM) { PG8_MMA(1, 0, At, B0); PG8_MMA(1, 1, At, B1); } PG8_BAR; PG8_SCHED;
;             PG8_LDB(B0, 1, 0); PG8_LDB(B1, 1, 1); PG8_SCHED; PG8_LDA(At, 1, 0); PG8_STAGE(PG8_SA(0, 1), a2 + hstep, voffA);
;             PG8_WAIT_V(8); PG8_WAIT_L(0); PG8_BAR; PG8_MMA(0, 0, At, B0); PG8_MMA(0, 1, At, B1); PG8_BAR; PG8_SCHED;
;             PG8_LDA(At, 1, 1); PG8_STAGE(PG8_SB(1, 0), b3, voffB); PG8_STAGE(PG8_SB(1, 1), b3 + hstep, voffB); PG8_STAGE(PG8_SA(1, 0), a3, voffA);
;             PG8_WAIT_V(8); PG8_WAIT_L(0); PG8_BAR; if constexpr (!HALFM) { PG8_MMA(1, 0, At, B0); PG8_MMA(1, 1, At, B1); } PG8_BAR; PG8_SCHED;
	s_setprio 1
	v_mfma_f32_16x16x32_bf16 v[134:137], v[126:129], v[162:165], v[134:137]
	v_mfma_f32_16x16x32_bf16 v[122:125], v[138:141], v[162:165], v[122:125]
	v_mfma_f32_16x16x32_bf16 v[110:113], v[126:129], v[170:173], v[110:113]
	v_mfma_f32_16x16x32_bf16 v[106:109], v[138:141], v[170:173], v[106:109]
	v_mfma_f32_16x16x32_bf16 v[94:97], v[126:129], v[194:197], v[94:97]
	v_mfma_f32_16x16x32_bf16 v[90:93], v[138:141], v[194:197], v[90:93]
	v_mfma_f32_16x16x32_bf16 v[78:81], v[126:129], v[202:205], v[78:81]
	v_mfma_f32_16x16x32_bf16 v[74:77], v[138:141], v[202:205], v[74:77]
	v_mfma_f32_16x16x32_bf16 v[134:137], v[130:133], v[166:169], v[134:137]
	v_mfma_f32_16x16x32_bf16 v[122:125], v[142:145], v[166:169], v[122:125]
	v_mfma_f32_16x16x32_bf16 v[110:113], v[130:133], v[174:177], v[110:113]
	v_mfma_f32_16x16x32_bf16 v[106:109], v[142:145], v[174:177], v[106:109]
	v_mfma_f32_16x16x32_bf16 v[94:97], v[130:133], v[198:201], v[94:97]
	v_mfma_f32_16x16x32_bf16 v[90:93], v[142:145], v[198:201], v[90:93]
	v_mfma_f32_16x16x32_bf16 v[78:81], v[130:133], v[206:209], v[78:81]
	v_mfma_f32_16x16x32_bf16 v[74:77], v[142:145], v[206:209], v[74:77]
	s_setprio 0
	s_setprio 1
	v_mfma_f32_16x16x32_bf16 v[118:121], v[146:149], v[162:165], v[118:121]
	v_mfma_f32_16x16x32_bf16 v[114:117], v[154:157], v[162:165], v[114:117]
	v_mfma_f32_16x16x32_bf16 v[102:105], v[146:149], v[170:173], v[102:105]
	v_mfma_f32_16x16x32_bf16 v[98:101], v[154:157], v[170:173], v[98:101]
	v_mfma_f32_16x16x32_bf16 v[86:89], v[146:149], v[194:197], v[86:89]
	v_mfma_f32_16x16x32_bf16 v[82:85], v[154:157], v[194:197], v[82:85]
	v_mfma_f32_16x16x32_bf16 v[70:73], v[146:149], v[202:205], v[70:73]
	v_mfma_f32_16x16x32_bf16 v[66:69], v[154:157], v[202:205], v[66:69]
	v_mfma_f32_16x16x32_bf16 v[118:121], v[150:153], v[166:169], v[118:121]
	v_mfma_f32_16x16x32_bf16 v[114:117], v[158:161], v[166:169], v[114:117]
	v_mfma_f32_16x16x32_bf16 v[102:105], v[150:153], v[174:177], v[102:105]
	v_mfma_f32_16x16x32_bf16 v[98:101], v[158:161], v[174:177], v[98:101]
	v_mfma_f32_16x16x32_bf16 v[86:89], v[150:153], v[198:201], v[86:89]
	v_mfma_f32_16x16x32_bf16 v[82:85], v[158:161], v[198:201], v[82:85]
	v_mfma_f32_16x16x32_bf16 v[70:73], v[150:153], v[206:209], v[70:73]
	v_mfma_f32_16x16x32_bf16 v[66:69], v[158:161], v[206:209], v[66:69]
	s_setprio 0
	s_barrier
	s_add_i32 s40, s57, s0
	v_lshl_add_u64 v[216:217], v[216:217], 0, s[10:11]
	s_mov_b32 m0, s40
	ds_read_b128 v[162:165], v214 offset:49152
	ds_read_b128 v[166:169], v214 offset:50176
	ds_read_b128 v[170:173], v214 offset:51200
	ds_read_b128 v[174:177], v214 offset:52224
	ds_read_b128 v[194:197], v214 offset:53248
	ds_read_b128 v[198:201], v214 offset:54272
	ds_read_b128 v[202:205], v214 offset:55296
	ds_read_b128 v[206:209], v214 offset:56320
	global_load_lds_dwordx4 v[216:217], off
	s_add_i32 m0, s40, 0x2000
	s_add_u32 s38, s38, 0x40080
	v_lshl_add_u64 v[216:217], v[218:219], 0, s[10:11]
	s_addc_u32 s39, s39, 0
	s_add_i32 s40, s58, s0
	global_load_lds_dwordx4 v[216:217], off
	v_lshl_add_u64 v[216:217], s[38:39], 0, v[180:181]
	s_mov_b32 m0, s40
	s_nop 0
	global_load_lds_dwordx4 v[216:217], off
	v_lshl_add_u64 v[216:217], s[38:39], 0, v[184:185]
	s_add_i32 m0, s40, 0x2000
	s_nop 0
	global_load_lds_dwordx4 v[216:217], off
	s_waitcnt vmcnt(4)
	s_waitcnt lgkmcnt(0)
	s_barrier
	s_setprio 1
	v_mfma_f32_16x16x32_bf16 v[62:65], v[126:129], v[162:165], v[62:65]
	v_mfma_f32_16x16x32_bf16 v[58:61], v[138:141], v[162:165], v[58:61]
	v_mfma_f32_16x16x32_bf16 v[46:49], v[126:129], v[170:173], v[46:49]
	v_mfma_f32_16x16x32_bf16 v[42:45], v[138:141], v[170:173], v[42:45]
	v_mfma_f32_16x16x32_bf16 v[30:33], v[126:129], v[194:197], v[30:33]
	v_mfma_f32_16x16x32_bf16 v[26:29], v[138:141], v[194:197], v[26:29]
	v_mfma_f32_16x16x32_bf16 v[14:17], v[126:129], v[202:205], v[14:17]
	v_mfma_f32_16x16x32_bf16 v[10:13], v[138:141], v[202:205], v[10:13]
	v_mfma_f32_16x16x32_bf16 v[62:65], v[130:133], v[166:169], v[62:65]
	v_mfma_f32_16x16x32_bf16 v[58:61], v[142:145], v[166:169], v[58:61]
	v_mfma_f32_16x16x32_bf16 v[46:49], v[130:133], v[174:177], v[46:49]
	v_mfma_f32_16x16x32_bf16 v[42:45], v[142:145], v[174:177], v[42:45]
	v_mfma_f32_16x16x32_bf16 v[30:33], v[130:133], v[198:201], v[30:33]
	v_mfma_f32_16x16x32_bf16 v[26:29], v[142:145], v[198:201], v[26:29]
	v_mfma_f32_16x16x32_bf16 v[14:17], v[130:133], v[206:209], v[14:17]
	v_mfma_f32_16x16x32_bf16 v[10:13], v[142:145], v[206:209], v[10:13]
	s_setprio 0
	s_setprio 1
	v_mfma_f32_16x16x32_bf16 v[54:57], v[146:149], v[162:165], v[54:57]
	v_mfma_f32_16x16x32_bf16 v[50:53], v[154:157], v[162:165], v[50:53]
	v_mfma_f32_16x16x32_bf16 v[38:41], v[146:149], v[170:173], v[38:41]
	v_mfma_f32_16x16x32_bf16 v[34:37], v[154:157], v[170:173], v[34:37]
	v_mfma_f32_16x16x32_bf16 v[22:25], v[146:149], v[194:197], v[22:25]
	v_mfma_f32_16x16x32_bf16 v[18:21], v[154:157], v[194:197], v[18:21]
	v_mfma_f32_16x16x32_bf16 v[6:9], v[146:149], v[202:205], v[6:9]
	v_mfma_f32_16x16x32_bf16 v[2:5], v[154:157], v[202:205], v[2:5]
	v_mfma_f32_16x16x32_bf16 v[54:57], v[150:153], v[166:169], v[54:57]
	v_mfma_f32_16x16x32_bf16 v[50:53], v[158:161], v[166:169], v[50:53]
	v_mfma_f32_16x16x32_bf16 v[38:41], v[150:153], v[174:177], v[38:41]
	v_mfma_f32_16x16x32_bf16 v[34:37], v[158:161], v[174:177], v[34:37]
	v_mfma_f32_16x16x32_bf16 v[22:25], v[150:153], v[198:201], v[22:25]
	v_mfma_f32_16x16x32_bf16 v[18:21], v[158:161], v[198:201], v[18:21]
	v_mfma_f32_16x16x32_bf16 v[6:9], v[150:153], v[206:209], v[6:9]
	v_mfma_f32_16x16x32_bf16 v[2:5], v[158:161], v[206:209], v[2:5]
	s_setprio 0
	s_barrier
	s_add_i32 s56, s56, 2
	s_add_u32 s36, s36, 0x100
	s_addc_u32 s37, s37, 0
	s_add_u32 s54, s54, 0x100
	s_addc_u32 s55, s55, 0
	s_cmp_gt_u32 s56, 13
	s_cbranch_scc0 .LBB0_2049
	s_and_b64 vcc, exec, s[12:13]
	s_cbranch_vccz .LBB0_2052
	s_barrier
